# d4 + MFMA order within each 8-group changed so SrcA operand stays constant for 4 consecutive MFMAs
# baseline (speedup 1.0000x reference)
; #define PG8_STAGE(bufoff, gbase, voff) do { _Pragma("unroll") for (int _i = 0; _i < 2; ++_i) \
;         __builtin_amdgcn_global_load_lds((const unsigned*)((const char*)(gbase) + (voff)[_i]), (LAS unsigned*)(lds + (bufoff) + ldsw + _i * 8192), 16, 0, 0); } while (0)
; #define PG8_LDA(dst, b, h) do { _Pragma("unroll") for (int m = 0; m < 4; ++m) _Pragma("unroll") for (int k = 0; k < 2; ++k) dst[m][k] = *(const LAS bf16x8*)(lds + PG8_SA(b, h) + aoff + m * 2048 + k * 1024); } while (0)
; #define PG8_LDB(dst, b, h) do { _Pragma("unroll") for (int n = 0; n < 2; ++n) _Pragma("unroll") for (int k = 0; k < 2; ++k) dst[n][k] = *(const LAS bf16x8*)(lds + PG8_SB(b, h) + boff + n * 2048 + k * 1024); } while (0)
; #define PG8_MMA(ai, bj, At, Bt) do { __builtin_amdgcn_s_setprio(1); _Pragma("unroll") for (int m = 0; m < 4; ++m) _Pragma("unroll") for (int n = 0; n < 2; ++n) _Pragma("unroll") for (int k = 0; k < 2; ++k) \
;         acc[ai][bj][m][n] = __builtin_amdgcn_mfma_f32_16x16x32_bf16(Bt[n][k], At[m][k], acc[ai][bj][m][n], 0, 0, 0); __builtin_amdgcn_s_setprio(0); } while (0)
; #define PG8_WAIT_V(n) asm volatile("s_waitcnt vmcnt(" #n ")" ::: "memory")
; #define PG8_WAIT_L(n) asm volatile("s_waitcnt lgkmcnt(" #n ")" ::: "memory")
; #define PG8_BAR __builtin_amdgcn_s_barrier()
; template <class Epi>
; __device__ __forceinline__ void gemm_phase(LAS unsigned char* lds, const Gemm g, const StaticOrder& S, const Epi& E) {
;     ...
;             const bool last = (t == nt - 2);
;             const char* a1 = cA + (size_t)(t + 1) * kstep;
;             const char* a2 = last ? nA : cA + (size_t)(t + 2) * kstep; const char* b2 = last ? nB : cB + (size_t)(t + 2) * kstep;
;             const char* a3 = a2 + kstep; const char* b3 = b2 + kstep;
;             if constexpr (Epi::MIDK > 0) { if (t == Epi::MIDK) E.mid(acc, cur, wr, wc, fr, fq); }
;             PG8_LDB(B0, 0, 0); PG8_LDB(B1, 0, 1); PG8_SCHED; PG8_LDA(At, 0, 0); PG8_STAGE(PG8_SA(1, 1), a1 + hstep, voffA);
;             PG8_WAIT_V(8); PG8_WAIT_L(0); PG8_BAR; PG8_MMA(0, 0, At, B0); PG8_MMA(0, 1, At, B1); PG8_BAR; PG8_SCHED;
;             PG8_LDA(At, 0, 1); PG8_STAGE(PG8_SB(0, 0), b2, voffB); PG8_STAGE(PG8_SB(0, 1), b2 + hstep, voffB); PG8_STAGE(PG8_SA(0, 0), a2, voffA);
;             PG8_WAIT_V(8); PG8_WAIT_L(0); PG8_BAR; PG8_MMA(1, 0, At, B0); PG8_MMA(1, 1, At, B1); PG8_BAR; PG8_SCHED;
.LBB0_134:
	ds_read_b128 v[158:161], v150
	ds_read_b128 v[162:165], v150 offset:1024
	ds_read_b128 v[166:169], v150 offset:2048
	ds_read_b128 v[174:177], v150 offset:3072
	ds_read_b128 v[178:181], v151
	ds_read_b128 v[182:185], v151 offset:1024
	ds_read_b128 v[186:189], v151 offset:2048
	ds_read_b128 v[190:193], v151 offset:3072
	s_add_u32 s66, s64, 0xfffc0080
	s_addc_u32 s67, s65, -1
	s_cmp_eq_u32 s92, 12
	s_cselect_b32 s69, s87, s67
	s_cselect_b32 s68, s88, s66
	s_cselect_b32 s67, s47, s91
	s_cselect_b32 s66, s89, s90
	s_add_i32 m0, s61, 0xc000
	ds_read_b128 v[194:197], v152
	ds_read_b128 v[198:201], v152 offset:1024
	ds_read_b128 v[202:205], v152 offset:2048
	ds_read_b128 v[206:209], v152 offset:3072
	ds_read_b128 v[210:213], v152 offset:4096
	ds_read_b128 v[214:217], v152 offset:5120
	ds_read_b128 v[218:221], v152 offset:6144
	ds_read_b128 v[222:225], v152 offset:7168
	global_load_lds_dwordx4 v140, s[64:65]
	s_add_i32 m0, s61, 0xe000
	s_nop 0
	global_load_lds_dwordx4 v142, s[64:65]
	s_waitcnt vmcnt(8)
	s_waitcnt lgkmcnt(0)
	s_setprio 1
	s_barrier
	v_mfma_f32_16x16x32_bf16 v[126:129], v[158:161], v[194:197], v[126:129]
	v_mfma_f32_16x16x32_bf16 v[110:113], v[158:161], v[202:205], v[110:113]
	v_mfma_f32_16x16x32_bf16 v[94:97], v[158:161], v[210:213], v[94:97]
	v_mfma_f32_16x16x32_bf16 v[78:81], v[158:161], v[218:221], v[78:81]
	v_mfma_f32_16x16x32_bf16 v[118:121], v[166:169], v[194:197], v[118:121]
	v_mfma_f32_16x16x32_bf16 v[102:105], v[166:169], v[202:205], v[102:105]
	v_mfma_f32_16x16x32_bf16 v[86:89], v[166:169], v[210:213], v[86:89]
	v_mfma_f32_16x16x32_bf16 v[70:73], v[166:169], v[218:221], v[70:73]
	v_mfma_f32_16x16x32_bf16 v[126:129], v[162:165], v[198:201], v[126:129]
	v_mfma_f32_16x16x32_bf16 v[110:113], v[162:165], v[206:209], v[110:113]
	v_mfma_f32_16x16x32_bf16 v[94:97], v[162:165], v[214:217], v[94:97]
	v_mfma_f32_16x16x32_bf16 v[78:81], v[162:165], v[222:225], v[78:81]
	v_mfma_f32_16x16x32_bf16 v[118:121], v[174:177], v[198:201], v[118:121]
	v_mfma_f32_16x16x32_bf16 v[102:105], v[174:177], v[206:209], v[102:105]
	v_mfma_f32_16x16x32_bf16 v[86:89], v[174:177], v[214:217], v[86:89]
	v_mfma_f32_16x16x32_bf16 v[70:73], v[174:177], v[222:225], v[70:73]
	v_mfma_f32_16x16x32_bf16 v[122:125], v[178:181], v[194:197], v[122:125]
	v_mfma_f32_16x16x32_bf16 v[106:109], v[178:181], v[202:205], v[106:109]
	v_mfma_f32_16x16x32_bf16 v[90:93], v[178:181], v[210:213], v[90:93]
	v_mfma_f32_16x16x32_bf16 v[74:77], v[178:181], v[218:221], v[74:77]
	v_mfma_f32_16x16x32_bf16 v[114:117], v[186:189], v[194:197], v[114:117]
	v_mfma_f32_16x16x32_bf16 v[98:101], v[186:189], v[202:205], v[98:101]
	v_mfma_f32_16x16x32_bf16 v[82:85], v[186:189], v[210:213], v[82:85]
	v_mfma_f32_16x16x32_bf16 v[66:69], v[186:189], v[218:221], v[66:69]
	v_mfma_f32_16x16x32_bf16 v[122:125], v[182:185], v[198:201], v[122:125]
	v_mfma_f32_16x16x32_bf16 v[106:109], v[182:185], v[206:209], v[106:109]
	v_mfma_f32_16x16x32_bf16 v[90:93], v[182:185], v[214:217], v[90:93]
	v_mfma_f32_16x16x32_bf16 v[74:77], v[182:185], v[222:225], v[74:77]
	v_mfma_f32_16x16x32_bf16 v[114:117], v[190:193], v[198:201], v[114:117]
	v_mfma_f32_16x16x32_bf16 v[98:101], v[190:193], v[206:209], v[98:101]
	v_mfma_f32_16x16x32_bf16 v[82:85], v[190:193], v[214:217], v[82:85]
	v_mfma_f32_16x16x32_bf16 v[66:69], v[190:193], v[222:225], v[66:69]
	s_barrier
	s_setprio 0
	s_add_u32 s98, s66, s8
	s_addc_u32 s99, s67, s9
	s_add_u32 s100, s68, s8
	s_addc_u32 s101, s69, s9
	s_add_i32 s93, s83, s6
	s_mov_b32 m0, s93
	ds_read_b128 v[194:197], v152 offset:16384
	ds_read_b128 v[198:201], v152 offset:17408
	ds_read_b128 v[202:205], v152 offset:18432
	ds_read_b128 v[206:209], v152 offset:19456
	ds_read_b128 v[210:213], v152 offset:20480
	ds_read_b128 v[214:217], v152 offset:21504
	ds_read_b128 v[218:221], v152 offset:22528
	ds_read_b128 v[222:225], v152 offset:23552
	global_load_lds_dwordx4 v132, s[66:67]
	s_add_i32 m0, s93, 0x2000
	s_add_u32 s94, s66, 0x40000
	s_addc_u32 s95, s67, 0
	s_add_i32 s93, s84, s6
	global_load_lds_dwordx4 v136, s[66:67]
	s_mov_b32 m0, s93
	s_nop 0
	global_load_lds_dwordx4 v132, s[94:95]
	s_add_i32 m0, s93, 0x2000
	s_nop 0
	global_load_lds_dwordx4 v136, s[94:95]
	s_mov_b32 m0, s61
	s_nop 0
	global_load_lds_dwordx4 v130, s[68:69]
	s_mov_b32 m0, s63
	s_nop 0
	global_load_lds_dwordx4 v134, s[68:69]
	s_waitcnt vmcnt(8)
	s_waitcnt lgkmcnt(0)
	s_setprio 1
	s_barrier
	v_mfma_f32_16x16x32_bf16 v[62:65], v[158:161], v[194:197], v[62:65]
	v_mfma_f32_16x16x32_bf16 v[46:49], v[158:161], v[202:205], v[46:49]
	v_mfma_f32_16x16x32_bf16 v[30:33], v[158:161], v[210:213], v[30:33]
	v_mfma_f32_16x16x32_bf16 v[14:17], v[158:161], v[218:221], v[14:17]
	v_mfma_f32_16x16x32_bf16 v[54:57], v[166:169], v[194:197], v[54:57]
	v_mfma_f32_16x16x32_bf16 v[38:41], v[166:169], v[202:205], v[38:41]
	v_mfma_f32_16x16x32_bf16 v[22:25], v[166:169], v[210:213], v[22:25]
	v_mfma_f32_16x16x32_bf16 v[6:9], v[166:169], v[218:221], v[6:9]
	v_mfma_f32_16x16x32_bf16 v[62:65], v[162:165], v[198:201], v[62:65]
	v_mfma_f32_16x16x32_bf16 v[46:49], v[162:165], v[206:209], v[46:49]
	v_mfma_f32_16x16x32_bf16 v[30:33], v[162:165], v[214:217], v[30:33]
	v_mfma_f32_16x16x32_bf16 v[14:17], v[162:165], v[222:225], v[14:17]
	v_mfma_f32_16x16x32_bf16 v[54:57], v[174:177], v[198:201], v[54:57]
	v_mfma_f32_16x16x32_bf16 v[38:41], v[174:177], v[206:209], v[38:41]
	v_mfma_f32_16x16x32_bf16 v[22:25], v[174:177], v[214:217], v[22:25]
	v_mfma_f32_16x16x32_bf16 v[6:9], v[174:177], v[222:225], v[6:9]
	v_mfma_f32_16x16x32_bf16 v[58:61], v[178:181], v[194:197], v[58:61]
	v_mfma_f32_16x16x32_bf16 v[42:45], v[178:181], v[202:205], v[42:45]
	v_mfma_f32_16x16x32_bf16 v[26:29], v[178:181], v[210:213], v[26:29]
	v_mfma_f32_16x16x32_bf16 v[10:13], v[178:181], v[218:221], v[10:13]
	v_mfma_f32_16x16x32_bf16 v[50:53], v[186:189], v[194:197], v[50:53]
	v_mfma_f32_16x16x32_bf16 v[34:37], v[186:189], v[202:205], v[34:37]
	v_mfma_f32_16x16x32_bf16 v[18:21], v[186:189], v[210:213], v[18:21]
	v_mfma_f32_16x16x32_bf16 v[2:5], v[186:189], v[218:221], v[2:5]
	v_mfma_f32_16x16x32_bf16 v[58:61], v[182:185], v[198:201], v[58:61]
	v_mfma_f32_16x16x32_bf16 v[42:45], v[182:185], v[206:209], v[42:45]
	v_mfma_f32_16x16x32_bf16 v[26:29], v[182:185], v[214:217], v[26:29]
	v_mfma_f32_16x16x32_bf16 v[10:13], v[182:185], v[222:225], v[10:13]
	v_mfma_f32_16x16x32_bf16 v[50:53], v[190:193], v[198:201], v[50:53]
	v_mfma_f32_16x16x32_bf16 v[34:37], v[190:193], v[206:209], v[34:37]
	v_mfma_f32_16x16x32_bf16 v[18:21], v[190:193], v[214:217], v[18:21]
	v_mfma_f32_16x16x32_bf16 v[2:5], v[190:193], v[222:225], v[2:5]
	s_barrier
; #define PG8_STAGE(bufoff, gbase, voff) do { _Pragma("unroll") for (int _i = 0; _i < 2; ++_i) \
;         __builtin_amdgcn_global_load_lds((const unsigned*)((const char*)(gbase) + (voff)[_i]), (LAS unsigned*)(lds + (bufoff) + ldsw + _i * 8192), 16, 0, 0); } while (0)
; #define PG8_LDA(dst, b, h) do { _Pragma("unroll") for (int m = 0; m < 4; ++m) _Pragma("unroll") for (int k = 0; k < 2; ++k) dst[m][k] = *(const LAS bf16x8*)(lds + PG8_SA(b, h) + aoff + m * 2048 + k * 1024); } while (0)
; #define PG8_LDB(dst, b, h) do { _Pragma("unroll") for (int n = 0; n < 2; ++n) _Pragma("unroll") for (int k = 0; k < 2; ++k) dst[n][k] = *(const LAS bf16x8*)(lds + PG8_SB(b, h) + boff + n * 2048 + k * 1024); } while (0)
; #define PG8_MMA(ai, bj, At, Bt) do { __builtin_amdgcn_s_setprio(1); _Pragma("unroll") for (int m = 0; m < 4; ++m) _Pragma("unroll") for (int n = 0; n < 2; ++n) _Pragma("unroll") for (int k = 0; k < 2; ++k) \
;         acc[ai][bj][m][n] = __builtin_amdgcn_mfma_f32_16x16x32_bf16(Bt[n][k], At[m][k], acc[ai][bj][m][n], 0, 0, 0); __builtin_amdgcn_s_setprio(0); } while (0)
; #define PG8_WAIT_V(n) asm volatile("s_waitcnt vmcnt(" #n ")" ::: "memory")
; #define PG8_WAIT_L(n) asm volatile("s_waitcnt lgkmcnt(" #n ")" ::: "memory")
; #define PG8_BAR __builtin_amdgcn_s_barrier()
; #define PG8_SCHED __builtin_amdgcn_sched_barrier(0)
; template <class Epi>
; __device__ __forceinline__ void gemm_phase(LAS unsigned char* lds, const Gemm g, const StaticOrder& S, const Epi& E) {
;     ...
;             PG8_LDB(B0, 1, 0); PG8_LDB(B1, 1, 1); PG8_SCHED; PG8_LDA(At, 1, 0); PG8_STAGE(PG8_SA(0, 1), a2 + hstep, voffA);
;             PG8_WAIT_V(8); PG8_WAIT_L(0); PG8_BAR; PG8_MMA(0, 0, At, B0); PG8_MMA(0, 1, At, B1); PG8_BAR; PG8_SCHED;
;             PG8_LDA(At, 1, 1); PG8_STAGE(PG8_SB(1, 0), b3, voffB); PG8_STAGE(PG8_SB(1, 1), b3 + hstep, voffB); PG8_STAGE(PG8_SA(1, 0), a3, voffA);
;             PG8_WAIT_V(8); PG8_WAIT_L(0); PG8_BAR; PG8_MMA(1, 0, At, B0); PG8_MMA(1, 1, At, B1); PG8_BAR; PG8_SCHED;
;         }
;         if (wr == 0) PG8_BAR;
	s_setprio 0
	s_add_i32 s93, 0, 0x18000
	s_add_i32 s94, 0, 0x1c000
	v_add_u32_e32 v174, s93, v148
	v_add_u32_e32 v190, s94, v148
	ds_read_b128 v[158:161], v174
	ds_read_b128 v[162:165], v174 offset:1024
	ds_read_b128 v[166:169], v174 offset:2048
	ds_read_b128 v[174:177], v174 offset:3072
	ds_read_b128 v[178:181], v190
	ds_read_b128 v[182:185], v190 offset:1024
	ds_read_b128 v[186:189], v190 offset:2048
	ds_read_b128 v[190:193], v190 offset:3072
	s_add_u32 s68, s68, 0x40000
	s_addc_u32 s69, s69, 0
	s_mov_b32 m0, s77
	ds_read_b128 v[194:197], v152 offset:32768
	ds_read_b128 v[198:201], v152 offset:33792
	ds_read_b128 v[202:205], v152 offset:34816
	ds_read_b128 v[206:209], v152 offset:35840
	ds_read_b128 v[210:213], v152 offset:36864
	ds_read_b128 v[214:217], v152 offset:37888
	ds_read_b128 v[218:221], v152 offset:38912
	ds_read_b128 v[222:225], v152 offset:39936
	global_load_lds_dwordx4 v130, s[68:69]
	s_mov_b32 m0, s78
	s_nop 0
	global_load_lds_dwordx4 v134, s[68:69]
	s_waitcnt vmcnt(8)
	s_waitcnt lgkmcnt(0)
	s_setprio 1
	s_barrier
	v_mfma_f32_16x16x32_bf16 v[126:129], v[158:161], v[194:197], v[126:129]
	v_mfma_f32_16x16x32_bf16 v[110:113], v[158:161], v[202:205], v[110:113]
	v_mfma_f32_16x16x32_bf16 v[94:97], v[158:161], v[210:213], v[94:97]
	v_mfma_f32_16x16x32_bf16 v[78:81], v[158:161], v[218:221], v[78:81]
	v_mfma_f32_16x16x32_bf16 v[118:121], v[166:169], v[194:197], v[118:121]
	v_mfma_f32_16x16x32_bf16 v[102:105], v[166:169], v[202:205], v[102:105]
	v_mfma_f32_16x16x32_bf16 v[86:89], v[166:169], v[210:213], v[86:89]
	v_mfma_f32_16x16x32_bf16 v[70:73], v[166:169], v[218:221], v[70:73]
	v_mfma_f32_16x16x32_bf16 v[126:129], v[162:165], v[198:201], v[126:129]
	v_mfma_f32_16x16x32_bf16 v[110:113], v[162:165], v[206:209], v[110:113]
	v_mfma_f32_16x16x32_bf16 v[94:97], v[162:165], v[214:217], v[94:97]
	v_mfma_f32_16x16x32_bf16 v[78:81], v[162:165], v[222:225], v[78:81]
	v_mfma_f32_16x16x32_bf16 v[118:121], v[174:177], v[198:201], v[118:121]
	v_mfma_f32_16x16x32_bf16 v[102:105], v[174:177], v[206:209], v[102:105]
	v_mfma_f32_16x16x32_bf16 v[86:89], v[174:177], v[214:217], v[86:89]
	v_mfma_f32_16x16x32_bf16 v[70:73], v[174:177], v[222:225], v[70:73]
	v_mfma_f32_16x16x32_bf16 v[122:125], v[178:181], v[194:197], v[122:125]
	v_mfma_f32_16x16x32_bf16 v[106:109], v[178:181], v[202:205], v[106:109]
	v_mfma_f32_16x16x32_bf16 v[90:93], v[178:181], v[210:213], v[90:93]
	v_mfma_f32_16x16x32_bf16 v[74:77], v[178:181], v[218:221], v[74:77]
	v_mfma_f32_16x16x32_bf16 v[114:117], v[186:189], v[194:197], v[114:117]
	v_mfma_f32_16x16x32_bf16 v[98:101], v[186:189], v[202:205], v[98:101]
	v_mfma_f32_16x16x32_bf16 v[82:85], v[186:189], v[210:213], v[82:85]
	v_mfma_f32_16x16x32_bf16 v[66:69], v[186:189], v[218:221], v[66:69]
	v_mfma_f32_16x16x32_bf16 v[122:125], v[182:185], v[198:201], v[122:125]
	v_mfma_f32_16x16x32_bf16 v[106:109], v[182:185], v[206:209], v[106:109]
	v_mfma_f32_16x16x32_bf16 v[90:93], v[182:185], v[214:217], v[90:93]
	v_mfma_f32_16x16x32_bf16 v[74:77], v[182:185], v[222:225], v[74:77]
	v_mfma_f32_16x16x32_bf16 v[114:117], v[190:193], v[198:201], v[114:117]
	v_mfma_f32_16x16x32_bf16 v[98:101], v[190:193], v[206:209], v[98:101]
	v_mfma_f32_16x16x32_bf16 v[82:85], v[190:193], v[214:217], v[82:85]
	v_mfma_f32_16x16x32_bf16 v[66:69], v[190:193], v[222:225], v[66:69]
	s_barrier
	s_setprio 0
	s_add_i32 s68, s93, s6
	s_mov_b32 m0, s68
	ds_read_b128 v[194:197], v152 offset:49152
	ds_read_b128 v[198:201], v152 offset:50176
	ds_read_b128 v[202:205], v152 offset:51200
	ds_read_b128 v[206:209], v152 offset:52224
	ds_read_b128 v[210:213], v152 offset:53248
	ds_read_b128 v[214:217], v152 offset:54272
	ds_read_b128 v[218:221], v152 offset:55296
	ds_read_b128 v[222:225], v152 offset:56320
	global_load_lds_dwordx4 v132, s[98:99]
	s_add_i32 m0, s68, 0x2000
	s_add_u32 s66, s66, 0x40080
	s_addc_u32 s67, s67, 0
	s_add_i32 s68, s94, s6
	global_load_lds_dwordx4 v136, s[98:99]
	s_mov_b32 m0, s68
	s_nop 0
	global_load_lds_dwordx4 v132, s[66:67]
	s_add_i32 m0, s68, 0x2000
	s_nop 0
	global_load_lds_dwordx4 v136, s[66:67]
	s_mov_b32 m0, s79
	s_nop 0
	global_load_lds_dwordx4 v130, s[100:101]
	s_mov_b32 m0, s80
	s_nop 0
	global_load_lds_dwordx4 v134, s[100:101]
	s_waitcnt vmcnt(8)
	s_waitcnt lgkmcnt(0)
	s_setprio 1
	s_barrier
	v_mfma_f32_16x16x32_bf16 v[62:65], v[158:161], v[194:197], v[62:65]
	v_mfma_f32_16x16x32_bf16 v[46:49], v[158:161], v[202:205], v[46:49]
	v_mfma_f32_16x16x32_bf16 v[30:33], v[158:161], v[210:213], v[30:33]
	v_mfma_f32_16x16x32_bf16 v[14:17], v[158:161], v[218:221], v[14:17]
	v_mfma_f32_16x16x32_bf16 v[54:57], v[166:169], v[194:197], v[54:57]
	v_mfma_f32_16x16x32_bf16 v[38:41], v[166:169], v[202:205], v[38:41]
	v_mfma_f32_16x16x32_bf16 v[22:25], v[166:169], v[210:213], v[22:25]
	v_mfma_f32_16x16x32_bf16 v[6:9], v[166:169], v[218:221], v[6:9]
	v_mfma_f32_16x16x32_bf16 v[62:65], v[162:165], v[198:201], v[62:65]
	v_mfma_f32_16x16x32_bf16 v[46:49], v[162:165], v[206:209], v[46:49]
	v_mfma_f32_16x16x32_bf16 v[30:33], v[162:165], v[214:217], v[30:33]
	v_mfma_f32_16x16x32_bf16 v[14:17], v[162:165], v[222:225], v[14:17]
	v_mfma_f32_16x16x32_bf16 v[54:57], v[174:177], v[198:201], v[54:57]
	v_mfma_f32_16x16x32_bf16 v[38:41], v[174:177], v[206:209], v[38:41]
	v_mfma_f32_16x16x32_bf16 v[22:25], v[174:177], v[214:217], v[22:25]
	v_mfma_f32_16x16x32_bf16 v[6:9], v[174:177], v[222:225], v[6:9]
	v_mfma_f32_16x16x32_bf16 v[58:61], v[178:181], v[194:197], v[58:61]
	v_mfma_f32_16x16x32_bf16 v[42:45], v[178:181], v[202:205], v[42:45]
	v_mfma_f32_16x16x32_bf16 v[26:29], v[178:181], v[210:213], v[26:29]
	v_mfma_f32_16x16x32_bf16 v[10:13], v[178:181], v[218:221], v[10:13]
	v_mfma_f32_16x16x32_bf16 v[50:53], v[186:189], v[194:197], v[50:53]
	v_mfma_f32_16x16x32_bf16 v[34:37], v[186:189], v[202:205], v[34:37]
	v_mfma_f32_16x16x32_bf16 v[18:21], v[186:189], v[210:213], v[18:21]
	v_mfma_f32_16x16x32_bf16 v[2:5], v[186:189], v[218:221], v[2:5]
	v_mfma_f32_16x16x32_bf16 v[58:61], v[182:185], v[198:201], v[58:61]
	v_mfma_f32_16x16x32_bf16 v[42:45], v[182:185], v[206:209], v[42:45]
	v_mfma_f32_16x16x32_bf16 v[26:29], v[182:185], v[214:217], v[26:29]
	v_mfma_f32_16x16x32_bf16 v[10:13], v[182:185], v[222:225], v[10:13]
	v_mfma_f32_16x16x32_bf16 v[50:53], v[190:193], v[198:201], v[50:53]
	v_mfma_f32_16x16x32_bf16 v[34:37], v[190:193], v[206:209], v[34:37]
	v_mfma_f32_16x16x32_bf16 v[18:21], v[190:193], v[214:217], v[18:21]
	v_mfma_f32_16x16x32_bf16 v[2:5], v[190:193], v[222:225], v[2:5]
	s_barrier
	s_setprio 0
	s_add_i32 s92, s92, 2
	s_add_u32 s64, s64, 0x100
	s_addc_u32 s65, s65, 0
	s_add_u32 s90, s90, 0x100
	s_addc_u32 s91, s91, 0
	s_cmp_gt_u32 s92, 13
	s_cbranch_scc0 .LBB0_134
	s_and_b64 vcc, exec, s[38:39]
	s_cbranch_vccz .LBB0_137
	s_barrier

; #define PG8_STAGE(bufoff, gbase, voff) do { _Pragma("unroll") for (int _i = 0; _i < 2; ++_i) \
;         __builtin_amdgcn_global_load_lds((const unsigned*)((const char*)(gbase) + (voff)[_i]), (LAS unsigned*)(lds + (bufoff) + ldsw + _i * 8192), 16, 0, 0); } while (0)
; #define PG8_LDA(dst, b, h) do { _Pragma("unroll") for (int m = 0; m < 4; ++m) _Pragma("unroll") for (int k = 0; k < 2; ++k) dst[m][k] = *(const LAS bf16x8*)(lds + PG8_SA(b, h) + aoff + m * 2048 + k * 1024); } while (0)
; #define PG8_LDB(dst, b, h) do { _Pragma("unroll") for (int n = 0; n < 2; ++n) _Pragma("unroll") for (int k = 0; k < 2; ++k) dst[n][k] = *(const LAS bf16x8*)(lds + PG8_SB(b, h) + boff + n * 2048 + k * 1024); } while (0)
; #define PG8_MMA(ai, bj, At, Bt) do { __builtin_amdgcn_s_setprio(1); _Pragma("unroll") for (int m = 0; m < 4; ++m) _Pragma("unroll") for (int n = 0; n < 2; ++n) _Pragma("unroll") for (int k = 0; k < 2; ++k) \
;         acc[ai][bj][m][n] = __builtin_amdgcn_mfma_f32_16x16x32_bf16(Bt[n][k], At[m][k], acc[ai][bj][m][n], 0, 0, 0); __builtin_amdgcn_s_setprio(0); } while (0)
; #define PG8_WAIT_V(n) asm volatile("s_waitcnt vmcnt(" #n ")" ::: "memory")
; #define PG8_WAIT_L(n) asm volatile("s_waitcnt lgkmcnt(" #n ")" ::: "memory")
; #define PG8_BAR __builtin_amdgcn_s_barrier()
; template <class Epi>
; __device__ __forceinline__ void gemm_phase(LAS unsigned char* lds, const Gemm g, const StaticOrder& S, const Epi& E) {
;     ...
;             const bool last = (t == nt - 2);
;             const char* a1 = cA + (size_t)(t + 1) * kstep;
;             const char* a2 = last ? nA : cA + (size_t)(t + 2) * kstep; const char* b2 = last ? nB : cB + (size_t)(t + 2) * kstep;
;             const char* a3 = a2 + kstep; const char* b3 = b2 + kstep;
;             if constexpr (Epi::MIDK > 0) { if (t == Epi::MIDK) E.mid(acc, cur, wr, wc, fr, fq); }
;             PG8_LDB(B0, 0, 0); PG8_LDB(B1, 0, 1); PG8_SCHED; PG8_LDA(At, 0, 0); PG8_STAGE(PG8_SA(1, 1), a1 + hstep, voffA);
;             PG8_WAIT_V(8); PG8_WAIT_L(0); PG8_BAR; PG8_MMA(0, 0, At, B0); PG8_MMA(0, 1, At, B1); PG8_BAR; PG8_SCHED;
;             PG8_LDA(At, 0, 1); PG8_STAGE(PG8_SB(0, 0), b2, voffB); PG8_STAGE(PG8_SB(0, 1), b2 + hstep, voffB); PG8_STAGE(PG8_SA(0, 0), a2, voffA);
;             PG8_WAIT_V(8); PG8_WAIT_L(0); PG8_BAR; PG8_MMA(1, 0, At, B0); PG8_MMA(1, 1, At, B1); PG8_BAR; PG8_SCHED;
.LBB0_221:
	ds_read_b128 v[130:133], v162
	ds_read_b128 v[134:137], v162 offset:1024
	ds_read_b128 v[154:157], v162 offset:2048
	ds_read_b128 v[166:169], v162 offset:3072
	ds_read_b128 v[174:177], v163
	ds_read_b128 v[178:181], v163 offset:1024
	ds_read_b128 v[182:185], v163 offset:2048
	ds_read_b128 v[186:189], v163 offset:3072
	s_add_u32 s48, s46, 0xfff50080
	s_addc_u32 s49, s47, -1
	s_cmp_eq_u32 s84, 40
	s_cselect_b32 s51, s5, s49
	s_cselect_b32 s50, s4, s48
	s_cselect_b32 s49, s45, s83
	s_cselect_b32 s48, s44, s82
	s_add_i32 m0, s59, 0xc000
	ds_read_b128 v[190:193], v164
	ds_read_b128 v[194:197], v164 offset:1024
	ds_read_b128 v[198:201], v164 offset:2048
	ds_read_b128 v[202:205], v164 offset:3072
	ds_read_b128 v[206:209], v164 offset:4096
	ds_read_b128 v[210:213], v164 offset:5120
	ds_read_b128 v[214:217], v164 offset:6144
	ds_read_b128 v[218:221], v164 offset:7168
	global_load_lds_dwordx4 v146, s[46:47]
	s_add_i32 m0, s59, 0xe000
	s_nop 0
	global_load_lds_dwordx4 v148, s[46:47]
	s_waitcnt vmcnt(8)
	s_waitcnt lgkmcnt(0)
	s_setprio 1
	s_barrier
	v_mfma_f32_16x16x32_bf16 v[126:129], v[130:133], v[190:193], v[126:129]
	v_mfma_f32_16x16x32_bf16 v[110:113], v[130:133], v[198:201], v[110:113]
	v_mfma_f32_16x16x32_bf16 v[94:97], v[130:133], v[206:209], v[94:97]
	v_mfma_f32_16x16x32_bf16 v[78:81], v[130:133], v[214:217], v[78:81]
	v_mfma_f32_16x16x32_bf16 v[122:125], v[154:157], v[190:193], v[122:125]
	v_mfma_f32_16x16x32_bf16 v[106:109], v[154:157], v[198:201], v[106:109]
	v_mfma_f32_16x16x32_bf16 v[90:93], v[154:157], v[206:209], v[90:93]
	v_mfma_f32_16x16x32_bf16 v[74:77], v[154:157], v[214:217], v[74:77]
	v_mfma_f32_16x16x32_bf16 v[126:129], v[134:137], v[194:197], v[126:129]
	v_mfma_f32_16x16x32_bf16 v[110:113], v[134:137], v[202:205], v[110:113]
	v_mfma_f32_16x16x32_bf16 v[94:97], v[134:137], v[210:213], v[94:97]
	v_mfma_f32_16x16x32_bf16 v[78:81], v[134:137], v[218:221], v[78:81]
	v_mfma_f32_16x16x32_bf16 v[122:125], v[166:169], v[194:197], v[122:125]
	v_mfma_f32_16x16x32_bf16 v[106:109], v[166:169], v[202:205], v[106:109]
	v_mfma_f32_16x16x32_bf16 v[90:93], v[166:169], v[210:213], v[90:93]
	v_mfma_f32_16x16x32_bf16 v[74:77], v[166:169], v[218:221], v[74:77]
	v_mfma_f32_16x16x32_bf16 v[118:121], v[174:177], v[190:193], v[118:121]
	v_mfma_f32_16x16x32_bf16 v[102:105], v[174:177], v[198:201], v[102:105]
	v_mfma_f32_16x16x32_bf16 v[86:89], v[174:177], v[206:209], v[86:89]
	v_mfma_f32_16x16x32_bf16 v[70:73], v[174:177], v[214:217], v[70:73]
	v_mfma_f32_16x16x32_bf16 v[114:117], v[182:185], v[190:193], v[114:117]
	v_mfma_f32_16x16x32_bf16 v[98:101], v[182:185], v[198:201], v[98:101]
	v_mfma_f32_16x16x32_bf16 v[82:85], v[182:185], v[206:209], v[82:85]
	v_mfma_f32_16x16x32_bf16 v[66:69], v[182:185], v[214:217], v[66:69]
	v_mfma_f32_16x16x32_bf16 v[118:121], v[178:181], v[194:197], v[118:121]
	v_mfma_f32_16x16x32_bf16 v[102:105], v[178:181], v[202:205], v[102:105]
	v_mfma_f32_16x16x32_bf16 v[86:89], v[178:181], v[210:213], v[86:89]
	v_mfma_f32_16x16x32_bf16 v[70:73], v[178:181], v[218:221], v[70:73]
	v_mfma_f32_16x16x32_bf16 v[114:117], v[186:189], v[194:197], v[114:117]
	v_mfma_f32_16x16x32_bf16 v[98:101], v[186:189], v[202:205], v[98:101]
	v_mfma_f32_16x16x32_bf16 v[82:85], v[186:189], v[210:213], v[82:85]
	v_mfma_f32_16x16x32_bf16 v[66:69], v[186:189], v[218:221], v[66:69]
	s_barrier
	s_setprio 0
	s_add_u32 s98, s48, s38
	s_addc_u32 s99, s49, s39
	s_add_u32 s100, s50, s38
	s_addc_u32 s101, s51, s39
	s_add_i32 s85, s76, s58
	s_mov_b32 m0, s85
	ds_read_b128 v[190:193], v164 offset:16384
	ds_read_b128 v[194:197], v164 offset:17408
	ds_read_b128 v[198:201], v164 offset:18432
	ds_read_b128 v[202:205], v164 offset:19456
	ds_read_b128 v[206:209], v164 offset:20480
	ds_read_b128 v[210:213], v164 offset:21504
	ds_read_b128 v[214:217], v164 offset:22528
	ds_read_b128 v[218:221], v164 offset:23552
	global_load_lds_dwordx4 v140, s[48:49]
	s_add_i32 m0, s85, 0x2000
	s_add_u32 s86, s48, 0xb0000
	s_addc_u32 s87, s49, 0
	s_add_i32 s85, s77, s58
	global_load_lds_dwordx4 v144, s[48:49]
	s_mov_b32 m0, s85
	s_nop 0
	global_load_lds_dwordx4 v140, s[86:87]
	s_add_i32 m0, s85, 0x2000
	s_nop 0
	global_load_lds_dwordx4 v144, s[86:87]
	s_mov_b32 m0, s59
	s_nop 0
	global_load_lds_dwordx4 v138, s[50:51]
	s_mov_b32 m0, s60
	s_nop 0
	global_load_lds_dwordx4 v142, s[50:51]
	s_waitcnt vmcnt(8)
	s_waitcnt lgkmcnt(0)
	s_setprio 1
	s_barrier
	v_mfma_f32_16x16x32_bf16 v[62:65], v[130:133], v[190:193], v[62:65]
	v_mfma_f32_16x16x32_bf16 v[46:49], v[130:133], v[198:201], v[46:49]
	v_mfma_f32_16x16x32_bf16 v[30:33], v[130:133], v[206:209], v[30:33]
	v_mfma_f32_16x16x32_bf16 v[14:17], v[130:133], v[214:217], v[14:17]
	v_mfma_f32_16x16x32_bf16 v[58:61], v[154:157], v[190:193], v[58:61]
	v_mfma_f32_16x16x32_bf16 v[42:45], v[154:157], v[198:201], v[42:45]
	v_mfma_f32_16x16x32_bf16 v[26:29], v[154:157], v[206:209], v[26:29]
	v_mfma_f32_16x16x32_bf16 v[10:13], v[154:157], v[214:217], v[10:13]
	v_mfma_f32_16x16x32_bf16 v[62:65], v[134:137], v[194:197], v[62:65]
	v_mfma_f32_16x16x32_bf16 v[46:49], v[134:137], v[202:205], v[46:49]
	v_mfma_f32_16x16x32_bf16 v[30:33], v[134:137], v[210:213], v[30:33]
	v_mfma_f32_16x16x32_bf16 v[14:17], v[134:137], v[218:221], v[14:17]
	v_mfma_f32_16x16x32_bf16 v[58:61], v[166:169], v[194:197], v[58:61]
	v_mfma_f32_16x16x32_bf16 v[42:45], v[166:169], v[202:205], v[42:45]
	v_mfma_f32_16x16x32_bf16 v[26:29], v[166:169], v[210:213], v[26:29]
	v_mfma_f32_16x16x32_bf16 v[10:13], v[166:169], v[218:221], v[10:13]
	v_mfma_f32_16x16x32_bf16 v[54:57], v[174:177], v[190:193], v[54:57]
	v_mfma_f32_16x16x32_bf16 v[38:41], v[174:177], v[198:201], v[38:41]
	v_mfma_f32_16x16x32_bf16 v[22:25], v[174:177], v[206:209], v[22:25]
	v_mfma_f32_16x16x32_bf16 v[6:9], v[174:177], v[214:217], v[6:9]
	v_mfma_f32_16x16x32_bf16 v[50:53], v[182:185], v[190:193], v[50:53]
	v_mfma_f32_16x16x32_bf16 v[34:37], v[182:185], v[198:201], v[34:37]
	v_mfma_f32_16x16x32_bf16 v[18:21], v[182:185], v[206:209], v[18:21]
	v_mfma_f32_16x16x32_bf16 v[2:5], v[182:185], v[214:217], v[2:5]
	v_mfma_f32_16x16x32_bf16 v[54:57], v[178:181], v[194:197], v[54:57]
	v_mfma_f32_16x16x32_bf16 v[38:41], v[178:181], v[202:205], v[38:41]
	v_mfma_f32_16x16x32_bf16 v[22:25], v[178:181], v[210:213], v[22:25]
	v_mfma_f32_16x16x32_bf16 v[6:9], v[178:181], v[218:221], v[6:9]
	v_mfma_f32_16x16x32_bf16 v[50:53], v[186:189], v[194:197], v[50:53]
	v_mfma_f32_16x16x32_bf16 v[34:37], v[186:189], v[202:205], v[34:37]
	v_mfma_f32_16x16x32_bf16 v[18:21], v[186:189], v[210:213], v[18:21]
	v_mfma_f32_16x16x32_bf16 v[2:5], v[186:189], v[218:221], v[2:5]
	s_barrier
; #define PG8_STAGE(bufoff, gbase, voff) do { _Pragma("unroll") for (int _i = 0; _i < 2; ++_i) \
;         __builtin_amdgcn_global_load_lds((const unsigned*)((const char*)(gbase) + (voff)[_i]), (LAS unsigned*)(lds + (bufoff) + ldsw + _i * 8192), 16, 0, 0); } while (0)
; #define PG8_LDA(dst, b, h) do { _Pragma("unroll") for (int m = 0; m < 4; ++m) _Pragma("unroll") for (int k = 0; k < 2; ++k) dst[m][k] = *(const LAS bf16x8*)(lds + PG8_SA(b, h) + aoff + m * 2048 + k * 1024); } while (0)
; #define PG8_LDB(dst, b, h) do { _Pragma("unroll") for (int n = 0; n < 2; ++n) _Pragma("unroll") for (int k = 0; k < 2; ++k) dst[n][k] = *(const LAS bf16x8*)(lds + PG8_SB(b, h) + boff + n * 2048 + k * 1024); } while (0)
; #define PG8_MMA(ai, bj, At, Bt) do { __builtin_amdgcn_s_setprio(1); _Pragma("unroll") for (int m = 0; m < 4; ++m) _Pragma("unroll") for (int n = 0; n < 2; ++n) _Pragma("unroll") for (int k = 0; k < 2; ++k) \
;         acc[ai][bj][m][n] = __builtin_amdgcn_mfma_f32_16x16x32_bf16(Bt[n][k], At[m][k], acc[ai][bj][m][n], 0, 0, 0); __builtin_amdgcn_s_setprio(0); } while (0)
; #define PG8_WAIT_V(n) asm volatile("s_waitcnt vmcnt(" #n ")" ::: "memory")
; #define PG8_WAIT_L(n) asm volatile("s_waitcnt lgkmcnt(" #n ")" ::: "memory")
; #define PG8_BAR __builtin_amdgcn_s_barrier()
; #define PG8_SCHED __builtin_amdgcn_sched_barrier(0)
; template <class Epi>
; __device__ __forceinline__ void gemm_phase(LAS unsigned char* lds, const Gemm g, const StaticOrder& S, const Epi& E) {
;     ...
;             PG8_LDB(B0, 1, 0); PG8_LDB(B1, 1, 1); PG8_SCHED; PG8_LDA(At, 1, 0); PG8_STAGE(PG8_SA(0, 1), a2 + hstep, voffA);
;             PG8_WAIT_V(8); PG8_WAIT_L(0); PG8_BAR; PG8_MMA(0, 0, At, B0); PG8_MMA(0, 1, At, B1); PG8_BAR; PG8_SCHED;
;             PG8_LDA(At, 1, 1); PG8_STAGE(PG8_SB(1, 0), b3, voffB); PG8_STAGE(PG8_SB(1, 1), b3 + hstep, voffB); PG8_STAGE(PG8_SA(1, 0), a3, voffA);
;             PG8_WAIT_V(8); PG8_WAIT_L(0); PG8_BAR; PG8_MMA(1, 0, At, B0); PG8_MMA(1, 1, At, B1); PG8_BAR; PG8_SCHED;
;         }
;         if (wr == 0) PG8_BAR;
	s_setprio 0
	s_add_i32 s85, 0, 0x18000
	s_add_i32 s86, 0, 0x1c000
	v_add_u32_e32 v166, s85, v160
	v_add_u32_e32 v186, s86, v160
	ds_read_b128 v[130:133], v166
	ds_read_b128 v[134:137], v166 offset:1024
	ds_read_b128 v[154:157], v166 offset:2048
	ds_read_b128 v[166:169], v166 offset:3072
	ds_read_b128 v[174:177], v186
	ds_read_b128 v[178:181], v186 offset:1024
	ds_read_b128 v[182:185], v186 offset:2048
	ds_read_b128 v[186:189], v186 offset:3072
	s_add_u32 s50, s50, 0xb0000
	s_addc_u32 s51, s51, 0
	s_mov_b32 m0, s61
	ds_read_b128 v[190:193], v164 offset:32768
	ds_read_b128 v[194:197], v164 offset:33792
	ds_read_b128 v[198:201], v164 offset:34816
	ds_read_b128 v[202:205], v164 offset:35840
	ds_read_b128 v[206:209], v164 offset:36864
	ds_read_b128 v[210:213], v164 offset:37888
	ds_read_b128 v[214:217], v164 offset:38912
	ds_read_b128 v[218:221], v164 offset:39936
	global_load_lds_dwordx4 v138, s[50:51]
	s_mov_b32 m0, s62
	s_nop 0
	global_load_lds_dwordx4 v142, s[50:51]
	s_waitcnt vmcnt(8)
	s_waitcnt lgkmcnt(0)
	s_setprio 1
	s_barrier
	v_mfma_f32_16x16x32_bf16 v[126:129], v[130:133], v[190:193], v[126:129]
	v_mfma_f32_16x16x32_bf16 v[110:113], v[130:133], v[198:201], v[110:113]
	v_mfma_f32_16x16x32_bf16 v[94:97], v[130:133], v[206:209], v[94:97]
	v_mfma_f32_16x16x32_bf16 v[78:81], v[130:133], v[214:217], v[78:81]
	v_mfma_f32_16x16x32_bf16 v[122:125], v[154:157], v[190:193], v[122:125]
	v_mfma_f32_16x16x32_bf16 v[106:109], v[154:157], v[198:201], v[106:109]
	v_mfma_f32_16x16x32_bf16 v[90:93], v[154:157], v[206:209], v[90:93]
	v_mfma_f32_16x16x32_bf16 v[74:77], v[154:157], v[214:217], v[74:77]
	v_mfma_f32_16x16x32_bf16 v[126:129], v[134:137], v[194:197], v[126:129]
	v_mfma_f32_16x16x32_bf16 v[110:113], v[134:137], v[202:205], v[110:113]
	v_mfma_f32_16x16x32_bf16 v[94:97], v[134:137], v[210:213], v[94:97]
	v_mfma_f32_16x16x32_bf16 v[78:81], v[134:137], v[218:221], v[78:81]
	v_mfma_f32_16x16x32_bf16 v[122:125], v[166:169], v[194:197], v[122:125]
	v_mfma_f32_16x16x32_bf16 v[106:109], v[166:169], v[202:205], v[106:109]
	v_mfma_f32_16x16x32_bf16 v[90:93], v[166:169], v[210:213], v[90:93]
	v_mfma_f32_16x16x32_bf16 v[74:77], v[166:169], v[218:221], v[74:77]
	v_mfma_f32_16x16x32_bf16 v[118:121], v[174:177], v[190:193], v[118:121]
	v_mfma_f32_16x16x32_bf16 v[102:105], v[174:177], v[198:201], v[102:105]
	v_mfma_f32_16x16x32_bf16 v[86:89], v[174:177], v[206:209], v[86:89]
	v_mfma_f32_16x16x32_bf16 v[70:73], v[174:177], v[214:217], v[70:73]
	v_mfma_f32_16x16x32_bf16 v[114:117], v[182:185], v[190:193], v[114:117]
	v_mfma_f32_16x16x32_bf16 v[98:101], v[182:185], v[198:201], v[98:101]
	v_mfma_f32_16x16x32_bf16 v[82:85], v[182:185], v[206:209], v[82:85]
	v_mfma_f32_16x16x32_bf16 v[66:69], v[182:185], v[214:217], v[66:69]
	v_mfma_f32_16x16x32_bf16 v[118:121], v[178:181], v[194:197], v[118:121]
	v_mfma_f32_16x16x32_bf16 v[102:105], v[178:181], v[202:205], v[102:105]
	v_mfma_f32_16x16x32_bf16 v[86:89], v[178:181], v[210:213], v[86:89]
	v_mfma_f32_16x16x32_bf16 v[70:73], v[178:181], v[218:221], v[70:73]
	v_mfma_f32_16x16x32_bf16 v[114:117], v[186:189], v[194:197], v[114:117]
	v_mfma_f32_16x16x32_bf16 v[98:101], v[186:189], v[202:205], v[98:101]
	v_mfma_f32_16x16x32_bf16 v[82:85], v[186:189], v[210:213], v[82:85]
	v_mfma_f32_16x16x32_bf16 v[66:69], v[186:189], v[218:221], v[66:69]
	s_barrier
	s_setprio 0
	s_add_i32 s50, s85, s58
	s_mov_b32 m0, s50
	ds_read_b128 v[190:193], v164 offset:49152
	ds_read_b128 v[194:197], v164 offset:50176
	ds_read_b128 v[198:201], v164 offset:51200
	ds_read_b128 v[202:205], v164 offset:52224
	ds_read_b128 v[206:209], v164 offset:53248
	ds_read_b128 v[210:213], v164 offset:54272
	ds_read_b128 v[214:217], v164 offset:55296
	ds_read_b128 v[218:221], v164 offset:56320
	global_load_lds_dwordx4 v140, s[98:99]
	s_add_i32 m0, s50, 0x2000
	s_add_u32 s48, s48, 0xb0080
	s_addc_u32 s49, s49, 0
	s_add_i32 s50, s86, s58
	global_load_lds_dwordx4 v144, s[98:99]
	s_mov_b32 m0, s50
	s_nop 0
	global_load_lds_dwordx4 v140, s[48:49]
	s_add_i32 m0, s50, 0x2000
	s_nop 0
	global_load_lds_dwordx4 v144, s[48:49]
	s_mov_b32 m0, s64
	s_nop 0
	global_load_lds_dwordx4 v138, s[100:101]
	s_mov_b32 m0, s65
	s_nop 0
	global_load_lds_dwordx4 v142, s[100:101]
	s_waitcnt vmcnt(8)
	s_waitcnt lgkmcnt(0)
	s_setprio 1
	s_barrier
	v_mfma_f32_16x16x32_bf16 v[62:65], v[130:133], v[190:193], v[62:65]
	v_mfma_f32_16x16x32_bf16 v[46:49], v[130:133], v[198:201], v[46:49]
	v_mfma_f32_16x16x32_bf16 v[30:33], v[130:133], v[206:209], v[30:33]
	v_mfma_f32_16x16x32_bf16 v[14:17], v[130:133], v[214:217], v[14:17]
	v_mfma_f32_16x16x32_bf16 v[58:61], v[154:157], v[190:193], v[58:61]
	v_mfma_f32_16x16x32_bf16 v[42:45], v[154:157], v[198:201], v[42:45]
	v_mfma_f32_16x16x32_bf16 v[26:29], v[154:157], v[206:209], v[26:29]
	v_mfma_f32_16x16x32_bf16 v[10:13], v[154:157], v[214:217], v[10:13]
	v_mfma_f32_16x16x32_bf16 v[62:65], v[134:137], v[194:197], v[62:65]
	v_mfma_f32_16x16x32_bf16 v[46:49], v[134:137], v[202:205], v[46:49]
	v_mfma_f32_16x16x32_bf16 v[30:33], v[134:137], v[210:213], v[30:33]
	v_mfma_f32_16x16x32_bf16 v[14:17], v[134:137], v[218:221], v[14:17]
	v_mfma_f32_16x16x32_bf16 v[58:61], v[166:169], v[194:197], v[58:61]
	v_mfma_f32_16x16x32_bf16 v[42:45], v[166:169], v[202:205], v[42:45]
	v_mfma_f32_16x16x32_bf16 v[26:29], v[166:169], v[210:213], v[26:29]
	v_mfma_f32_16x16x32_bf16 v[10:13], v[166:169], v[218:221], v[10:13]
	v_mfma_f32_16x16x32_bf16 v[54:57], v[174:177], v[190:193], v[54:57]
	v_mfma_f32_16x16x32_bf16 v[38:41], v[174:177], v[198:201], v[38:41]
	v_mfma_f32_16x16x32_bf16 v[22:25], v[174:177], v[206:209], v[22:25]
	v_mfma_f32_16x16x32_bf16 v[6:9], v[174:177], v[214:217], v[6:9]
	v_mfma_f32_16x16x32_bf16 v[50:53], v[182:185], v[190:193], v[50:53]
	v_mfma_f32_16x16x32_bf16 v[34:37], v[182:185], v[198:201], v[34:37]
	v_mfma_f32_16x16x32_bf16 v[18:21], v[182:185], v[206:209], v[18:21]
	v_mfma_f32_16x16x32_bf16 v[2:5], v[182:185], v[214:217], v[2:5]
	v_mfma_f32_16x16x32_bf16 v[54:57], v[178:181], v[194:197], v[54:57]
	v_mfma_f32_16x16x32_bf16 v[38:41], v[178:181], v[202:205], v[38:41]
	v_mfma_f32_16x16x32_bf16 v[22:25], v[178:181], v[210:213], v[22:25]
	v_mfma_f32_16x16x32_bf16 v[6:9], v[178:181], v[218:221], v[6:9]
	v_mfma_f32_16x16x32_bf16 v[50:53], v[186:189], v[194:197], v[50:53]
	v_mfma_f32_16x16x32_bf16 v[34:37], v[186:189], v[202:205], v[34:37]
	v_mfma_f32_16x16x32_bf16 v[18:21], v[186:189], v[210:213], v[18:21]
	v_mfma_f32_16x16x32_bf16 v[2:5], v[186:189], v[218:221], v[2:5]
	s_barrier
	s_setprio 0
	s_add_i32 s84, s84, 2
	s_add_u32 s46, s46, 0x100
	s_addc_u32 s47, s47, 0
	s_add_u32 s82, s82, 0x100
	s_addc_u32 s83, s83, 0
	s_cmp_gt_u32 s84, 41
	s_cbranch_scc0 .LBB0_221
	s_and_b64 vcc, exec, s[42:43]
	s_cbranch_vccz .LBB0_224
	s_barrier

; #define PG8_STAGE(bufoff, gbase, voff) do { _Pragma("unroll") for (int _i = 0; _i < 2; ++_i) \
;         __builtin_amdgcn_global_load_lds((const unsigned*)((const char*)(gbase) + (voff)[_i]), (LAS unsigned*)(lds + (bufoff) + ldsw + _i * 8192), 16, 0, 0); } while (0)
; #define PG8_LDA(dst, b, h) do { _Pragma("unroll") for (int m = 0; m < 4; ++m) _Pragma("unroll") for (int k = 0; k < 2; ++k) dst[m][k] = *(const LAS bf16x8*)(lds + PG8_SA(b, h) + aoff + m * 2048 + k * 1024); } while (0)
; #define PG8_LDB(dst, b, h) do { _Pragma("unroll") for (int n = 0; n < 2; ++n) _Pragma("unroll") for (int k = 0; k < 2; ++k) dst[n][k] = *(const LAS bf16x8*)(lds + PG8_SB(b, h) + boff + n * 2048 + k * 1024); } while (0)
; #define PG8_MMA(ai, bj, At, Bt) do { __builtin_amdgcn_s_setprio(1); _Pragma("unroll") for (int m = 0; m < 4; ++m) _Pragma("unroll") for (int n = 0; n < 2; ++n) _Pragma("unroll") for (int k = 0; k < 2; ++k) \
;         acc[ai][bj][m][n] = __builtin_amdgcn_mfma_f32_16x16x32_bf16(Bt[n][k], At[m][k], acc[ai][bj][m][n], 0, 0, 0); __builtin_amdgcn_s_setprio(0); } while (0)
; #define PG8_WAIT_V(n) asm volatile("s_waitcnt vmcnt(" #n ")" ::: "memory")
; #define PG8_WAIT_L(n) asm volatile("s_waitcnt lgkmcnt(" #n ")" ::: "memory")
; #define PG8_BAR __builtin_amdgcn_s_barrier()
; template <class Epi>
; __device__ __forceinline__ void gemm_phase(LAS unsigned char* lds, const Gemm g, const StaticOrder& S, const Epi& E) {
;     ...
;             const bool last = (t == nt - 2);
;             const char* a1 = cA + (size_t)(t + 1) * kstep;
;             const char* a2 = last ? nA : cA + (size_t)(t + 2) * kstep; const char* b2 = last ? nB : cB + (size_t)(t + 2) * kstep;
;             const char* a3 = a2 + kstep; const char* b3 = b2 + kstep;
;             if constexpr (Epi::MIDK > 0) { if (t == Epi::MIDK) E.mid(acc, cur, wr, wc, fr, fq); }
;             PG8_LDB(B0, 0, 0); PG8_LDB(B1, 0, 1); PG8_SCHED; PG8_LDA(At, 0, 0); PG8_STAGE(PG8_SA(1, 1), a1 + hstep, voffA);
;             PG8_WAIT_V(8); PG8_WAIT_L(0); PG8_BAR; PG8_MMA(0, 0, At, B0); PG8_MMA(0, 1, At, B1); PG8_BAR; PG8_SCHED;
;             PG8_LDA(At, 0, 1); PG8_STAGE(PG8_SB(0, 0), b2, voffB); PG8_STAGE(PG8_SB(0, 1), b2 + hstep, voffB); PG8_STAGE(PG8_SA(0, 0), a2, voffA);
;             PG8_WAIT_V(8); PG8_WAIT_L(0); PG8_BAR; PG8_MMA(1, 0, At, B0); PG8_MMA(1, 1, At, B1); PG8_BAR; PG8_SCHED;
.LBB0_322:
	ds_read_b128 v[130:133], v191
	ds_read_b128 v[134:137], v191 offset:1024
	ds_read_b128 v[138:141], v191 offset:2048
	ds_read_b128 v[142:145], v191 offset:3072
	ds_read_b128 v[166:169], v193
	ds_read_b128 v[172:175], v193 offset:1024
	ds_read_b128 v[176:179], v193 offset:2048
	ds_read_b128 v[180:183], v193 offset:3072
	s_add_u32 s76, s88, 0xfffc0080
	s_addc_u32 s77, s89, -1
	s_cmp_eq_u32 vcc_hi, 12
	s_cselect_b32 s93, s1, s77
	s_cselect_b32 s92, s7, s76
	s_cselect_b32 s91, s9, vcc_lo
	s_cselect_b32 s90, s46, s81
	s_add_i32 m0, s96, 0xc000
	ds_read_b128 v[200:203], v194
	ds_read_b128 v[204:207], v194 offset:1024
	ds_read_b128 v[208:211], v194 offset:2048
	ds_read_b128 v[212:215], v194 offset:3072
	ds_read_b128 v[216:219], v194 offset:4096
	ds_read_b128 v[220:223], v194 offset:5120
	ds_read_b128 v[224:227], v194 offset:6144
	ds_read_b128 v[228:231], v194 offset:7168
	global_load_lds_dwordx4 v158, s[88:89]
	s_add_i32 m0, s96, 0xe000
	s_nop 0
	global_load_lds_dwordx4 v160, s[88:89]
	s_waitcnt vmcnt(8)
	s_waitcnt lgkmcnt(0)
	s_setprio 1
	s_barrier
	v_mfma_f32_16x16x32_bf16 v[126:129], v[130:133], v[200:203], v[126:129]
	v_mfma_f32_16x16x32_bf16 v[110:113], v[130:133], v[208:211], v[110:113]
	v_mfma_f32_16x16x32_bf16 v[94:97], v[130:133], v[216:219], v[94:97]
	v_mfma_f32_16x16x32_bf16 v[78:81], v[130:133], v[224:227], v[78:81]
	v_mfma_f32_16x16x32_bf16 v[122:125], v[138:141], v[200:203], v[122:125]
	v_mfma_f32_16x16x32_bf16 v[106:109], v[138:141], v[208:211], v[106:109]
	v_mfma_f32_16x16x32_bf16 v[90:93], v[138:141], v[216:219], v[90:93]
	v_mfma_f32_16x16x32_bf16 v[74:77], v[138:141], v[224:227], v[74:77]
	v_mfma_f32_16x16x32_bf16 v[126:129], v[134:137], v[204:207], v[126:129]
	v_mfma_f32_16x16x32_bf16 v[110:113], v[134:137], v[212:215], v[110:113]
	v_mfma_f32_16x16x32_bf16 v[94:97], v[134:137], v[220:223], v[94:97]
	v_mfma_f32_16x16x32_bf16 v[78:81], v[134:137], v[228:231], v[78:81]
	v_mfma_f32_16x16x32_bf16 v[122:125], v[142:145], v[204:207], v[122:125]
	v_mfma_f32_16x16x32_bf16 v[106:109], v[142:145], v[212:215], v[106:109]
	v_mfma_f32_16x16x32_bf16 v[90:93], v[142:145], v[220:223], v[90:93]
	v_mfma_f32_16x16x32_bf16 v[74:77], v[142:145], v[228:231], v[74:77]
	v_mfma_f32_16x16x32_bf16 v[118:121], v[166:169], v[200:203], v[118:121]
	v_mfma_f32_16x16x32_bf16 v[102:105], v[166:169], v[208:211], v[102:105]
	v_mfma_f32_16x16x32_bf16 v[86:89], v[166:169], v[216:219], v[86:89]
	v_mfma_f32_16x16x32_bf16 v[70:73], v[166:169], v[224:227], v[70:73]
	v_mfma_f32_16x16x32_bf16 v[114:117], v[176:179], v[200:203], v[114:117]
	v_mfma_f32_16x16x32_bf16 v[98:101], v[176:179], v[208:211], v[98:101]
	v_mfma_f32_16x16x32_bf16 v[82:85], v[176:179], v[216:219], v[82:85]
	v_mfma_f32_16x16x32_bf16 v[66:69], v[176:179], v[224:227], v[66:69]
	v_mfma_f32_16x16x32_bf16 v[118:121], v[172:175], v[204:207], v[118:121]
	v_mfma_f32_16x16x32_bf16 v[102:105], v[172:175], v[212:215], v[102:105]
	v_mfma_f32_16x16x32_bf16 v[86:89], v[172:175], v[220:223], v[86:89]
	v_mfma_f32_16x16x32_bf16 v[70:73], v[172:175], v[228:231], v[70:73]
	v_mfma_f32_16x16x32_bf16 v[114:117], v[180:183], v[204:207], v[114:117]
	v_mfma_f32_16x16x32_bf16 v[98:101], v[180:183], v[212:215], v[98:101]
	v_mfma_f32_16x16x32_bf16 v[82:85], v[180:183], v[220:223], v[82:85]
	v_mfma_f32_16x16x32_bf16 v[66:69], v[180:183], v[228:231], v[66:69]
	s_barrier
	s_setprio 0
	s_add_u32 s98, s90, s50
	s_addc_u32 s99, s91, s51
	s_add_u32 s100, s92, s50
	s_addc_u32 s101, s93, s51
	s_add_i32 s76, s42, s44
	s_mov_b32 m0, s76
	ds_read_b128 v[200:203], v194 offset:16384
	ds_read_b128 v[204:207], v194 offset:17408
	ds_read_b128 v[208:211], v194 offset:18432
	ds_read_b128 v[212:215], v194 offset:19456
	ds_read_b128 v[216:219], v194 offset:20480
	ds_read_b128 v[220:223], v194 offset:21504
	ds_read_b128 v[224:227], v194 offset:22528
	ds_read_b128 v[228:231], v194 offset:23552
	global_load_lds_dwordx4 v148, s[90:91]
	s_add_i32 m0, s76, 0x2000
	s_add_u32 s76, s90, 0x40000
	s_addc_u32 s77, s91, 0
	s_add_i32 s60, s43, s44
	global_load_lds_dwordx4 v152, s[90:91]
	s_mov_b32 m0, s60
	s_nop 0
	global_load_lds_dwordx4 v148, s[76:77]
	s_add_i32 m0, s60, 0x2000
	s_nop 0
	global_load_lds_dwordx4 v152, s[76:77]
	s_mov_b32 m0, s96
	s_nop 0
	global_load_lds_dwordx4 v146, s[92:93]
	s_mov_b32 m0, s97
	s_nop 0
	global_load_lds_dwordx4 v150, s[92:93]
	s_waitcnt vmcnt(8)
	s_waitcnt lgkmcnt(0)
	s_setprio 1
	s_barrier
	v_mfma_f32_16x16x32_bf16 v[62:65], v[130:133], v[200:203], v[62:65]
	v_mfma_f32_16x16x32_bf16 v[46:49], v[130:133], v[208:211], v[46:49]
	v_mfma_f32_16x16x32_bf16 v[30:33], v[130:133], v[216:219], v[30:33]
	v_mfma_f32_16x16x32_bf16 v[14:17], v[130:133], v[224:227], v[14:17]
	v_mfma_f32_16x16x32_bf16 v[58:61], v[138:141], v[200:203], v[58:61]
	v_mfma_f32_16x16x32_bf16 v[42:45], v[138:141], v[208:211], v[42:45]
	v_mfma_f32_16x16x32_bf16 v[26:29], v[138:141], v[216:219], v[26:29]
	v_mfma_f32_16x16x32_bf16 v[10:13], v[138:141], v[224:227], v[10:13]
	v_mfma_f32_16x16x32_bf16 v[62:65], v[134:137], v[204:207], v[62:65]
	v_mfma_f32_16x16x32_bf16 v[46:49], v[134:137], v[212:215], v[46:49]
	v_mfma_f32_16x16x32_bf16 v[30:33], v[134:137], v[220:223], v[30:33]
	v_mfma_f32_16x16x32_bf16 v[14:17], v[134:137], v[228:231], v[14:17]
	v_mfma_f32_16x16x32_bf16 v[58:61], v[142:145], v[204:207], v[58:61]
	v_mfma_f32_16x16x32_bf16 v[42:45], v[142:145], v[212:215], v[42:45]
	v_mfma_f32_16x16x32_bf16 v[26:29], v[142:145], v[220:223], v[26:29]
	v_mfma_f32_16x16x32_bf16 v[10:13], v[142:145], v[228:231], v[10:13]
	v_mfma_f32_16x16x32_bf16 v[54:57], v[166:169], v[200:203], v[54:57]
	v_mfma_f32_16x16x32_bf16 v[38:41], v[166:169], v[208:211], v[38:41]
	v_mfma_f32_16x16x32_bf16 v[22:25], v[166:169], v[216:219], v[22:25]
	v_mfma_f32_16x16x32_bf16 v[6:9], v[166:169], v[224:227], v[6:9]
	v_mfma_f32_16x16x32_bf16 v[50:53], v[176:179], v[200:203], v[50:53]
	v_mfma_f32_16x16x32_bf16 v[34:37], v[176:179], v[208:211], v[34:37]
	v_mfma_f32_16x16x32_bf16 v[18:21], v[176:179], v[216:219], v[18:21]
	v_mfma_f32_16x16x32_bf16 v[2:5], v[176:179], v[224:227], v[2:5]
	v_mfma_f32_16x16x32_bf16 v[54:57], v[172:175], v[204:207], v[54:57]
	v_mfma_f32_16x16x32_bf16 v[38:41], v[172:175], v[212:215], v[38:41]
	v_mfma_f32_16x16x32_bf16 v[22:25], v[172:175], v[220:223], v[22:25]
	v_mfma_f32_16x16x32_bf16 v[6:9], v[172:175], v[228:231], v[6:9]
	v_mfma_f32_16x16x32_bf16 v[50:53], v[180:183], v[204:207], v[50:53]
	v_mfma_f32_16x16x32_bf16 v[34:37], v[180:183], v[212:215], v[34:37]
	v_mfma_f32_16x16x32_bf16 v[18:21], v[180:183], v[220:223], v[18:21]
	v_mfma_f32_16x16x32_bf16 v[2:5], v[180:183], v[228:231], v[2:5]
	s_barrier
; #define PG8_STAGE(bufoff, gbase, voff) do { _Pragma("unroll") for (int _i = 0; _i < 2; ++_i) \
;         __builtin_amdgcn_global_load_lds((const unsigned*)((const char*)(gbase) + (voff)[_i]), (LAS unsigned*)(lds + (bufoff) + ldsw + _i * 8192), 16, 0, 0); } while (0)
; #define PG8_LDA(dst, b, h) do { _Pragma("unroll") for (int m = 0; m < 4; ++m) _Pragma("unroll") for (int k = 0; k < 2; ++k) dst[m][k] = *(const LAS bf16x8*)(lds + PG8_SA(b, h) + aoff + m * 2048 + k * 1024); } while (0)
; #define PG8_LDB(dst, b, h) do { _Pragma("unroll") for (int n = 0; n < 2; ++n) _Pragma("unroll") for (int k = 0; k < 2; ++k) dst[n][k] = *(const LAS bf16x8*)(lds + PG8_SB(b, h) + boff + n * 2048 + k * 1024); } while (0)
; #define PG8_MMA(ai, bj, At, Bt) do { __builtin_amdgcn_s_setprio(1); _Pragma("unroll") for (int m = 0; m < 4; ++m) _Pragma("unroll") for (int n = 0; n < 2; ++n) _Pragma("unroll") for (int k = 0; k < 2; ++k) \
;         acc[ai][bj][m][n] = __builtin_amdgcn_mfma_f32_16x16x32_bf16(Bt[n][k], At[m][k], acc[ai][bj][m][n], 0, 0, 0); __builtin_amdgcn_s_setprio(0); } while (0)
; #define PG8_WAIT_V(n) asm volatile("s_waitcnt vmcnt(" #n ")" ::: "memory")
; #define PG8_WAIT_L(n) asm volatile("s_waitcnt lgkmcnt(" #n ")" ::: "memory")
; #define PG8_BAR __builtin_amdgcn_s_barrier()
; #define PG8_SCHED __builtin_amdgcn_sched_barrier(0)
; template <class Epi>
; __device__ __forceinline__ void gemm_phase(LAS unsigned char* lds, const Gemm g, const StaticOrder& S, const Epi& E) {
;     ...
;             PG8_LDB(B0, 1, 0); PG8_LDB(B1, 1, 1); PG8_SCHED; PG8_LDA(At, 1, 0); PG8_STAGE(PG8_SA(0, 1), a2 + hstep, voffA);
;             PG8_WAIT_V(8); PG8_WAIT_L(0); PG8_BAR; PG8_MMA(0, 0, At, B0); PG8_MMA(0, 1, At, B1); PG8_BAR; PG8_SCHED;
;             PG8_LDA(At, 1, 1); PG8_STAGE(PG8_SB(1, 0), b3, voffB); PG8_STAGE(PG8_SB(1, 1), b3 + hstep, voffB); PG8_STAGE(PG8_SA(1, 0), a3, voffA);
;             PG8_WAIT_V(8); PG8_WAIT_L(0); PG8_BAR; PG8_MMA(1, 0, At, B0); PG8_MMA(1, 1, At, B1); PG8_BAR; PG8_SCHED;
;         }
;         if (wr == 0) PG8_BAR;
	s_setprio 0
	s_add_i32 s60, 0, 0x18000
	s_add_i32 s61, 0, 0x1c000
	v_add_u32_e32 v142, s60, v187
	v_add_u32_e32 v180, s61, v187
	ds_read_b128 v[130:133], v142
	ds_read_b128 v[134:137], v142 offset:1024
	ds_read_b128 v[138:141], v142 offset:2048
	ds_read_b128 v[142:145], v142 offset:3072
	ds_read_b128 v[166:169], v180
	ds_read_b128 v[172:175], v180 offset:1024
	ds_read_b128 v[176:179], v180 offset:2048
	ds_read_b128 v[180:183], v180 offset:3072
	s_add_u32 s76, s92, 0x40000
	s_addc_u32 s77, s93, 0
	s_mov_b32 m0, s11
	ds_read_b128 v[200:203], v194 offset:32768
	ds_read_b128 v[204:207], v194 offset:33792
	ds_read_b128 v[208:211], v194 offset:34816
	ds_read_b128 v[212:215], v194 offset:35840
	ds_read_b128 v[216:219], v194 offset:36864
	ds_read_b128 v[220:223], v194 offset:37888
	ds_read_b128 v[224:227], v194 offset:38912
	ds_read_b128 v[228:231], v194 offset:39936
	global_load_lds_dwordx4 v146, s[76:77]
	s_mov_b32 m0, s94
	s_nop 0
	global_load_lds_dwordx4 v150, s[76:77]
	s_waitcnt vmcnt(8)
	s_waitcnt lgkmcnt(0)
	s_setprio 1
	s_barrier
	v_mfma_f32_16x16x32_bf16 v[126:129], v[130:133], v[200:203], v[126:129]
	v_mfma_f32_16x16x32_bf16 v[110:113], v[130:133], v[208:211], v[110:113]
	v_mfma_f32_16x16x32_bf16 v[94:97], v[130:133], v[216:219], v[94:97]
	v_mfma_f32_16x16x32_bf16 v[78:81], v[130:133], v[224:227], v[78:81]
	v_mfma_f32_16x16x32_bf16 v[122:125], v[138:141], v[200:203], v[122:125]
	v_mfma_f32_16x16x32_bf16 v[106:109], v[138:141], v[208:211], v[106:109]
	v_mfma_f32_16x16x32_bf16 v[90:93], v[138:141], v[216:219], v[90:93]
	v_mfma_f32_16x16x32_bf16 v[74:77], v[138:141], v[224:227], v[74:77]
	v_mfma_f32_16x16x32_bf16 v[126:129], v[134:137], v[204:207], v[126:129]
	v_mfma_f32_16x16x32_bf16 v[110:113], v[134:137], v[212:215], v[110:113]
	v_mfma_f32_16x16x32_bf16 v[94:97], v[134:137], v[220:223], v[94:97]
	v_mfma_f32_16x16x32_bf16 v[78:81], v[134:137], v[228:231], v[78:81]
	v_mfma_f32_16x16x32_bf16 v[122:125], v[142:145], v[204:207], v[122:125]
	v_mfma_f32_16x16x32_bf16 v[106:109], v[142:145], v[212:215], v[106:109]
	v_mfma_f32_16x16x32_bf16 v[90:93], v[142:145], v[220:223], v[90:93]
	v_mfma_f32_16x16x32_bf16 v[74:77], v[142:145], v[228:231], v[74:77]
	v_mfma_f32_16x16x32_bf16 v[118:121], v[166:169], v[200:203], v[118:121]
	v_mfma_f32_16x16x32_bf16 v[102:105], v[166:169], v[208:211], v[102:105]
	v_mfma_f32_16x16x32_bf16 v[86:89], v[166:169], v[216:219], v[86:89]
	v_mfma_f32_16x16x32_bf16 v[70:73], v[166:169], v[224:227], v[70:73]
	v_mfma_f32_16x16x32_bf16 v[114:117], v[176:179], v[200:203], v[114:117]
	v_mfma_f32_16x16x32_bf16 v[98:101], v[176:179], v[208:211], v[98:101]
	v_mfma_f32_16x16x32_bf16 v[82:85], v[176:179], v[216:219], v[82:85]
	v_mfma_f32_16x16x32_bf16 v[66:69], v[176:179], v[224:227], v[66:69]
	v_mfma_f32_16x16x32_bf16 v[118:121], v[172:175], v[204:207], v[118:121]
	v_mfma_f32_16x16x32_bf16 v[102:105], v[172:175], v[212:215], v[102:105]
	v_mfma_f32_16x16x32_bf16 v[86:89], v[172:175], v[220:223], v[86:89]
	v_mfma_f32_16x16x32_bf16 v[70:73], v[172:175], v[228:231], v[70:73]
	v_mfma_f32_16x16x32_bf16 v[114:117], v[180:183], v[204:207], v[114:117]
	v_mfma_f32_16x16x32_bf16 v[98:101], v[180:183], v[212:215], v[98:101]
	v_mfma_f32_16x16x32_bf16 v[82:85], v[180:183], v[220:223], v[82:85]
	v_mfma_f32_16x16x32_bf16 v[66:69], v[180:183], v[228:231], v[66:69]
	s_barrier
	s_setprio 0
	s_add_i32 s60, s60, s44
	s_mov_b32 m0, s60
	ds_read_b128 v[200:203], v194 offset:49152
	ds_read_b128 v[204:207], v194 offset:50176
	ds_read_b128 v[208:211], v194 offset:51200
	ds_read_b128 v[212:215], v194 offset:52224
	ds_read_b128 v[216:219], v194 offset:53248
	ds_read_b128 v[220:223], v194 offset:54272
	ds_read_b128 v[224:227], v194 offset:55296
	ds_read_b128 v[228:231], v194 offset:56320
	global_load_lds_dwordx4 v148, s[98:99]
	s_add_i32 m0, s60, 0x2000
	s_add_u32 s76, s90, 0x40080
	s_addc_u32 s77, s91, 0
	s_add_i32 s60, s61, s44
	global_load_lds_dwordx4 v152, s[98:99]
	s_mov_b32 m0, s60
	s_nop 0
	global_load_lds_dwordx4 v148, s[76:77]
	s_add_i32 m0, s60, 0x2000
	s_nop 0
	global_load_lds_dwordx4 v152, s[76:77]
	s_mov_b32 m0, s79
	s_nop 0
	global_load_lds_dwordx4 v146, s[100:101]
	s_mov_b32 m0, s33
	s_nop 0
	global_load_lds_dwordx4 v150, s[100:101]
	s_waitcnt vmcnt(8)
	s_waitcnt lgkmcnt(0)
	s_setprio 1
	s_barrier
	v_mfma_f32_16x16x32_bf16 v[62:65], v[130:133], v[200:203], v[62:65]
	v_mfma_f32_16x16x32_bf16 v[46:49], v[130:133], v[208:211], v[46:49]
	v_mfma_f32_16x16x32_bf16 v[30:33], v[130:133], v[216:219], v[30:33]
	v_mfma_f32_16x16x32_bf16 v[14:17], v[130:133], v[224:227], v[14:17]
	v_mfma_f32_16x16x32_bf16 v[58:61], v[138:141], v[200:203], v[58:61]
	v_mfma_f32_16x16x32_bf16 v[42:45], v[138:141], v[208:211], v[42:45]
	v_mfma_f32_16x16x32_bf16 v[26:29], v[138:141], v[216:219], v[26:29]
	v_mfma_f32_16x16x32_bf16 v[10:13], v[138:141], v[224:227], v[10:13]
	v_mfma_f32_16x16x32_bf16 v[62:65], v[134:137], v[204:207], v[62:65]
	v_mfma_f32_16x16x32_bf16 v[46:49], v[134:137], v[212:215], v[46:49]
	v_mfma_f32_16x16x32_bf16 v[30:33], v[134:137], v[220:223], v[30:33]
	v_mfma_f32_16x16x32_bf16 v[14:17], v[134:137], v[228:231], v[14:17]
	v_mfma_f32_16x16x32_bf16 v[58:61], v[142:145], v[204:207], v[58:61]
	v_mfma_f32_16x16x32_bf16 v[42:45], v[142:145], v[212:215], v[42:45]
	v_mfma_f32_16x16x32_bf16 v[26:29], v[142:145], v[220:223], v[26:29]
	v_mfma_f32_16x16x32_bf16 v[10:13], v[142:145], v[228:231], v[10:13]
	v_mfma_f32_16x16x32_bf16 v[54:57], v[166:169], v[200:203], v[54:57]
	v_mfma_f32_16x16x32_bf16 v[38:41], v[166:169], v[208:211], v[38:41]
	v_mfma_f32_16x16x32_bf16 v[22:25], v[166:169], v[216:219], v[22:25]
	v_mfma_f32_16x16x32_bf16 v[6:9], v[166:169], v[224:227], v[6:9]
	v_mfma_f32_16x16x32_bf16 v[50:53], v[176:179], v[200:203], v[50:53]
	v_mfma_f32_16x16x32_bf16 v[34:37], v[176:179], v[208:211], v[34:37]
	v_mfma_f32_16x16x32_bf16 v[18:21], v[176:179], v[216:219], v[18:21]
	v_mfma_f32_16x16x32_bf16 v[2:5], v[176:179], v[224:227], v[2:5]
	v_mfma_f32_16x16x32_bf16 v[54:57], v[172:175], v[204:207], v[54:57]
	v_mfma_f32_16x16x32_bf16 v[38:41], v[172:175], v[212:215], v[38:41]
	v_mfma_f32_16x16x32_bf16 v[22:25], v[172:175], v[220:223], v[22:25]
	v_mfma_f32_16x16x32_bf16 v[6:9], v[172:175], v[228:231], v[6:9]
	v_mfma_f32_16x16x32_bf16 v[50:53], v[180:183], v[204:207], v[50:53]
	v_mfma_f32_16x16x32_bf16 v[34:37], v[180:183], v[212:215], v[34:37]
	v_mfma_f32_16x16x32_bf16 v[18:21], v[180:183], v[220:223], v[18:21]
	v_mfma_f32_16x16x32_bf16 v[2:5], v[180:183], v[228:231], v[2:5]
	s_barrier
	s_setprio 0
	s_add_i32 vcc_hi, vcc_hi, 2
	s_add_u32 s88, s88, 0x100
	s_addc_u32 s89, s89, 0
	s_add_u32 s81, s81, 0x100
	s_addc_u32 vcc_lo, vcc_lo, 0
	s_cmp_gt_u32 vcc_hi, 13
	s_cbranch_scc0 .LBB0_322
	s_and_b64 vcc, exec, s[58:59]
	s_cbranch_vccz .LBB0_325
	s_barrier

; #define PG8_STAGE(bufoff, gbase, voff) do { _Pragma("unroll") for (int _i = 0; _i < 2; ++_i) \
;         __builtin_amdgcn_global_load_lds((const unsigned*)((const char*)(gbase) + (voff)[_i]), (LAS unsigned*)(lds + (bufoff) + ldsw + _i * 8192), 16, 0, 0); } while (0)
; #define PG8_LDA(dst, b, h) do { _Pragma("unroll") for (int m = 0; m < 4; ++m) _Pragma("unroll") for (int k = 0; k < 2; ++k) dst[m][k] = *(const LAS bf16x8*)(lds + PG8_SA(b, h) + aoff + m * 2048 + k * 1024); } while (0)
; #define PG8_LDB(dst, b, h) do { _Pragma("unroll") for (int n = 0; n < 2; ++n) _Pragma("unroll") for (int k = 0; k < 2; ++k) dst[n][k] = *(const LAS bf16x8*)(lds + PG8_SB(b, h) + boff + n * 2048 + k * 1024); } while (0)
; #define PG8_MMA(ai, bj, At, Bt) do { __builtin_amdgcn_s_setprio(1); _Pragma("unroll") for (int m = 0; m < 4; ++m) _Pragma("unroll") for (int n = 0; n < 2; ++n) _Pragma("unroll") for (int k = 0; k < 2; ++k) \
;         acc[ai][bj][m][n] = __builtin_amdgcn_mfma_f32_16x16x32_bf16(Bt[n][k], At[m][k], acc[ai][bj][m][n], 0, 0, 0); __builtin_amdgcn_s_setprio(0); } while (0)
; #define PG8_WAIT_V(n) asm volatile("s_waitcnt vmcnt(" #n ")" ::: "memory")
; #define PG8_WAIT_L(n) asm volatile("s_waitcnt lgkmcnt(" #n ")" ::: "memory")
; #define PG8_BAR __builtin_amdgcn_s_barrier()
; template <class Epi>
; __device__ __forceinline__ void gemm_phase(LAS unsigned char* lds, const Gemm g, const StaticOrder& S, const Epi& E) {
;     ...
;             const bool last = (t == nt - 2);
;             const char* a1 = cA + (size_t)(t + 1) * kstep;
;             const char* a2 = last ? nA : cA + (size_t)(t + 2) * kstep; const char* b2 = last ? nB : cB + (size_t)(t + 2) * kstep;
;             const char* a3 = a2 + kstep; const char* b3 = b2 + kstep;
;             if constexpr (Epi::MIDK > 0) { if (t == Epi::MIDK) E.mid(acc, cur, wr, wc, fr, fq); }
;             PG8_LDB(B0, 0, 0); PG8_LDB(B1, 0, 1); PG8_SCHED; PG8_LDA(At, 0, 0); PG8_STAGE(PG8_SA(1, 1), a1 + hstep, voffA);
;             PG8_WAIT_V(8); PG8_WAIT_L(0); PG8_BAR; PG8_MMA(0, 0, At, B0); PG8_MMA(0, 1, At, B1); PG8_BAR; PG8_SCHED;
;             PG8_LDA(At, 0, 1); PG8_STAGE(PG8_SB(0, 0), b2, voffB); PG8_STAGE(PG8_SB(0, 1), b2 + hstep, voffB); PG8_STAGE(PG8_SA(0, 0), a2, voffA);
;             PG8_WAIT_V(8); PG8_WAIT_L(0); PG8_BAR; PG8_MMA(1, 0, At, B0); PG8_MMA(1, 1, At, B1); PG8_BAR; PG8_SCHED;
.LBB0_619:
	ds_read_b128 v[154:157], v174
	ds_read_b128 v[158:161], v174 offset:1024
	ds_read_b128 v[162:165], v174 offset:2048
	ds_read_b128 v[166:169], v174 offset:3072
	ds_read_b128 v[182:185], v175
	ds_read_b128 v[186:189], v175 offset:1024
	ds_read_b128 v[190:193], v175 offset:2048
	ds_read_b128 v[194:197], v175 offset:3072
	s_add_u32 s46, s44, 0xfffc0080
	s_addc_u32 s47, s45, -1
	s_cmp_eq_u32 s69, 12
	s_cselect_b32 s49, s64, s47
	s_cselect_b32 s48, s65, s46
	s_cselect_b32 s47, s25, s68
	s_cselect_b32 s46, s66, s67
	s_add_i32 m0, s43, 0xc000
	ds_read_b128 v[198:201], v176
	ds_read_b128 v[202:205], v176 offset:1024
	ds_read_b128 v[206:209], v176 offset:2048
	ds_read_b128 v[210:213], v176 offset:3072
	ds_read_b128 v[214:217], v176 offset:4096
	ds_read_b128 v[218:221], v176 offset:5120
	ds_read_b128 v[222:225], v176 offset:6144
	ds_read_b128 v[226:229], v176 offset:7168
	global_load_lds_dwordx4 v144, s[44:45]
	s_add_i32 m0, s43, 0xe000
	s_nop 0
	global_load_lds_dwordx4 v146, s[44:45]
	s_waitcnt vmcnt(8)
	s_waitcnt lgkmcnt(0)
	s_setprio 1
	s_barrier
	v_mfma_f32_16x16x32_bf16 v[126:129], v[154:157], v[198:201], v[126:129]
	v_mfma_f32_16x16x32_bf16 v[110:113], v[154:157], v[206:209], v[110:113]
	v_mfma_f32_16x16x32_bf16 v[94:97], v[154:157], v[214:217], v[94:97]
	v_mfma_f32_16x16x32_bf16 v[78:81], v[154:157], v[222:225], v[78:81]
	v_mfma_f32_16x16x32_bf16 v[122:125], v[162:165], v[198:201], v[122:125]
	v_mfma_f32_16x16x32_bf16 v[106:109], v[162:165], v[206:209], v[106:109]
	v_mfma_f32_16x16x32_bf16 v[90:93], v[162:165], v[214:217], v[90:93]
	v_mfma_f32_16x16x32_bf16 v[74:77], v[162:165], v[222:225], v[74:77]
	v_mfma_f32_16x16x32_bf16 v[126:129], v[158:161], v[202:205], v[126:129]
	v_mfma_f32_16x16x32_bf16 v[110:113], v[158:161], v[210:213], v[110:113]
	v_mfma_f32_16x16x32_bf16 v[94:97], v[158:161], v[218:221], v[94:97]
	v_mfma_f32_16x16x32_bf16 v[78:81], v[158:161], v[226:229], v[78:81]
	v_mfma_f32_16x16x32_bf16 v[122:125], v[166:169], v[202:205], v[122:125]
	v_mfma_f32_16x16x32_bf16 v[106:109], v[166:169], v[210:213], v[106:109]
	v_mfma_f32_16x16x32_bf16 v[90:93], v[166:169], v[218:221], v[90:93]
	v_mfma_f32_16x16x32_bf16 v[74:77], v[166:169], v[226:229], v[74:77]
	v_mfma_f32_16x16x32_bf16 v[118:121], v[182:185], v[198:201], v[118:121]
	v_mfma_f32_16x16x32_bf16 v[102:105], v[182:185], v[206:209], v[102:105]
	v_mfma_f32_16x16x32_bf16 v[86:89], v[182:185], v[214:217], v[86:89]
	v_mfma_f32_16x16x32_bf16 v[70:73], v[182:185], v[222:225], v[70:73]
	v_mfma_f32_16x16x32_bf16 v[114:117], v[190:193], v[198:201], v[114:117]
	v_mfma_f32_16x16x32_bf16 v[98:101], v[190:193], v[206:209], v[98:101]
	v_mfma_f32_16x16x32_bf16 v[82:85], v[190:193], v[214:217], v[82:85]
	v_mfma_f32_16x16x32_bf16 v[66:69], v[190:193], v[222:225], v[66:69]
	v_mfma_f32_16x16x32_bf16 v[118:121], v[186:189], v[202:205], v[118:121]
	v_mfma_f32_16x16x32_bf16 v[102:105], v[186:189], v[210:213], v[102:105]
	v_mfma_f32_16x16x32_bf16 v[86:89], v[186:189], v[218:221], v[86:89]
	v_mfma_f32_16x16x32_bf16 v[70:73], v[186:189], v[226:229], v[70:73]
	v_mfma_f32_16x16x32_bf16 v[114:117], v[194:197], v[202:205], v[114:117]
	v_mfma_f32_16x16x32_bf16 v[98:101], v[194:197], v[210:213], v[98:101]
	v_mfma_f32_16x16x32_bf16 v[82:85], v[194:197], v[218:221], v[82:85]
	v_mfma_f32_16x16x32_bf16 v[66:69], v[194:197], v[226:229], v[66:69]
	s_barrier
	s_setprio 0
	s_add_u32 s98, s46, s8
	s_addc_u32 s99, s47, s9
	s_add_u32 s100, s48, s8
	s_addc_u32 s101, s49, s9
	s_add_i32 s76, s60, s6
	s_mov_b32 m0, s76
	ds_read_b128 v[198:201], v176 offset:16384
	ds_read_b128 v[202:205], v176 offset:17408
	ds_read_b128 v[206:209], v176 offset:18432
	ds_read_b128 v[210:213], v176 offset:19456
	ds_read_b128 v[214:217], v176 offset:20480
	ds_read_b128 v[218:221], v176 offset:21504
	ds_read_b128 v[222:225], v176 offset:22528
	ds_read_b128 v[226:229], v176 offset:23552
	global_load_lds_dwordx4 v132, s[46:47]
	s_add_i32 m0, s76, 0x2000
	s_add_u32 s76, s46, 0x40000
	s_addc_u32 s77, s47, 0
	s_add_i32 s78, s61, s6
	global_load_lds_dwordx4 v136, s[46:47]
	s_mov_b32 m0, s78
	s_nop 0
	global_load_lds_dwordx4 v132, s[76:77]
	s_add_i32 m0, s78, 0x2000
	s_nop 0
	global_load_lds_dwordx4 v136, s[76:77]
	s_mov_b32 m0, s43
	s_nop 0
	global_load_lds_dwordx4 v130, s[48:49]
	s_mov_b32 m0, s51
	s_nop 0
	global_load_lds_dwordx4 v134, s[48:49]
	s_waitcnt vmcnt(8)
	s_waitcnt lgkmcnt(0)
	s_setprio 1
	s_barrier
	v_mfma_f32_16x16x32_bf16 v[62:65], v[154:157], v[198:201], v[62:65]
	v_mfma_f32_16x16x32_bf16 v[46:49], v[154:157], v[206:209], v[46:49]
	v_mfma_f32_16x16x32_bf16 v[30:33], v[154:157], v[214:217], v[30:33]
	v_mfma_f32_16x16x32_bf16 v[14:17], v[154:157], v[222:225], v[14:17]
	v_mfma_f32_16x16x32_bf16 v[58:61], v[162:165], v[198:201], v[58:61]
	v_mfma_f32_16x16x32_bf16 v[42:45], v[162:165], v[206:209], v[42:45]
	v_mfma_f32_16x16x32_bf16 v[26:29], v[162:165], v[214:217], v[26:29]
	v_mfma_f32_16x16x32_bf16 v[10:13], v[162:165], v[222:225], v[10:13]
	v_mfma_f32_16x16x32_bf16 v[62:65], v[158:161], v[202:205], v[62:65]
	v_mfma_f32_16x16x32_bf16 v[46:49], v[158:161], v[210:213], v[46:49]
	v_mfma_f32_16x16x32_bf16 v[30:33], v[158:161], v[218:221], v[30:33]
	v_mfma_f32_16x16x32_bf16 v[14:17], v[158:161], v[226:229], v[14:17]
	v_mfma_f32_16x16x32_bf16 v[58:61], v[166:169], v[202:205], v[58:61]
	v_mfma_f32_16x16x32_bf16 v[42:45], v[166:169], v[210:213], v[42:45]
	v_mfma_f32_16x16x32_bf16 v[26:29], v[166:169], v[218:221], v[26:29]
	v_mfma_f32_16x16x32_bf16 v[10:13], v[166:169], v[226:229], v[10:13]
	v_mfma_f32_16x16x32_bf16 v[54:57], v[182:185], v[198:201], v[54:57]
	v_mfma_f32_16x16x32_bf16 v[38:41], v[182:185], v[206:209], v[38:41]
	v_mfma_f32_16x16x32_bf16 v[22:25], v[182:185], v[214:217], v[22:25]
	v_mfma_f32_16x16x32_bf16 v[6:9], v[182:185], v[222:225], v[6:9]
	v_mfma_f32_16x16x32_bf16 v[50:53], v[190:193], v[198:201], v[50:53]
	v_mfma_f32_16x16x32_bf16 v[34:37], v[190:193], v[206:209], v[34:37]
	v_mfma_f32_16x16x32_bf16 v[18:21], v[190:193], v[214:217], v[18:21]
	v_mfma_f32_16x16x32_bf16 v[2:5], v[190:193], v[222:225], v[2:5]
	v_mfma_f32_16x16x32_bf16 v[54:57], v[186:189], v[202:205], v[54:57]
	v_mfma_f32_16x16x32_bf16 v[38:41], v[186:189], v[210:213], v[38:41]
	v_mfma_f32_16x16x32_bf16 v[22:25], v[186:189], v[218:221], v[22:25]
	v_mfma_f32_16x16x32_bf16 v[6:9], v[186:189], v[226:229], v[6:9]
	v_mfma_f32_16x16x32_bf16 v[50:53], v[194:197], v[202:205], v[50:53]
	v_mfma_f32_16x16x32_bf16 v[34:37], v[194:197], v[210:213], v[34:37]
	v_mfma_f32_16x16x32_bf16 v[18:21], v[194:197], v[218:221], v[18:21]
	v_mfma_f32_16x16x32_bf16 v[2:5], v[194:197], v[226:229], v[2:5]
	s_barrier
; #define PG8_STAGE(bufoff, gbase, voff) do { _Pragma("unroll") for (int _i = 0; _i < 2; ++_i) \
;         __builtin_amdgcn_global_load_lds((const unsigned*)((const char*)(gbase) + (voff)[_i]), (LAS unsigned*)(lds + (bufoff) + ldsw + _i * 8192), 16, 0, 0); } while (0)
; #define PG8_LDA(dst, b, h) do { _Pragma("unroll") for (int m = 0; m < 4; ++m) _Pragma("unroll") for (int k = 0; k < 2; ++k) dst[m][k] = *(const LAS bf16x8*)(lds + PG8_SA(b, h) + aoff + m * 2048 + k * 1024); } while (0)
; #define PG8_LDB(dst, b, h) do { _Pragma("unroll") for (int n = 0; n < 2; ++n) _Pragma("unroll") for (int k = 0; k < 2; ++k) dst[n][k] = *(const LAS bf16x8*)(lds + PG8_SB(b, h) + boff + n * 2048 + k * 1024); } while (0)
; #define PG8_MMA(ai, bj, At, Bt) do { __builtin_amdgcn_s_setprio(1); _Pragma("unroll") for (int m = 0; m < 4; ++m) _Pragma("unroll") for (int n = 0; n < 2; ++n) _Pragma("unroll") for (int k = 0; k < 2; ++k) \
;         acc[ai][bj][m][n] = __builtin_amdgcn_mfma_f32_16x16x32_bf16(Bt[n][k], At[m][k], acc[ai][bj][m][n], 0, 0, 0); __builtin_amdgcn_s_setprio(0); } while (0)
; #define PG8_WAIT_V(n) asm volatile("s_waitcnt vmcnt(" #n ")" ::: "memory")
; #define PG8_WAIT_L(n) asm volatile("s_waitcnt lgkmcnt(" #n ")" ::: "memory")
; #define PG8_BAR __builtin_amdgcn_s_barrier()
; #define PG8_SCHED __builtin_amdgcn_sched_barrier(0)
; template <class Epi>
; __device__ __forceinline__ void gemm_phase(LAS unsigned char* lds, const Gemm g, const StaticOrder& S, const Epi& E) {
;     ...
;             PG8_LDB(B0, 1, 0); PG8_LDB(B1, 1, 1); PG8_SCHED; PG8_LDA(At, 1, 0); PG8_STAGE(PG8_SA(0, 1), a2 + hstep, voffA);
;             PG8_WAIT_V(8); PG8_WAIT_L(0); PG8_BAR; PG8_MMA(0, 0, At, B0); PG8_MMA(0, 1, At, B1); PG8_BAR; PG8_SCHED;
;             PG8_LDA(At, 1, 1); PG8_STAGE(PG8_SB(1, 0), b3, voffB); PG8_STAGE(PG8_SB(1, 1), b3 + hstep, voffB); PG8_STAGE(PG8_SA(1, 0), a3, voffA);
;             PG8_WAIT_V(8); PG8_WAIT_L(0); PG8_BAR; PG8_MMA(1, 0, At, B0); PG8_MMA(1, 1, At, B1); PG8_BAR; PG8_SCHED;
;         }
;         if (wr == 0) PG8_BAR;
	s_setprio 0
	s_add_i32 s76, 0, 0x18000
	v_add_u32_e32 v138, s76, v172
	s_add_i32 s77, 0, 0x1c000
	ds_read_b128 v[154:157], v138
	ds_read_b128 v[158:161], v138 offset:1024
	ds_read_b128 v[162:165], v138 offset:2048
	ds_read_b128 v[166:169], v138 offset:3072
	v_add_u32_e32 v138, s77, v172
	ds_read_b128 v[182:185], v138
	ds_read_b128 v[186:189], v138 offset:1024
	ds_read_b128 v[190:193], v138 offset:2048
	ds_read_b128 v[194:197], v138 offset:3072
	s_add_u32 s48, s48, 0x40000
	s_addc_u32 s49, s49, 0
	s_mov_b32 m0, s52
	ds_read_b128 v[198:201], v176 offset:32768
	ds_read_b128 v[202:205], v176 offset:33792
	ds_read_b128 v[206:209], v176 offset:34816
	ds_read_b128 v[210:213], v176 offset:35840
	ds_read_b128 v[214:217], v176 offset:36864
	ds_read_b128 v[218:221], v176 offset:37888
	ds_read_b128 v[222:225], v176 offset:38912
	ds_read_b128 v[226:229], v176 offset:39936
	global_load_lds_dwordx4 v130, s[48:49]
	s_mov_b32 m0, s53
	s_nop 0
	global_load_lds_dwordx4 v134, s[48:49]
	s_waitcnt vmcnt(8)
	s_waitcnt lgkmcnt(0)
	s_setprio 1
	s_barrier
	v_mfma_f32_16x16x32_bf16 v[126:129], v[154:157], v[198:201], v[126:129]
	v_mfma_f32_16x16x32_bf16 v[110:113], v[154:157], v[206:209], v[110:113]
	v_mfma_f32_16x16x32_bf16 v[94:97], v[154:157], v[214:217], v[94:97]
	v_mfma_f32_16x16x32_bf16 v[78:81], v[154:157], v[222:225], v[78:81]
	v_mfma_f32_16x16x32_bf16 v[122:125], v[162:165], v[198:201], v[122:125]
	v_mfma_f32_16x16x32_bf16 v[106:109], v[162:165], v[206:209], v[106:109]
	v_mfma_f32_16x16x32_bf16 v[90:93], v[162:165], v[214:217], v[90:93]
	v_mfma_f32_16x16x32_bf16 v[74:77], v[162:165], v[222:225], v[74:77]
	v_mfma_f32_16x16x32_bf16 v[126:129], v[158:161], v[202:205], v[126:129]
	v_mfma_f32_16x16x32_bf16 v[110:113], v[158:161], v[210:213], v[110:113]
	v_mfma_f32_16x16x32_bf16 v[94:97], v[158:161], v[218:221], v[94:97]
	v_mfma_f32_16x16x32_bf16 v[78:81], v[158:161], v[226:229], v[78:81]
	v_mfma_f32_16x16x32_bf16 v[122:125], v[166:169], v[202:205], v[122:125]
	v_mfma_f32_16x16x32_bf16 v[106:109], v[166:169], v[210:213], v[106:109]
	v_mfma_f32_16x16x32_bf16 v[90:93], v[166:169], v[218:221], v[90:93]
	v_mfma_f32_16x16x32_bf16 v[74:77], v[166:169], v[226:229], v[74:77]
	v_mfma_f32_16x16x32_bf16 v[118:121], v[182:185], v[198:201], v[118:121]
	v_mfma_f32_16x16x32_bf16 v[102:105], v[182:185], v[206:209], v[102:105]
	v_mfma_f32_16x16x32_bf16 v[86:89], v[182:185], v[214:217], v[86:89]
	v_mfma_f32_16x16x32_bf16 v[70:73], v[182:185], v[222:225], v[70:73]
	v_mfma_f32_16x16x32_bf16 v[114:117], v[190:193], v[198:201], v[114:117]
	v_mfma_f32_16x16x32_bf16 v[98:101], v[190:193], v[206:209], v[98:101]
	v_mfma_f32_16x16x32_bf16 v[82:85], v[190:193], v[214:217], v[82:85]
	v_mfma_f32_16x16x32_bf16 v[66:69], v[190:193], v[222:225], v[66:69]
	v_mfma_f32_16x16x32_bf16 v[118:121], v[186:189], v[202:205], v[118:121]
	v_mfma_f32_16x16x32_bf16 v[102:105], v[186:189], v[210:213], v[102:105]
	v_mfma_f32_16x16x32_bf16 v[86:89], v[186:189], v[218:221], v[86:89]
	v_mfma_f32_16x16x32_bf16 v[70:73], v[186:189], v[226:229], v[70:73]
	v_mfma_f32_16x16x32_bf16 v[114:117], v[194:197], v[202:205], v[114:117]
	v_mfma_f32_16x16x32_bf16 v[98:101], v[194:197], v[210:213], v[98:101]
	v_mfma_f32_16x16x32_bf16 v[82:85], v[194:197], v[218:221], v[82:85]
	v_mfma_f32_16x16x32_bf16 v[66:69], v[194:197], v[226:229], v[66:69]
	s_barrier
	s_setprio 0
	s_add_i32 s48, s76, s6
	s_mov_b32 m0, s48
	ds_read_b128 v[198:201], v176 offset:49152
	ds_read_b128 v[202:205], v176 offset:50176
	ds_read_b128 v[206:209], v176 offset:51200
	ds_read_b128 v[210:213], v176 offset:52224
	ds_read_b128 v[214:217], v176 offset:53248
	ds_read_b128 v[218:221], v176 offset:54272
	ds_read_b128 v[222:225], v176 offset:55296
	ds_read_b128 v[226:229], v176 offset:56320
	global_load_lds_dwordx4 v132, s[98:99]
	s_add_i32 m0, s48, 0x2000
	s_add_u32 s46, s46, 0x40080
	s_addc_u32 s47, s47, 0
	s_add_i32 s48, s77, s6
	global_load_lds_dwordx4 v136, s[98:99]
	s_mov_b32 m0, s48
	s_nop 0
	global_load_lds_dwordx4 v132, s[46:47]
	s_add_i32 m0, s48, 0x2000
	s_nop 0
	global_load_lds_dwordx4 v136, s[46:47]
	s_mov_b32 m0, s56
	s_nop 0
	global_load_lds_dwordx4 v130, s[100:101]
	s_mov_b32 m0, s57
	s_nop 0
	global_load_lds_dwordx4 v134, s[100:101]
	s_waitcnt vmcnt(8)
	s_waitcnt lgkmcnt(0)
	s_setprio 1
	s_barrier
	v_mfma_f32_16x16x32_bf16 v[62:65], v[154:157], v[198:201], v[62:65]
	v_mfma_f32_16x16x32_bf16 v[46:49], v[154:157], v[206:209], v[46:49]
	v_mfma_f32_16x16x32_bf16 v[30:33], v[154:157], v[214:217], v[30:33]
	v_mfma_f32_16x16x32_bf16 v[14:17], v[154:157], v[222:225], v[14:17]
	v_mfma_f32_16x16x32_bf16 v[58:61], v[162:165], v[198:201], v[58:61]
	v_mfma_f32_16x16x32_bf16 v[42:45], v[162:165], v[206:209], v[42:45]
	v_mfma_f32_16x16x32_bf16 v[26:29], v[162:165], v[214:217], v[26:29]
	v_mfma_f32_16x16x32_bf16 v[10:13], v[162:165], v[222:225], v[10:13]
	v_mfma_f32_16x16x32_bf16 v[62:65], v[158:161], v[202:205], v[62:65]
	v_mfma_f32_16x16x32_bf16 v[46:49], v[158:161], v[210:213], v[46:49]
	v_mfma_f32_16x16x32_bf16 v[30:33], v[158:161], v[218:221], v[30:33]
	v_mfma_f32_16x16x32_bf16 v[14:17], v[158:161], v[226:229], v[14:17]
	v_mfma_f32_16x16x32_bf16 v[58:61], v[166:169], v[202:205], v[58:61]
	v_mfma_f32_16x16x32_bf16 v[42:45], v[166:169], v[210:213], v[42:45]
	v_mfma_f32_16x16x32_bf16 v[26:29], v[166:169], v[218:221], v[26:29]
	v_mfma_f32_16x16x32_bf16 v[10:13], v[166:169], v[226:229], v[10:13]
	v_mfma_f32_16x16x32_bf16 v[54:57], v[182:185], v[198:201], v[54:57]
	v_mfma_f32_16x16x32_bf16 v[38:41], v[182:185], v[206:209], v[38:41]
	v_mfma_f32_16x16x32_bf16 v[22:25], v[182:185], v[214:217], v[22:25]
	v_mfma_f32_16x16x32_bf16 v[6:9], v[182:185], v[222:225], v[6:9]
	v_mfma_f32_16x16x32_bf16 v[50:53], v[190:193], v[198:201], v[50:53]
	v_mfma_f32_16x16x32_bf16 v[34:37], v[190:193], v[206:209], v[34:37]
	v_mfma_f32_16x16x32_bf16 v[18:21], v[190:193], v[214:217], v[18:21]
	v_mfma_f32_16x16x32_bf16 v[2:5], v[190:193], v[222:225], v[2:5]
	v_mfma_f32_16x16x32_bf16 v[54:57], v[186:189], v[202:205], v[54:57]
	v_mfma_f32_16x16x32_bf16 v[38:41], v[186:189], v[210:213], v[38:41]
	v_mfma_f32_16x16x32_bf16 v[22:25], v[186:189], v[218:221], v[22:25]
	v_mfma_f32_16x16x32_bf16 v[6:9], v[186:189], v[226:229], v[6:9]
	v_mfma_f32_16x16x32_bf16 v[50:53], v[194:197], v[202:205], v[50:53]
	v_mfma_f32_16x16x32_bf16 v[34:37], v[194:197], v[210:213], v[34:37]
	v_mfma_f32_16x16x32_bf16 v[18:21], v[194:197], v[218:221], v[18:21]
	v_mfma_f32_16x16x32_bf16 v[2:5], v[194:197], v[226:229], v[2:5]
	s_barrier
	s_setprio 0
	s_add_i32 s69, s69, 2
	s_add_u32 s44, s44, 0x100
	s_addc_u32 s45, s45, 0
	s_add_u32 s67, s67, 0x100
	s_addc_u32 s68, s68, 0
	s_cmp_gt_u32 s69, 13
	s_cbranch_scc0 .LBB0_619
	s_and_b64 vcc, exec, s[18:19]
	s_cbranch_vccz .LBB0_622
	s_barrier

; #define PG8_STAGE(bufoff, gbase, voff) do { _Pragma("unroll") for (int _i = 0; _i < 2; ++_i) \
;         __builtin_amdgcn_global_load_lds((const unsigned*)((const char*)(gbase) + (voff)[_i]), (LAS unsigned*)(lds + (bufoff) + ldsw + _i * 8192), 16, 0, 0); } while (0)
; #define PG8_LDA(dst, b, h) do { _Pragma("unroll") for (int m = 0; m < 4; ++m) _Pragma("unroll") for (int k = 0; k < 2; ++k) dst[m][k] = *(const LAS bf16x8*)(lds + PG8_SA(b, h) + aoff + m * 2048 + k * 1024); } while (0)
; #define PG8_LDB(dst, b, h) do { _Pragma("unroll") for (int n = 0; n < 2; ++n) _Pragma("unroll") for (int k = 0; k < 2; ++k) dst[n][k] = *(const LAS bf16x8*)(lds + PG8_SB(b, h) + boff + n * 2048 + k * 1024); } while (0)
; #define PG8_MMA(ai, bj, At, Bt) do { __builtin_amdgcn_s_setprio(1); _Pragma("unroll") for (int m = 0; m < 4; ++m) _Pragma("unroll") for (int n = 0; n < 2; ++n) _Pragma("unroll") for (int k = 0; k < 2; ++k) \
;         acc[ai][bj][m][n] = __builtin_amdgcn_mfma_f32_16x16x32_bf16(Bt[n][k], At[m][k], acc[ai][bj][m][n], 0, 0, 0); __builtin_amdgcn_s_setprio(0); } while (0)
; #define PG8_WAIT_V(n) asm volatile("s_waitcnt vmcnt(" #n ")" ::: "memory")
; #define PG8_WAIT_L(n) asm volatile("s_waitcnt lgkmcnt(" #n ")" ::: "memory")
; #define PG8_BAR __builtin_amdgcn_s_barrier()
; template <class Epi>
; __device__ __forceinline__ void gemm_phase(LAS unsigned char* lds, const Gemm g, const StaticOrder& S, const Epi& E) {
;     ...
;             const bool last = (t == nt - 2);
;             const char* a1 = cA + (size_t)(t + 1) * kstep;
;             const char* a2 = last ? nA : cA + (size_t)(t + 2) * kstep; const char* b2 = last ? nB : cB + (size_t)(t + 2) * kstep;
;             const char* a3 = a2 + kstep; const char* b3 = b2 + kstep;
;             if constexpr (Epi::MIDK > 0) { if (t == Epi::MIDK) E.mid(acc, cur, wr, wc, fr, fq); }
;             PG8_LDB(B0, 0, 0); PG8_LDB(B1, 0, 1); PG8_SCHED; PG8_LDA(At, 0, 0); PG8_STAGE(PG8_SA(1, 1), a1 + hstep, voffA);
;             PG8_WAIT_V(8); PG8_WAIT_L(0); PG8_BAR; PG8_MMA(0, 0, At, B0); PG8_MMA(0, 1, At, B1); PG8_BAR; PG8_SCHED;
;             PG8_LDA(At, 0, 1); PG8_STAGE(PG8_SB(0, 0), b2, voffB); PG8_STAGE(PG8_SB(0, 1), b2 + hstep, voffB); PG8_STAGE(PG8_SA(0, 0), a2, voffA);
;             PG8_WAIT_V(8); PG8_WAIT_L(0); PG8_BAR; PG8_MMA(1, 0, At, B0); PG8_MMA(1, 1, At, B1); PG8_BAR; PG8_SCHED;
.LBB0_700:
	v_add_u32_e32 v3, s68, v198
	ds_read_b128 v[134:137], v3
	ds_read_b128 v[138:141], v3 offset:1024
	ds_read_b128 v[142:145], v3 offset:2048
	ds_read_b128 v[146:149], v3 offset:3072
	v_add_u32_e32 v3, s69, v198
	s_add_u32 s52, s48, s50
	ds_read_b128 v[158:161], v3
	ds_read_b128 v[162:165], v3 offset:1024
	ds_read_b128 v[166:169], v3 offset:2048
	ds_read_b128 v[188:191], v3 offset:3072
	s_addc_u32 s53, s49, s51
	s_add_u32 s52, s52, 0x100
	s_addc_u32 s53, s53, 0
	s_add_u32 s81, s78, s50
	s_addc_u32 s82, s79, s51
	s_cmpk_eq_i32 s50, 0x700
	s_cselect_b32 s55, s43, s53
	s_cselect_b32 s54, s76, s52
	s_cselect_b32 s53, s41, s82
	s_cselect_b32 s52, s77, s81
	v_lshl_add_u64 v[4:5], v[154:155], 0, s[50:51]
	s_add_i32 m0, s59, 0xc000
	ds_read_b128 v[192:195], v200
	ds_read_b128 v[202:205], v200 offset:1024
	ds_read_b128 v[206:209], v200 offset:2048
	ds_read_b128 v[210:213], v200 offset:3072
	ds_read_b128 v[214:217], v200 offset:4096
	ds_read_b128 v[218:221], v200 offset:5120
	ds_read_b128 v[222:225], v200 offset:6144
	ds_read_b128 v[226:229], v200 offset:7168
	global_load_lds_dwordx4 v[4:5], off
	v_lshl_add_u64 v[4:5], v[156:157], 0, s[50:51]
	s_add_i32 m0, s59, 0xe000
	s_nop 0
	global_load_lds_dwordx4 v[4:5], off
	s_waitcnt vmcnt(8)
	s_waitcnt lgkmcnt(0)
	s_setprio 1
	s_barrier
	v_mfma_f32_16x16x32_bf16 v[130:133], v[134:137], v[192:195], v[130:133]
	v_mfma_f32_16x16x32_bf16 v[114:117], v[134:137], v[206:209], v[114:117]
	v_mfma_f32_16x16x32_bf16 v[98:101], v[134:137], v[214:217], v[98:101]
	v_mfma_f32_16x16x32_bf16 v[82:85], v[134:137], v[222:225], v[82:85]
	v_mfma_f32_16x16x32_bf16 v[126:129], v[142:145], v[192:195], v[126:129]
	v_mfma_f32_16x16x32_bf16 v[110:113], v[142:145], v[206:209], v[110:113]
	v_mfma_f32_16x16x32_bf16 v[94:97], v[142:145], v[214:217], v[94:97]
	v_mfma_f32_16x16x32_bf16 v[78:81], v[142:145], v[222:225], v[78:81]
	v_mfma_f32_16x16x32_bf16 v[130:133], v[138:141], v[202:205], v[130:133]
	v_mfma_f32_16x16x32_bf16 v[114:117], v[138:141], v[210:213], v[114:117]
	v_mfma_f32_16x16x32_bf16 v[98:101], v[138:141], v[218:221], v[98:101]
	v_mfma_f32_16x16x32_bf16 v[82:85], v[138:141], v[226:229], v[82:85]
	v_mfma_f32_16x16x32_bf16 v[126:129], v[146:149], v[202:205], v[126:129]
	v_mfma_f32_16x16x32_bf16 v[110:113], v[146:149], v[210:213], v[110:113]
	v_mfma_f32_16x16x32_bf16 v[94:97], v[146:149], v[218:221], v[94:97]
	v_mfma_f32_16x16x32_bf16 v[78:81], v[146:149], v[226:229], v[78:81]
	v_mfma_f32_16x16x32_bf16 v[122:125], v[158:161], v[192:195], v[122:125]
	v_mfma_f32_16x16x32_bf16 v[106:109], v[158:161], v[206:209], v[106:109]
	v_mfma_f32_16x16x32_bf16 v[90:93], v[158:161], v[214:217], v[90:93]
	v_mfma_f32_16x16x32_bf16 v[74:77], v[158:161], v[222:225], v[74:77]
	v_mfma_f32_16x16x32_bf16 v[118:121], v[166:169], v[192:195], v[118:121]
	v_mfma_f32_16x16x32_bf16 v[102:105], v[166:169], v[206:209], v[102:105]
	v_mfma_f32_16x16x32_bf16 v[86:89], v[166:169], v[214:217], v[86:89]
	v_mfma_f32_16x16x32_bf16 v[70:73], v[166:169], v[222:225], v[70:73]
	v_mfma_f32_16x16x32_bf16 v[122:125], v[162:165], v[202:205], v[122:125]
	v_mfma_f32_16x16x32_bf16 v[106:109], v[162:165], v[210:213], v[106:109]
	v_mfma_f32_16x16x32_bf16 v[90:93], v[162:165], v[218:221], v[90:93]
	v_mfma_f32_16x16x32_bf16 v[74:77], v[162:165], v[226:229], v[74:77]
	v_mfma_f32_16x16x32_bf16 v[118:121], v[188:191], v[202:205], v[118:121]
	v_mfma_f32_16x16x32_bf16 v[102:105], v[188:191], v[210:213], v[102:105]
	v_mfma_f32_16x16x32_bf16 v[86:89], v[188:191], v[218:221], v[86:89]
	v_mfma_f32_16x16x32_bf16 v[70:73], v[188:191], v[226:229], v[70:73]
	s_barrier
	s_setprio 0
	s_add_u32 s98, s52, s12
	s_addc_u32 s99, s53, s13
	s_add_u32 s100, s54, s12
	s_addc_u32 s101, s55, s13
	s_add_i32 s81, s68, s56
	s_mov_b32 m0, s81
	ds_read_b128 v[192:195], v200 offset:16384
	ds_read_b128 v[202:205], v200 offset:17408
	ds_read_b128 v[206:209], v200 offset:18432
	ds_read_b128 v[210:213], v200 offset:19456
	ds_read_b128 v[214:217], v200 offset:20480
	ds_read_b128 v[218:221], v200 offset:21504
	ds_read_b128 v[222:225], v200 offset:22528
	ds_read_b128 v[226:229], v200 offset:23552
	global_load_lds_dwordx4 v176, s[52:53]
	s_add_i32 m0, s81, 0x2000
	s_add_u32 s82, s52, 0x40000
	s_addc_u32 s83, s53, 0
	s_add_i32 s81, s69, s56
	global_load_lds_dwordx4 v172, s[52:53]
	s_mov_b32 m0, s81
	s_nop 0
	global_load_lds_dwordx4 v176, s[82:83]
	v_lshl_add_u64 v[4:5], s[82:83], 0, v[172:173]
	s_add_i32 m0, s81, 0x2000
	v_lshl_add_u64 v[234:235], s[54:55], 0, v[174:175]
	global_load_lds_dwordx4 v172, s[82:83]
	s_mov_b32 m0, s59
	s_nop 0
	global_load_lds_dwordx4 v178, s[54:55]
	s_mov_b32 m0, s60
	s_nop 0
	global_load_lds_dwordx4 v174, s[54:55]
	s_waitcnt vmcnt(8)
	s_waitcnt lgkmcnt(0)
	s_setprio 1
	s_barrier
; #define PG8_STAGE(bufoff, gbase, voff) do { _Pragma("unroll") for (int _i = 0; _i < 2; ++_i) \
;         __builtin_amdgcn_global_load_lds((const unsigned*)((const char*)(gbase) + (voff)[_i]), (LAS unsigned*)(lds + (bufoff) + ldsw + _i * 8192), 16, 0, 0); } while (0)
; #define PG8_LDA(dst, b, h) do { _Pragma("unroll") for (int m = 0; m < 4; ++m) _Pragma("unroll") for (int k = 0; k < 2; ++k) dst[m][k] = *(const LAS bf16x8*)(lds + PG8_SA(b, h) + aoff + m * 2048 + k * 1024); } while (0)
; #define PG8_LDB(dst, b, h) do { _Pragma("unroll") for (int n = 0; n < 2; ++n) _Pragma("unroll") for (int k = 0; k < 2; ++k) dst[n][k] = *(const LAS bf16x8*)(lds + PG8_SB(b, h) + boff + n * 2048 + k * 1024); } while (0)
; #define PG8_MMA(ai, bj, At, Bt) do { __builtin_amdgcn_s_setprio(1); _Pragma("unroll") for (int m = 0; m < 4; ++m) _Pragma("unroll") for (int n = 0; n < 2; ++n) _Pragma("unroll") for (int k = 0; k < 2; ++k) \
;         acc[ai][bj][m][n] = __builtin_amdgcn_mfma_f32_16x16x32_bf16(Bt[n][k], At[m][k], acc[ai][bj][m][n], 0, 0, 0); __builtin_amdgcn_s_setprio(0); } while (0)
; #define PG8_WAIT_V(n) asm volatile("s_waitcnt vmcnt(" #n ")" ::: "memory")
; #define PG8_WAIT_L(n) asm volatile("s_waitcnt lgkmcnt(" #n ")" ::: "memory")
; #define PG8_BAR __builtin_amdgcn_s_barrier()
; #define PG8_SCHED __builtin_amdgcn_sched_barrier(0)
; template <class Epi>
; __device__ __forceinline__ void gemm_phase(LAS unsigned char* lds, const Gemm g, const StaticOrder& S, const Epi& E) {
;     ...
;             PG8_WAIT_V(8); PG8_WAIT_L(0); PG8_BAR; PG8_MMA(1, 0, At, B0); PG8_MMA(1, 1, At, B1); PG8_BAR; PG8_SCHED;
;             PG8_LDB(B0, 1, 0); PG8_LDB(B1, 1, 1); PG8_SCHED; PG8_LDA(At, 1, 0); PG8_STAGE(PG8_SA(0, 1), a2 + hstep, voffA);
;             PG8_WAIT_V(8); PG8_WAIT_L(0); PG8_BAR; PG8_MMA(0, 0, At, B0); PG8_MMA(0, 1, At, B1); PG8_BAR; PG8_SCHED;
	v_mfma_f32_16x16x32_bf16 v[66:69], v[134:137], v[192:195], v[66:69]
	v_mfma_f32_16x16x32_bf16 v[50:53], v[134:137], v[206:209], v[50:53]
	v_mfma_f32_16x16x32_bf16 v[34:37], v[134:137], v[214:217], v[34:37]
	v_mfma_f32_16x16x32_bf16 v[18:21], v[134:137], v[222:225], v[18:21]
	v_mfma_f32_16x16x32_bf16 v[62:65], v[142:145], v[192:195], v[62:65]
	v_mfma_f32_16x16x32_bf16 v[46:49], v[142:145], v[206:209], v[46:49]
	v_mfma_f32_16x16x32_bf16 v[30:33], v[142:145], v[214:217], v[30:33]
	v_mfma_f32_16x16x32_bf16 v[14:17], v[142:145], v[222:225], v[14:17]
	v_mfma_f32_16x16x32_bf16 v[66:69], v[138:141], v[202:205], v[66:69]
	v_mfma_f32_16x16x32_bf16 v[50:53], v[138:141], v[210:213], v[50:53]
	v_mfma_f32_16x16x32_bf16 v[34:37], v[138:141], v[218:221], v[34:37]
	v_mfma_f32_16x16x32_bf16 v[18:21], v[138:141], v[226:229], v[18:21]
	v_mfma_f32_16x16x32_bf16 v[62:65], v[146:149], v[202:205], v[62:65]
	v_mfma_f32_16x16x32_bf16 v[46:49], v[146:149], v[210:213], v[46:49]
	v_mfma_f32_16x16x32_bf16 v[30:33], v[146:149], v[218:221], v[30:33]
	v_mfma_f32_16x16x32_bf16 v[14:17], v[146:149], v[226:229], v[14:17]
	v_mfma_f32_16x16x32_bf16 v[58:61], v[158:161], v[192:195], v[58:61]
	v_mfma_f32_16x16x32_bf16 v[42:45], v[158:161], v[206:209], v[42:45]
	v_mfma_f32_16x16x32_bf16 v[26:29], v[158:161], v[214:217], v[26:29]
	v_mfma_f32_16x16x32_bf16 v[10:13], v[158:161], v[222:225], v[10:13]
	v_mfma_f32_16x16x32_bf16 v[54:57], v[166:169], v[192:195], v[54:57]
	v_mfma_f32_16x16x32_bf16 v[38:41], v[166:169], v[206:209], v[38:41]
	v_mfma_f32_16x16x32_bf16 v[22:25], v[166:169], v[214:217], v[22:25]
	v_mfma_f32_16x16x32_bf16 v[4:7], v[166:169], v[222:225], v[6:9]
	v_mfma_f32_16x16x32_bf16 v[58:61], v[162:165], v[202:205], v[58:61]
	v_mfma_f32_16x16x32_bf16 v[42:45], v[162:165], v[210:213], v[42:45]
	v_mfma_f32_16x16x32_bf16 v[26:29], v[162:165], v[218:221], v[26:29]
	v_mfma_f32_16x16x32_bf16 v[10:13], v[162:165], v[226:229], v[10:13]
	v_mfma_f32_16x16x32_bf16 v[54:57], v[188:191], v[202:205], v[54:57]
	v_mfma_f32_16x16x32_bf16 v[38:41], v[188:191], v[210:213], v[38:41]
	v_mfma_f32_16x16x32_bf16 v[22:25], v[188:191], v[218:221], v[22:25]
	v_mfma_f32_16x16x32_bf16 v[4:7], v[188:191], v[226:229], v[4:7]
	s_barrier
	s_setprio 0
	s_add_i32 s81, 0, 0x18000
	v_add_u32_e32 v3, s81, v198
	s_add_i32 s82, 0, 0x1c000
	ds_read_b128 v[134:137], v3
	ds_read_b128 v[138:141], v3 offset:1024
	ds_read_b128 v[142:145], v3 offset:2048
	ds_read_b128 v[146:149], v3 offset:3072
	v_add_u32_e32 v3, s82, v198
	ds_read_b128 v[158:161], v3
	ds_read_b128 v[162:165], v3 offset:1024
	ds_read_b128 v[166:169], v3 offset:2048
	ds_read_b128 v[188:191], v3 offset:3072
	s_add_u32 s54, s54, 0x40000
	s_addc_u32 s55, s55, 0
	s_mov_b32 m0, s61
	ds_read_b128 v[192:195], v200 offset:32768
	ds_read_b128 v[202:205], v200 offset:33792
	ds_read_b128 v[206:209], v200 offset:34816
	ds_read_b128 v[210:213], v200 offset:35840
	ds_read_b128 v[214:217], v200 offset:36864
	ds_read_b128 v[218:221], v200 offset:37888
	ds_read_b128 v[222:225], v200 offset:38912
	ds_read_b128 v[226:229], v200 offset:39936
	global_load_lds_dwordx4 v178, s[54:55]
	s_mov_b32 m0, s62
	s_nop 0
	global_load_lds_dwordx4 v174, s[54:55]
	s_waitcnt vmcnt(8)
	s_waitcnt lgkmcnt(0)
	s_setprio 1
	s_barrier
	v_mfma_f32_16x16x32_bf16 v[130:133], v[134:137], v[192:195], v[130:133]
	v_mfma_f32_16x16x32_bf16 v[114:117], v[134:137], v[206:209], v[114:117]
	v_mfma_f32_16x16x32_bf16 v[98:101], v[134:137], v[214:217], v[98:101]
	v_mfma_f32_16x16x32_bf16 v[82:85], v[134:137], v[222:225], v[82:85]
	v_mfma_f32_16x16x32_bf16 v[126:129], v[142:145], v[192:195], v[126:129]
	v_mfma_f32_16x16x32_bf16 v[110:113], v[142:145], v[206:209], v[110:113]
	v_mfma_f32_16x16x32_bf16 v[94:97], v[142:145], v[214:217], v[94:97]
	v_mfma_f32_16x16x32_bf16 v[78:81], v[142:145], v[222:225], v[78:81]
	v_mfma_f32_16x16x32_bf16 v[130:133], v[138:141], v[202:205], v[130:133]
	v_mfma_f32_16x16x32_bf16 v[114:117], v[138:141], v[210:213], v[114:117]
	v_mfma_f32_16x16x32_bf16 v[98:101], v[138:141], v[218:221], v[98:101]
	v_mfma_f32_16x16x32_bf16 v[82:85], v[138:141], v[226:229], v[82:85]
	v_mfma_f32_16x16x32_bf16 v[126:129], v[146:149], v[202:205], v[126:129]
	v_mfma_f32_16x16x32_bf16 v[110:113], v[146:149], v[210:213], v[110:113]
	v_mfma_f32_16x16x32_bf16 v[94:97], v[146:149], v[218:221], v[94:97]
	v_mfma_f32_16x16x32_bf16 v[78:81], v[146:149], v[226:229], v[78:81]
	v_mfma_f32_16x16x32_bf16 v[122:125], v[158:161], v[192:195], v[122:125]
	v_mfma_f32_16x16x32_bf16 v[106:109], v[158:161], v[206:209], v[106:109]
	v_mfma_f32_16x16x32_bf16 v[90:93], v[158:161], v[214:217], v[90:93]
	v_mfma_f32_16x16x32_bf16 v[74:77], v[158:161], v[222:225], v[74:77]
	v_mfma_f32_16x16x32_bf16 v[118:121], v[166:169], v[192:195], v[118:121]
	v_mfma_f32_16x16x32_bf16 v[102:105], v[166:169], v[206:209], v[102:105]
	v_mfma_f32_16x16x32_bf16 v[86:89], v[166:169], v[214:217], v[86:89]
	v_mfma_f32_16x16x32_bf16 v[70:73], v[166:169], v[222:225], v[70:73]
	v_mfma_f32_16x16x32_bf16 v[122:125], v[162:165], v[202:205], v[122:125]
	v_mfma_f32_16x16x32_bf16 v[106:109], v[162:165], v[210:213], v[106:109]
	v_mfma_f32_16x16x32_bf16 v[90:93], v[162:165], v[218:221], v[90:93]
	v_mfma_f32_16x16x32_bf16 v[74:77], v[162:165], v[226:229], v[74:77]
	v_mfma_f32_16x16x32_bf16 v[118:121], v[188:191], v[202:205], v[118:121]
	v_mfma_f32_16x16x32_bf16 v[102:105], v[188:191], v[210:213], v[102:105]
	v_mfma_f32_16x16x32_bf16 v[86:89], v[188:191], v[218:221], v[86:89]
	v_mfma_f32_16x16x32_bf16 v[70:73], v[188:191], v[226:229], v[70:73]
	s_barrier
; #define PG8_STAGE(bufoff, gbase, voff) do { _Pragma("unroll") for (int _i = 0; _i < 2; ++_i) \
;         __builtin_amdgcn_global_load_lds((const unsigned*)((const char*)(gbase) + (voff)[_i]), (LAS unsigned*)(lds + (bufoff) + ldsw + _i * 8192), 16, 0, 0); } while (0)
; #define PG8_LDA(dst, b, h) do { _Pragma("unroll") for (int m = 0; m < 4; ++m) _Pragma("unroll") for (int k = 0; k < 2; ++k) dst[m][k] = *(const LAS bf16x8*)(lds + PG8_SA(b, h) + aoff + m * 2048 + k * 1024); } while (0)
; #define PG8_MMA(ai, bj, At, Bt) do { __builtin_amdgcn_s_setprio(1); _Pragma("unroll") for (int m = 0; m < 4; ++m) _Pragma("unroll") for (int n = 0; n < 2; ++n) _Pragma("unroll") for (int k = 0; k < 2; ++k) \
;         acc[ai][bj][m][n] = __builtin_amdgcn_mfma_f32_16x16x32_bf16(Bt[n][k], At[m][k], acc[ai][bj][m][n], 0, 0, 0); __builtin_amdgcn_s_setprio(0); } while (0)
; #define PG8_WAIT_V(n) asm volatile("s_waitcnt vmcnt(" #n ")" ::: "memory")
; #define PG8_WAIT_L(n) asm volatile("s_waitcnt lgkmcnt(" #n ")" ::: "memory")
; #define PG8_BAR __builtin_amdgcn_s_barrier()
; #define PG8_SCHED __builtin_amdgcn_sched_barrier(0)
; template <class Epi>
; __device__ __forceinline__ void gemm_phase(LAS unsigned char* lds, const Gemm g, const StaticOrder& S, const Epi& E) {
;     ...
;             PG8_LDA(At, 1, 1); PG8_STAGE(PG8_SB(1, 0), b3, voffB); PG8_STAGE(PG8_SB(1, 1), b3 + hstep, voffB); PG8_STAGE(PG8_SA(1, 0), a3, voffA);
;             PG8_WAIT_V(8); PG8_WAIT_L(0); PG8_BAR; PG8_MMA(1, 0, At, B0); PG8_MMA(1, 1, At, B1); PG8_BAR; PG8_SCHED;
;         }
	s_setprio 0
	s_add_i32 s54, s81, s56
	s_mov_b32 m0, s54
	ds_read_b128 v[192:195], v200 offset:49152
	ds_read_b128 v[202:205], v200 offset:50176
	ds_read_b128 v[206:209], v200 offset:51200
	ds_read_b128 v[210:213], v200 offset:52224
	ds_read_b128 v[214:217], v200 offset:53248
	ds_read_b128 v[218:221], v200 offset:54272
	ds_read_b128 v[222:225], v200 offset:55296
	ds_read_b128 v[226:229], v200 offset:56320
	global_load_lds_dwordx4 v176, s[98:99]
	s_add_i32 m0, s54, 0x2000
	s_add_u32 s52, s52, 0x40080
	s_addc_u32 s53, s53, 0
	s_add_i32 s54, s82, s56
	global_load_lds_dwordx4 v172, s[98:99]
	s_mov_b32 m0, s54
	s_nop 0
	global_load_lds_dwordx4 v176, s[52:53]
	s_add_i32 m0, s54, 0x2000
	s_nop 0
	global_load_lds_dwordx4 v172, s[52:53]
	s_mov_b32 m0, s64
	s_nop 0
	global_load_lds_dwordx4 v178, s[100:101]
	v_lshl_add_u64 v[8:9], v[234:235], 0, s[12:13]
	s_mov_b32 m0, s65
	s_nop 0
	global_load_lds_dwordx4 v174, s[100:101]
	s_waitcnt vmcnt(8)
	s_waitcnt lgkmcnt(0)
	s_setprio 1
	s_barrier
	v_mfma_f32_16x16x32_bf16 v[66:69], v[134:137], v[192:195], v[66:69]
	v_mfma_f32_16x16x32_bf16 v[50:53], v[134:137], v[206:209], v[50:53]
	v_mfma_f32_16x16x32_bf16 v[34:37], v[134:137], v[214:217], v[34:37]
	v_mfma_f32_16x16x32_bf16 v[18:21], v[134:137], v[222:225], v[18:21]
	v_mfma_f32_16x16x32_bf16 v[62:65], v[142:145], v[192:195], v[62:65]
	v_mfma_f32_16x16x32_bf16 v[46:49], v[142:145], v[206:209], v[46:49]
	v_mfma_f32_16x16x32_bf16 v[30:33], v[142:145], v[214:217], v[30:33]
	v_mfma_f32_16x16x32_bf16 v[14:17], v[142:145], v[222:225], v[14:17]
	v_mfma_f32_16x16x32_bf16 v[66:69], v[138:141], v[202:205], v[66:69]
	v_mfma_f32_16x16x32_bf16 v[50:53], v[138:141], v[210:213], v[50:53]
	v_mfma_f32_16x16x32_bf16 v[34:37], v[138:141], v[218:221], v[34:37]
	v_mfma_f32_16x16x32_bf16 v[18:21], v[138:141], v[226:229], v[18:21]
	v_mfma_f32_16x16x32_bf16 v[62:65], v[146:149], v[202:205], v[62:65]
	v_mfma_f32_16x16x32_bf16 v[46:49], v[146:149], v[210:213], v[46:49]
	v_mfma_f32_16x16x32_bf16 v[30:33], v[146:149], v[218:221], v[30:33]
	v_mfma_f32_16x16x32_bf16 v[14:17], v[146:149], v[226:229], v[14:17]
	v_mfma_f32_16x16x32_bf16 v[58:61], v[158:161], v[192:195], v[58:61]
	v_mfma_f32_16x16x32_bf16 v[42:45], v[158:161], v[206:209], v[42:45]
	v_mfma_f32_16x16x32_bf16 v[26:29], v[158:161], v[214:217], v[26:29]
	v_mfma_f32_16x16x32_bf16 v[8:11], v[158:161], v[222:225], v[10:13]
	v_mfma_f32_16x16x32_bf16 v[54:57], v[166:169], v[192:195], v[54:57]
	v_mfma_f32_16x16x32_bf16 v[38:41], v[166:169], v[206:209], v[38:41]
	v_mfma_f32_16x16x32_bf16 v[22:25], v[166:169], v[214:217], v[22:25]
	v_mfma_f32_16x16x32_bf16 v[4:7], v[166:169], v[222:225], v[4:7]
	v_mfma_f32_16x16x32_bf16 v[58:61], v[162:165], v[202:205], v[58:61]
	v_mfma_f32_16x16x32_bf16 v[42:45], v[162:165], v[210:213], v[42:45]
	v_mfma_f32_16x16x32_bf16 v[26:29], v[162:165], v[218:221], v[26:29]
	v_mfma_f32_16x16x32_bf16 v[10:13], v[162:165], v[226:229], v[8:11]
	v_mfma_f32_16x16x32_bf16 v[54:57], v[188:191], v[202:205], v[54:57]
	v_mfma_f32_16x16x32_bf16 v[38:41], v[188:191], v[210:213], v[38:41]
	v_mfma_f32_16x16x32_bf16 v[22:25], v[188:191], v[218:221], v[22:25]
	v_mfma_f32_16x16x32_bf16 v[6:9], v[188:191], v[226:229], v[4:7]
	s_barrier
	s_setprio 0
	s_add_i32 s80, s80, 2
	s_add_u32 s50, s50, 0x100
	s_addc_u32 s51, s51, 0
	s_cmp_gt_u32 s80, 13
	s_cbranch_scc1 .LBB0_703

; #define PG8_STAGE(bufoff, gbase, voff) do { _Pragma("unroll") for (int _i = 0; _i < 2; ++_i) \
;         __builtin_amdgcn_global_load_lds((const unsigned*)((const char*)(gbase) + (voff)[_i]), (LAS unsigned*)(lds + (bufoff) + ldsw + _i * 8192), 16, 0, 0); } while (0)
; #define PG8_LDA(dst, b, h) do { _Pragma("unroll") for (int m = 0; m < 4; ++m) _Pragma("unroll") for (int k = 0; k < 2; ++k) dst[m][k] = *(const LAS bf16x8*)(lds + PG8_SA(b, h) + aoff + m * 2048 + k * 1024); } while (0)
; #define PG8_LDB(dst, b, h) do { _Pragma("unroll") for (int n = 0; n < 2; ++n) _Pragma("unroll") for (int k = 0; k < 2; ++k) dst[n][k] = *(const LAS bf16x8*)(lds + PG8_SB(b, h) + boff + n * 2048 + k * 1024); } while (0)
; #define PG8_MMA(ai, bj, At, Bt) do { __builtin_amdgcn_s_setprio(1); _Pragma("unroll") for (int m = 0; m < 4; ++m) _Pragma("unroll") for (int n = 0; n < 2; ++n) _Pragma("unroll") for (int k = 0; k < 2; ++k) \
;         acc[ai][bj][m][n] = __builtin_amdgcn_mfma_f32_16x16x32_bf16(Bt[n][k], At[m][k], acc[ai][bj][m][n], 0, 0, 0); __builtin_amdgcn_s_setprio(0); } while (0)
; #define PG8_WAIT_V(n) asm volatile("s_waitcnt vmcnt(" #n ")" ::: "memory")
; #define PG8_WAIT_L(n) asm volatile("s_waitcnt lgkmcnt(" #n ")" ::: "memory")
; #define PG8_BAR __builtin_amdgcn_s_barrier()
; template <class Epi>
; __device__ __forceinline__ void gemm_phase(LAS unsigned char* lds, const Gemm g, const StaticOrder& S, const Epi& E) {
;     ...
;             const bool last = (t == nt - 2);
;             const char* a1 = cA + (size_t)(t + 1) * kstep;
;             const char* a2 = last ? nA : cA + (size_t)(t + 2) * kstep; const char* b2 = last ? nB : cB + (size_t)(t + 2) * kstep;
;             const char* a3 = a2 + kstep; const char* b3 = b2 + kstep;
;             if constexpr (Epi::MIDK > 0) { if (t == Epi::MIDK) E.mid(acc, cur, wr, wc, fr, fq); }
;             PG8_LDB(B0, 0, 0); PG8_LDB(B1, 0, 1); PG8_SCHED; PG8_LDA(At, 0, 0); PG8_STAGE(PG8_SA(1, 1), a1 + hstep, voffA);
;             PG8_WAIT_V(8); PG8_WAIT_L(0); PG8_BAR; PG8_MMA(0, 0, At, B0); PG8_MMA(0, 1, At, B1); PG8_BAR; PG8_SCHED;
;             PG8_LDA(At, 0, 1); PG8_STAGE(PG8_SB(0, 0), b2, voffB); PG8_STAGE(PG8_SB(0, 1), b2 + hstep, voffB); PG8_STAGE(PG8_SA(0, 0), a2, voffA);
;             PG8_WAIT_V(8); PG8_WAIT_L(0); PG8_BAR; PG8_MMA(1, 0, At, B0); PG8_MMA(1, 1, At, B1); PG8_BAR; PG8_SCHED;
.LBB0_785:
	ds_read_b128 v[130:133], v162
	ds_read_b128 v[134:137], v162 offset:1024
	ds_read_b128 v[154:157], v162 offset:2048
	ds_read_b128 v[166:169], v162 offset:3072
	ds_read_b128 v[172:175], v163
	ds_read_b128 v[176:179], v163 offset:1024
	ds_read_b128 v[180:183], v163 offset:2048
	ds_read_b128 v[184:187], v163 offset:3072
	s_add_u32 s40, s38, 0xfffc0080
	s_addc_u32 s41, s39, -1
	s_cmp_eq_u32 s63, 12
	s_cselect_b32 s43, s21, s41
	s_cselect_b32 s42, s27, s40
	s_cselect_b32 s41, s19, s62
	s_cselect_b32 s40, s60, s61
	s_add_i32 m0, s45, 0xc000
	ds_read_b128 v[188:191], v164
	ds_read_b128 v[192:195], v164 offset:1024
	ds_read_b128 v[196:199], v164 offset:2048
	ds_read_b128 v[200:203], v164 offset:3072
	ds_read_b128 v[204:207], v164 offset:4096
	ds_read_b128 v[208:211], v164 offset:5120
	ds_read_b128 v[212:215], v164 offset:6144
	ds_read_b128 v[216:219], v164 offset:7168
	global_load_lds_dwordx4 v146, s[38:39]
	s_add_i32 m0, s45, 0xe000
	s_nop 0
	global_load_lds_dwordx4 v148, s[38:39]
	s_waitcnt vmcnt(8)
	s_waitcnt lgkmcnt(0)
	s_setprio 1
	s_barrier
	v_mfma_f32_16x16x32_bf16 v[126:129], v[130:133], v[188:191], v[126:129]
	v_mfma_f32_16x16x32_bf16 v[110:113], v[130:133], v[196:199], v[110:113]
	v_mfma_f32_16x16x32_bf16 v[94:97], v[130:133], v[204:207], v[94:97]
	v_mfma_f32_16x16x32_bf16 v[78:81], v[130:133], v[212:215], v[78:81]
	v_mfma_f32_16x16x32_bf16 v[122:125], v[154:157], v[188:191], v[122:125]
	v_mfma_f32_16x16x32_bf16 v[106:109], v[154:157], v[196:199], v[106:109]
	v_mfma_f32_16x16x32_bf16 v[90:93], v[154:157], v[204:207], v[90:93]
	v_mfma_f32_16x16x32_bf16 v[74:77], v[154:157], v[212:215], v[74:77]
	v_mfma_f32_16x16x32_bf16 v[126:129], v[134:137], v[192:195], v[126:129]
	v_mfma_f32_16x16x32_bf16 v[110:113], v[134:137], v[200:203], v[110:113]
	v_mfma_f32_16x16x32_bf16 v[94:97], v[134:137], v[208:211], v[94:97]
	v_mfma_f32_16x16x32_bf16 v[78:81], v[134:137], v[216:219], v[78:81]
	v_mfma_f32_16x16x32_bf16 v[122:125], v[166:169], v[192:195], v[122:125]
	v_mfma_f32_16x16x32_bf16 v[106:109], v[166:169], v[200:203], v[106:109]
	v_mfma_f32_16x16x32_bf16 v[90:93], v[166:169], v[208:211], v[90:93]
	v_mfma_f32_16x16x32_bf16 v[74:77], v[166:169], v[216:219], v[74:77]
	v_mfma_f32_16x16x32_bf16 v[118:121], v[172:175], v[188:191], v[118:121]
	v_mfma_f32_16x16x32_bf16 v[102:105], v[172:175], v[196:199], v[102:105]
	v_mfma_f32_16x16x32_bf16 v[86:89], v[172:175], v[204:207], v[86:89]
	v_mfma_f32_16x16x32_bf16 v[70:73], v[172:175], v[212:215], v[70:73]
	v_mfma_f32_16x16x32_bf16 v[114:117], v[180:183], v[188:191], v[114:117]
	v_mfma_f32_16x16x32_bf16 v[98:101], v[180:183], v[196:199], v[98:101]
	v_mfma_f32_16x16x32_bf16 v[82:85], v[180:183], v[204:207], v[82:85]
	v_mfma_f32_16x16x32_bf16 v[66:69], v[180:183], v[212:215], v[66:69]
	v_mfma_f32_16x16x32_bf16 v[118:121], v[176:179], v[192:195], v[118:121]
	v_mfma_f32_16x16x32_bf16 v[102:105], v[176:179], v[200:203], v[102:105]
	v_mfma_f32_16x16x32_bf16 v[86:89], v[176:179], v[208:211], v[86:89]
	v_mfma_f32_16x16x32_bf16 v[70:73], v[176:179], v[216:219], v[70:73]
	v_mfma_f32_16x16x32_bf16 v[114:117], v[184:187], v[192:195], v[114:117]
	v_mfma_f32_16x16x32_bf16 v[98:101], v[184:187], v[200:203], v[98:101]
	v_mfma_f32_16x16x32_bf16 v[82:85], v[184:187], v[208:211], v[82:85]
	v_mfma_f32_16x16x32_bf16 v[66:69], v[184:187], v[216:219], v[66:69]
	s_barrier
	s_setprio 0
	s_add_u32 s98, s40, s12
	s_addc_u32 s99, s41, s13
	s_add_u32 s100, s42, s12
	s_addc_u32 s101, s43, s13
	s_add_i32 s64, s57, s44
	s_mov_b32 m0, s64
	ds_read_b128 v[188:191], v164 offset:16384
	ds_read_b128 v[192:195], v164 offset:17408
	ds_read_b128 v[196:199], v164 offset:18432
	ds_read_b128 v[200:203], v164 offset:19456
	ds_read_b128 v[204:207], v164 offset:20480
	ds_read_b128 v[208:211], v164 offset:21504
	ds_read_b128 v[212:215], v164 offset:22528
	ds_read_b128 v[216:219], v164 offset:23552
	global_load_lds_dwordx4 v140, s[40:41]
	s_add_i32 m0, s64, 0x2000
	s_add_u32 s64, s40, 0x40000
	s_addc_u32 s65, s41, 0
	s_add_i32 s66, s58, s44
	global_load_lds_dwordx4 v144, s[40:41]
	s_mov_b32 m0, s66
	s_nop 0
	global_load_lds_dwordx4 v140, s[64:65]
	s_add_i32 m0, s66, 0x2000
	s_nop 0
	global_load_lds_dwordx4 v144, s[64:65]
	s_mov_b32 m0, s45
	s_nop 0
	global_load_lds_dwordx4 v138, s[42:43]
	s_mov_b32 m0, s46
	s_nop 0
	global_load_lds_dwordx4 v142, s[42:43]
	s_waitcnt vmcnt(8)
	s_waitcnt lgkmcnt(0)
	s_setprio 1
	s_barrier
	v_mfma_f32_16x16x32_bf16 v[62:65], v[130:133], v[188:191], v[62:65]
	v_mfma_f32_16x16x32_bf16 v[46:49], v[130:133], v[196:199], v[46:49]
	v_mfma_f32_16x16x32_bf16 v[30:33], v[130:133], v[204:207], v[30:33]
	v_mfma_f32_16x16x32_bf16 v[14:17], v[130:133], v[212:215], v[14:17]
	v_mfma_f32_16x16x32_bf16 v[58:61], v[154:157], v[188:191], v[58:61]
	v_mfma_f32_16x16x32_bf16 v[42:45], v[154:157], v[196:199], v[42:45]
	v_mfma_f32_16x16x32_bf16 v[26:29], v[154:157], v[204:207], v[26:29]
	v_mfma_f32_16x16x32_bf16 v[10:13], v[154:157], v[212:215], v[10:13]
	v_mfma_f32_16x16x32_bf16 v[62:65], v[134:137], v[192:195], v[62:65]
	v_mfma_f32_16x16x32_bf16 v[46:49], v[134:137], v[200:203], v[46:49]
	v_mfma_f32_16x16x32_bf16 v[30:33], v[134:137], v[208:211], v[30:33]
	v_mfma_f32_16x16x32_bf16 v[14:17], v[134:137], v[216:219], v[14:17]
	v_mfma_f32_16x16x32_bf16 v[58:61], v[166:169], v[192:195], v[58:61]
	v_mfma_f32_16x16x32_bf16 v[42:45], v[166:169], v[200:203], v[42:45]
	v_mfma_f32_16x16x32_bf16 v[26:29], v[166:169], v[208:211], v[26:29]
	v_mfma_f32_16x16x32_bf16 v[10:13], v[166:169], v[216:219], v[10:13]
	v_mfma_f32_16x16x32_bf16 v[54:57], v[172:175], v[188:191], v[54:57]
	v_mfma_f32_16x16x32_bf16 v[38:41], v[172:175], v[196:199], v[38:41]
	v_mfma_f32_16x16x32_bf16 v[22:25], v[172:175], v[204:207], v[22:25]
	v_mfma_f32_16x16x32_bf16 v[6:9], v[172:175], v[212:215], v[6:9]
	v_mfma_f32_16x16x32_bf16 v[50:53], v[180:183], v[188:191], v[50:53]
	v_mfma_f32_16x16x32_bf16 v[34:37], v[180:183], v[196:199], v[34:37]
	v_mfma_f32_16x16x32_bf16 v[18:21], v[180:183], v[204:207], v[18:21]
	v_mfma_f32_16x16x32_bf16 v[2:5], v[180:183], v[212:215], v[2:5]
	v_mfma_f32_16x16x32_bf16 v[54:57], v[176:179], v[192:195], v[54:57]
	v_mfma_f32_16x16x32_bf16 v[38:41], v[176:179], v[200:203], v[38:41]
	v_mfma_f32_16x16x32_bf16 v[22:25], v[176:179], v[208:211], v[22:25]
	v_mfma_f32_16x16x32_bf16 v[6:9], v[176:179], v[216:219], v[6:9]
	v_mfma_f32_16x16x32_bf16 v[50:53], v[184:187], v[192:195], v[50:53]
	v_mfma_f32_16x16x32_bf16 v[34:37], v[184:187], v[200:203], v[34:37]
	v_mfma_f32_16x16x32_bf16 v[18:21], v[184:187], v[208:211], v[18:21]
	v_mfma_f32_16x16x32_bf16 v[2:5], v[184:187], v[216:219], v[2:5]
	s_barrier
; #define PG8_STAGE(bufoff, gbase, voff) do { _Pragma("unroll") for (int _i = 0; _i < 2; ++_i) \
;         __builtin_amdgcn_global_load_lds((const unsigned*)((const char*)(gbase) + (voff)[_i]), (LAS unsigned*)(lds + (bufoff) + ldsw + _i * 8192), 16, 0, 0); } while (0)
; #define PG8_LDA(dst, b, h) do { _Pragma("unroll") for (int m = 0; m < 4; ++m) _Pragma("unroll") for (int k = 0; k < 2; ++k) dst[m][k] = *(const LAS bf16x8*)(lds + PG8_SA(b, h) + aoff + m * 2048 + k * 1024); } while (0)
; #define PG8_LDB(dst, b, h) do { _Pragma("unroll") for (int n = 0; n < 2; ++n) _Pragma("unroll") for (int k = 0; k < 2; ++k) dst[n][k] = *(const LAS bf16x8*)(lds + PG8_SB(b, h) + boff + n * 2048 + k * 1024); } while (0)
; #define PG8_MMA(ai, bj, At, Bt) do { __builtin_amdgcn_s_setprio(1); _Pragma("unroll") for (int m = 0; m < 4; ++m) _Pragma("unroll") for (int n = 0; n < 2; ++n) _Pragma("unroll") for (int k = 0; k < 2; ++k) \
;         acc[ai][bj][m][n] = __builtin_amdgcn_mfma_f32_16x16x32_bf16(Bt[n][k], At[m][k], acc[ai][bj][m][n], 0, 0, 0); __builtin_amdgcn_s_setprio(0); } while (0)
; #define PG8_WAIT_V(n) asm volatile("s_waitcnt vmcnt(" #n ")" ::: "memory")
; #define PG8_WAIT_L(n) asm volatile("s_waitcnt lgkmcnt(" #n ")" ::: "memory")
; #define PG8_BAR __builtin_amdgcn_s_barrier()
; #define PG8_SCHED __builtin_amdgcn_sched_barrier(0)
; template <class Epi>
; __device__ __forceinline__ void gemm_phase(LAS unsigned char* lds, const Gemm g, const StaticOrder& S, const Epi& E) {
;     ...
;             PG8_LDB(B0, 1, 0); PG8_LDB(B1, 1, 1); PG8_SCHED; PG8_LDA(At, 1, 0); PG8_STAGE(PG8_SA(0, 1), a2 + hstep, voffA);
;             PG8_WAIT_V(8); PG8_WAIT_L(0); PG8_BAR; PG8_MMA(0, 0, At, B0); PG8_MMA(0, 1, At, B1); PG8_BAR; PG8_SCHED;
;             PG8_LDA(At, 1, 1); PG8_STAGE(PG8_SB(1, 0), b3, voffB); PG8_STAGE(PG8_SB(1, 1), b3 + hstep, voffB); PG8_STAGE(PG8_SA(1, 0), a3, voffA);
;             PG8_WAIT_V(8); PG8_WAIT_L(0); PG8_BAR; PG8_MMA(1, 0, At, B0); PG8_MMA(1, 1, At, B1); PG8_BAR; PG8_SCHED;
;         }
;         if (wr == 0) PG8_BAR;
	s_setprio 0
	s_add_i32 s64, 0, 0x18000
	s_add_i32 s65, 0, 0x1c000
	v_add_u32_e32 v166, s64, v160
	v_add_u32_e32 v184, s65, v160
	ds_read_b128 v[130:133], v166
	ds_read_b128 v[134:137], v166 offset:1024
	ds_read_b128 v[154:157], v166 offset:2048
	ds_read_b128 v[166:169], v166 offset:3072
	ds_read_b128 v[172:175], v184
	ds_read_b128 v[176:179], v184 offset:1024
	ds_read_b128 v[180:183], v184 offset:2048
	ds_read_b128 v[184:187], v184 offset:3072
	s_add_u32 s42, s42, 0x40000
	s_addc_u32 s43, s43, 0
	s_mov_b32 m0, s47
	ds_read_b128 v[188:191], v164 offset:32768
	ds_read_b128 v[192:195], v164 offset:33792
	ds_read_b128 v[196:199], v164 offset:34816
	ds_read_b128 v[200:203], v164 offset:35840
	ds_read_b128 v[204:207], v164 offset:36864
	ds_read_b128 v[208:211], v164 offset:37888
	ds_read_b128 v[212:215], v164 offset:38912
	ds_read_b128 v[216:219], v164 offset:39936
	global_load_lds_dwordx4 v138, s[42:43]
	s_mov_b32 m0, s48
	s_nop 0
	global_load_lds_dwordx4 v142, s[42:43]
	s_waitcnt vmcnt(8)
	s_waitcnt lgkmcnt(0)
	s_setprio 1
	s_barrier
	v_mfma_f32_16x16x32_bf16 v[126:129], v[130:133], v[188:191], v[126:129]
	v_mfma_f32_16x16x32_bf16 v[110:113], v[130:133], v[196:199], v[110:113]
	v_mfma_f32_16x16x32_bf16 v[94:97], v[130:133], v[204:207], v[94:97]
	v_mfma_f32_16x16x32_bf16 v[78:81], v[130:133], v[212:215], v[78:81]
	v_mfma_f32_16x16x32_bf16 v[122:125], v[154:157], v[188:191], v[122:125]
	v_mfma_f32_16x16x32_bf16 v[106:109], v[154:157], v[196:199], v[106:109]
	v_mfma_f32_16x16x32_bf16 v[90:93], v[154:157], v[204:207], v[90:93]
	v_mfma_f32_16x16x32_bf16 v[74:77], v[154:157], v[212:215], v[74:77]
	v_mfma_f32_16x16x32_bf16 v[126:129], v[134:137], v[192:195], v[126:129]
	v_mfma_f32_16x16x32_bf16 v[110:113], v[134:137], v[200:203], v[110:113]
	v_mfma_f32_16x16x32_bf16 v[94:97], v[134:137], v[208:211], v[94:97]
	v_mfma_f32_16x16x32_bf16 v[78:81], v[134:137], v[216:219], v[78:81]
	v_mfma_f32_16x16x32_bf16 v[122:125], v[166:169], v[192:195], v[122:125]
	v_mfma_f32_16x16x32_bf16 v[106:109], v[166:169], v[200:203], v[106:109]
	v_mfma_f32_16x16x32_bf16 v[90:93], v[166:169], v[208:211], v[90:93]
	v_mfma_f32_16x16x32_bf16 v[74:77], v[166:169], v[216:219], v[74:77]
	v_mfma_f32_16x16x32_bf16 v[118:121], v[172:175], v[188:191], v[118:121]
	v_mfma_f32_16x16x32_bf16 v[102:105], v[172:175], v[196:199], v[102:105]
	v_mfma_f32_16x16x32_bf16 v[86:89], v[172:175], v[204:207], v[86:89]
	v_mfma_f32_16x16x32_bf16 v[70:73], v[172:175], v[212:215], v[70:73]
	v_mfma_f32_16x16x32_bf16 v[114:117], v[180:183], v[188:191], v[114:117]
	v_mfma_f32_16x16x32_bf16 v[98:101], v[180:183], v[196:199], v[98:101]
	v_mfma_f32_16x16x32_bf16 v[82:85], v[180:183], v[204:207], v[82:85]
	v_mfma_f32_16x16x32_bf16 v[66:69], v[180:183], v[212:215], v[66:69]
	v_mfma_f32_16x16x32_bf16 v[118:121], v[176:179], v[192:195], v[118:121]
	v_mfma_f32_16x16x32_bf16 v[102:105], v[176:179], v[200:203], v[102:105]
	v_mfma_f32_16x16x32_bf16 v[86:89], v[176:179], v[208:211], v[86:89]
	v_mfma_f32_16x16x32_bf16 v[70:73], v[176:179], v[216:219], v[70:73]
	v_mfma_f32_16x16x32_bf16 v[114:117], v[184:187], v[192:195], v[114:117]
	v_mfma_f32_16x16x32_bf16 v[98:101], v[184:187], v[200:203], v[98:101]
	v_mfma_f32_16x16x32_bf16 v[82:85], v[184:187], v[208:211], v[82:85]
	v_mfma_f32_16x16x32_bf16 v[66:69], v[184:187], v[216:219], v[66:69]
	s_barrier
	s_setprio 0
	s_add_i32 s42, s64, s44
	s_mov_b32 m0, s42
	ds_read_b128 v[188:191], v164 offset:49152
	ds_read_b128 v[192:195], v164 offset:50176
	ds_read_b128 v[196:199], v164 offset:51200
	ds_read_b128 v[200:203], v164 offset:52224
	ds_read_b128 v[204:207], v164 offset:53248
	ds_read_b128 v[208:211], v164 offset:54272
	ds_read_b128 v[212:215], v164 offset:55296
	ds_read_b128 v[216:219], v164 offset:56320
	global_load_lds_dwordx4 v140, s[98:99]
	s_add_i32 m0, s42, 0x2000
	s_add_u32 s40, s40, 0x40080
	s_addc_u32 s41, s41, 0
	s_add_i32 s42, s65, s44
	global_load_lds_dwordx4 v144, s[98:99]
	s_mov_b32 m0, s42
	s_nop 0
	global_load_lds_dwordx4 v140, s[40:41]
	s_add_i32 m0, s42, 0x2000
	s_nop 0
	global_load_lds_dwordx4 v144, s[40:41]
	s_mov_b32 m0, s50
	s_nop 0
	global_load_lds_dwordx4 v138, s[100:101]
	s_mov_b32 m0, s51
	s_nop 0
	global_load_lds_dwordx4 v142, s[100:101]
	s_waitcnt vmcnt(8)
	s_waitcnt lgkmcnt(0)
	s_setprio 1
	s_barrier
	v_mfma_f32_16x16x32_bf16 v[62:65], v[130:133], v[188:191], v[62:65]
	v_mfma_f32_16x16x32_bf16 v[46:49], v[130:133], v[196:199], v[46:49]
	v_mfma_f32_16x16x32_bf16 v[30:33], v[130:133], v[204:207], v[30:33]
	v_mfma_f32_16x16x32_bf16 v[14:17], v[130:133], v[212:215], v[14:17]
	v_mfma_f32_16x16x32_bf16 v[58:61], v[154:157], v[188:191], v[58:61]
	v_mfma_f32_16x16x32_bf16 v[42:45], v[154:157], v[196:199], v[42:45]
	v_mfma_f32_16x16x32_bf16 v[26:29], v[154:157], v[204:207], v[26:29]
	v_mfma_f32_16x16x32_bf16 v[10:13], v[154:157], v[212:215], v[10:13]
	v_mfma_f32_16x16x32_bf16 v[62:65], v[134:137], v[192:195], v[62:65]
	v_mfma_f32_16x16x32_bf16 v[46:49], v[134:137], v[200:203], v[46:49]
	v_mfma_f32_16x16x32_bf16 v[30:33], v[134:137], v[208:211], v[30:33]
	v_mfma_f32_16x16x32_bf16 v[14:17], v[134:137], v[216:219], v[14:17]
	v_mfma_f32_16x16x32_bf16 v[58:61], v[166:169], v[192:195], v[58:61]
	v_mfma_f32_16x16x32_bf16 v[42:45], v[166:169], v[200:203], v[42:45]
	v_mfma_f32_16x16x32_bf16 v[26:29], v[166:169], v[208:211], v[26:29]
	v_mfma_f32_16x16x32_bf16 v[10:13], v[166:169], v[216:219], v[10:13]
	v_mfma_f32_16x16x32_bf16 v[54:57], v[172:175], v[188:191], v[54:57]
	v_mfma_f32_16x16x32_bf16 v[38:41], v[172:175], v[196:199], v[38:41]
	v_mfma_f32_16x16x32_bf16 v[22:25], v[172:175], v[204:207], v[22:25]
	v_mfma_f32_16x16x32_bf16 v[6:9], v[172:175], v[212:215], v[6:9]
	v_mfma_f32_16x16x32_bf16 v[50:53], v[180:183], v[188:191], v[50:53]
	v_mfma_f32_16x16x32_bf16 v[34:37], v[180:183], v[196:199], v[34:37]
	v_mfma_f32_16x16x32_bf16 v[18:21], v[180:183], v[204:207], v[18:21]
	v_mfma_f32_16x16x32_bf16 v[2:5], v[180:183], v[212:215], v[2:5]
	v_mfma_f32_16x16x32_bf16 v[54:57], v[176:179], v[192:195], v[54:57]
	v_mfma_f32_16x16x32_bf16 v[38:41], v[176:179], v[200:203], v[38:41]
	v_mfma_f32_16x16x32_bf16 v[22:25], v[176:179], v[208:211], v[22:25]
	v_mfma_f32_16x16x32_bf16 v[6:9], v[176:179], v[216:219], v[6:9]
	v_mfma_f32_16x16x32_bf16 v[50:53], v[184:187], v[192:195], v[50:53]
	v_mfma_f32_16x16x32_bf16 v[34:37], v[184:187], v[200:203], v[34:37]
	v_mfma_f32_16x16x32_bf16 v[18:21], v[184:187], v[208:211], v[18:21]
	v_mfma_f32_16x16x32_bf16 v[2:5], v[184:187], v[216:219], v[2:5]
	s_barrier
	s_setprio 0
	s_add_i32 s63, s63, 2
	s_add_u32 s38, s38, 0x100
	s_addc_u32 s39, s39, 0
	s_add_u32 s61, s61, 0x100
	s_addc_u32 s62, s62, 0
	s_cmp_gt_u32 s63, 13
	s_cbranch_scc0 .LBB0_785
	s_and_b64 vcc, exec, s[14:15]
	s_cbranch_vccz .LBB0_788
	s_barrier

; #define PG8_STAGE(bufoff, gbase, voff) do { _Pragma("unroll") for (int _i = 0; _i < 2; ++_i) \
;         __builtin_amdgcn_global_load_lds((const unsigned*)((const char*)(gbase) + (voff)[_i]), (LAS unsigned*)(lds + (bufoff) + ldsw + _i * 8192), 16, 0, 0); } while (0)
; #define PG8_LDA(dst, b, h) do { _Pragma("unroll") for (int m = 0; m < 4; ++m) _Pragma("unroll") for (int k = 0; k < 2; ++k) dst[m][k] = *(const LAS bf16x8*)(lds + PG8_SA(b, h) + aoff + m * 2048 + k * 1024); } while (0)
; #define PG8_LDB(dst, b, h) do { _Pragma("unroll") for (int n = 0; n < 2; ++n) _Pragma("unroll") for (int k = 0; k < 2; ++k) dst[n][k] = *(const LAS bf16x8*)(lds + PG8_SB(b, h) + boff + n * 2048 + k * 1024); } while (0)
; #define PG8_MMA(ai, bj, At, Bt) do { __builtin_amdgcn_s_setprio(1); _Pragma("unroll") for (int m = 0; m < 4; ++m) _Pragma("unroll") for (int n = 0; n < 2; ++n) _Pragma("unroll") for (int k = 0; k < 2; ++k) \
;         acc[ai][bj][m][n] = __builtin_amdgcn_mfma_f32_16x16x32_bf16(Bt[n][k], At[m][k], acc[ai][bj][m][n], 0, 0, 0); __builtin_amdgcn_s_setprio(0); } while (0)
; #define PG8_WAIT_V(n) asm volatile("s_waitcnt vmcnt(" #n ")" ::: "memory")
; #define PG8_WAIT_L(n) asm volatile("s_waitcnt lgkmcnt(" #n ")" ::: "memory")
; #define PG8_BAR __builtin_amdgcn_s_barrier()
; template <class Epi>
; __device__ __forceinline__ void gemm_phase(LAS unsigned char* lds, const Gemm g, const StaticOrder& S, const Epi& E) {
;     ...
;             const bool last = (t == nt - 2);
;             const char* a1 = cA + (size_t)(t + 1) * kstep;
;             const char* a2 = last ? nA : cA + (size_t)(t + 2) * kstep; const char* b2 = last ? nB : cB + (size_t)(t + 2) * kstep;
;             const char* a3 = a2 + kstep; const char* b3 = b2 + kstep;
;             if constexpr (Epi::MIDK > 0) { if (t == Epi::MIDK) E.mid(acc, cur, wr, wc, fr, fq); }
;             PG8_LDB(B0, 0, 0); PG8_LDB(B1, 0, 1); PG8_SCHED; PG8_LDA(At, 0, 0); PG8_STAGE(PG8_SA(1, 1), a1 + hstep, voffA);
;             PG8_WAIT_V(8); PG8_WAIT_L(0); PG8_BAR; PG8_MMA(0, 0, At, B0); PG8_MMA(0, 1, At, B1); PG8_BAR; PG8_SCHED;
;             PG8_LDA(At, 0, 1); PG8_STAGE(PG8_SB(0, 0), b2, voffB); PG8_STAGE(PG8_SB(0, 1), b2 + hstep, voffB); PG8_STAGE(PG8_SA(0, 0), a2, voffA);
;             PG8_WAIT_V(8); PG8_WAIT_L(0); PG8_BAR; PG8_MMA(1, 0, At, B0); PG8_MMA(1, 1, At, B1); PG8_BAR; PG8_SCHED;
.LBB0_884:
	ds_read_b128 v[158:161], v150
	ds_read_b128 v[162:165], v150 offset:1024
	ds_read_b128 v[166:169], v150 offset:2048
	ds_read_b128 v[174:177], v150 offset:3072
	ds_read_b128 v[178:181], v151
	ds_read_b128 v[182:185], v151 offset:1024
	ds_read_b128 v[186:189], v151 offset:2048
	ds_read_b128 v[190:193], v151 offset:3072
	s_add_u32 s46, s44, 0xfffc0080
	s_addc_u32 s47, s45, -1
	s_cmp_eq_u32 s67, 12
	s_cselect_b32 s49, s62, s47
	s_cselect_b32 s48, s63, s46
	s_cselect_b32 s47, s23, s66
	s_cselect_b32 s46, s64, s65
	s_add_i32 m0, s41, 0xc000
	ds_read_b128 v[194:197], v152
	ds_read_b128 v[198:201], v152 offset:1024
	ds_read_b128 v[202:205], v152 offset:2048
	ds_read_b128 v[206:209], v152 offset:3072
	ds_read_b128 v[210:213], v152 offset:4096
	ds_read_b128 v[214:217], v152 offset:5120
	ds_read_b128 v[218:221], v152 offset:6144
	ds_read_b128 v[222:225], v152 offset:7168
	global_load_lds_dwordx4 v140, s[44:45]
	s_add_i32 m0, s41, 0xe000
	s_nop 0
	global_load_lds_dwordx4 v142, s[44:45]
	s_waitcnt vmcnt(8)
	s_waitcnt lgkmcnt(0)
	s_setprio 1
	s_barrier
	v_mfma_f32_16x16x32_bf16 v[126:129], v[158:161], v[194:197], v[126:129]
	v_mfma_f32_16x16x32_bf16 v[110:113], v[158:161], v[202:205], v[110:113]
	v_mfma_f32_16x16x32_bf16 v[94:97], v[158:161], v[210:213], v[94:97]
	v_mfma_f32_16x16x32_bf16 v[78:81], v[158:161], v[218:221], v[78:81]
	v_mfma_f32_16x16x32_bf16 v[118:121], v[166:169], v[194:197], v[118:121]
	v_mfma_f32_16x16x32_bf16 v[102:105], v[166:169], v[202:205], v[102:105]
	v_mfma_f32_16x16x32_bf16 v[86:89], v[166:169], v[210:213], v[86:89]
	v_mfma_f32_16x16x32_bf16 v[70:73], v[166:169], v[218:221], v[70:73]
	v_mfma_f32_16x16x32_bf16 v[126:129], v[162:165], v[198:201], v[126:129]
	v_mfma_f32_16x16x32_bf16 v[110:113], v[162:165], v[206:209], v[110:113]
	v_mfma_f32_16x16x32_bf16 v[94:97], v[162:165], v[214:217], v[94:97]
	v_mfma_f32_16x16x32_bf16 v[78:81], v[162:165], v[222:225], v[78:81]
	v_mfma_f32_16x16x32_bf16 v[118:121], v[174:177], v[198:201], v[118:121]
	v_mfma_f32_16x16x32_bf16 v[102:105], v[174:177], v[206:209], v[102:105]
	v_mfma_f32_16x16x32_bf16 v[86:89], v[174:177], v[214:217], v[86:89]
	v_mfma_f32_16x16x32_bf16 v[70:73], v[174:177], v[222:225], v[70:73]
	v_mfma_f32_16x16x32_bf16 v[122:125], v[178:181], v[194:197], v[122:125]
	v_mfma_f32_16x16x32_bf16 v[106:109], v[178:181], v[202:205], v[106:109]
	v_mfma_f32_16x16x32_bf16 v[90:93], v[178:181], v[210:213], v[90:93]
	v_mfma_f32_16x16x32_bf16 v[74:77], v[178:181], v[218:221], v[74:77]
	v_mfma_f32_16x16x32_bf16 v[114:117], v[186:189], v[194:197], v[114:117]
	v_mfma_f32_16x16x32_bf16 v[98:101], v[186:189], v[202:205], v[98:101]
	v_mfma_f32_16x16x32_bf16 v[82:85], v[186:189], v[210:213], v[82:85]
	v_mfma_f32_16x16x32_bf16 v[66:69], v[186:189], v[218:221], v[66:69]
	v_mfma_f32_16x16x32_bf16 v[122:125], v[182:185], v[198:201], v[122:125]
	v_mfma_f32_16x16x32_bf16 v[106:109], v[182:185], v[206:209], v[106:109]
	v_mfma_f32_16x16x32_bf16 v[90:93], v[182:185], v[214:217], v[90:93]
	v_mfma_f32_16x16x32_bf16 v[74:77], v[182:185], v[222:225], v[74:77]
	v_mfma_f32_16x16x32_bf16 v[114:117], v[190:193], v[198:201], v[114:117]
	v_mfma_f32_16x16x32_bf16 v[98:101], v[190:193], v[206:209], v[98:101]
	v_mfma_f32_16x16x32_bf16 v[82:85], v[190:193], v[214:217], v[82:85]
	v_mfma_f32_16x16x32_bf16 v[66:69], v[190:193], v[222:225], v[66:69]
	s_barrier
	s_setprio 0
	s_add_u32 s98, s46, s8
	s_addc_u32 s99, s47, s9
	s_add_u32 s100, s48, s8
	s_addc_u32 s101, s49, s9
	s_add_i32 s68, s58, s6
	s_mov_b32 m0, s68
	ds_read_b128 v[194:197], v152 offset:16384
	ds_read_b128 v[198:201], v152 offset:17408
	ds_read_b128 v[202:205], v152 offset:18432
	ds_read_b128 v[206:209], v152 offset:19456
	ds_read_b128 v[210:213], v152 offset:20480
	ds_read_b128 v[214:217], v152 offset:21504
	ds_read_b128 v[218:221], v152 offset:22528
	ds_read_b128 v[222:225], v152 offset:23552
	global_load_lds_dwordx4 v132, s[46:47]
	s_add_i32 m0, s68, 0x2000
	s_add_u32 s68, s46, 0x40000
	s_addc_u32 s69, s47, 0
	s_add_i32 s76, s59, s6
	global_load_lds_dwordx4 v136, s[46:47]
	s_mov_b32 m0, s76
	s_nop 0
	global_load_lds_dwordx4 v132, s[68:69]
	s_add_i32 m0, s76, 0x2000
	s_nop 0
	global_load_lds_dwordx4 v136, s[68:69]
	s_mov_b32 m0, s41
	s_nop 0
	global_load_lds_dwordx4 v130, s[48:49]
	s_mov_b32 m0, s43
	s_nop 0
	global_load_lds_dwordx4 v134, s[48:49]
	s_waitcnt vmcnt(8)
	s_waitcnt lgkmcnt(0)
	s_setprio 1
	s_barrier
	v_mfma_f32_16x16x32_bf16 v[62:65], v[158:161], v[194:197], v[62:65]
	v_mfma_f32_16x16x32_bf16 v[46:49], v[158:161], v[202:205], v[46:49]
	v_mfma_f32_16x16x32_bf16 v[30:33], v[158:161], v[210:213], v[30:33]
	v_mfma_f32_16x16x32_bf16 v[14:17], v[158:161], v[218:221], v[14:17]
	v_mfma_f32_16x16x32_bf16 v[54:57], v[166:169], v[194:197], v[54:57]
	v_mfma_f32_16x16x32_bf16 v[38:41], v[166:169], v[202:205], v[38:41]
	v_mfma_f32_16x16x32_bf16 v[22:25], v[166:169], v[210:213], v[22:25]
	v_mfma_f32_16x16x32_bf16 v[6:9], v[166:169], v[218:221], v[6:9]
	v_mfma_f32_16x16x32_bf16 v[62:65], v[162:165], v[198:201], v[62:65]
	v_mfma_f32_16x16x32_bf16 v[46:49], v[162:165], v[206:209], v[46:49]
	v_mfma_f32_16x16x32_bf16 v[30:33], v[162:165], v[214:217], v[30:33]
	v_mfma_f32_16x16x32_bf16 v[14:17], v[162:165], v[222:225], v[14:17]
	v_mfma_f32_16x16x32_bf16 v[54:57], v[174:177], v[198:201], v[54:57]
	v_mfma_f32_16x16x32_bf16 v[38:41], v[174:177], v[206:209], v[38:41]
	v_mfma_f32_16x16x32_bf16 v[22:25], v[174:177], v[214:217], v[22:25]
	v_mfma_f32_16x16x32_bf16 v[6:9], v[174:177], v[222:225], v[6:9]
	v_mfma_f32_16x16x32_bf16 v[58:61], v[178:181], v[194:197], v[58:61]
	v_mfma_f32_16x16x32_bf16 v[42:45], v[178:181], v[202:205], v[42:45]
	v_mfma_f32_16x16x32_bf16 v[26:29], v[178:181], v[210:213], v[26:29]
	v_mfma_f32_16x16x32_bf16 v[10:13], v[178:181], v[218:221], v[10:13]
	v_mfma_f32_16x16x32_bf16 v[50:53], v[186:189], v[194:197], v[50:53]
	v_mfma_f32_16x16x32_bf16 v[34:37], v[186:189], v[202:205], v[34:37]
	v_mfma_f32_16x16x32_bf16 v[18:21], v[186:189], v[210:213], v[18:21]
	v_mfma_f32_16x16x32_bf16 v[2:5], v[186:189], v[218:221], v[2:5]
	v_mfma_f32_16x16x32_bf16 v[58:61], v[182:185], v[198:201], v[58:61]
	v_mfma_f32_16x16x32_bf16 v[42:45], v[182:185], v[206:209], v[42:45]
	v_mfma_f32_16x16x32_bf16 v[26:29], v[182:185], v[214:217], v[26:29]
	v_mfma_f32_16x16x32_bf16 v[10:13], v[182:185], v[222:225], v[10:13]
	v_mfma_f32_16x16x32_bf16 v[50:53], v[190:193], v[198:201], v[50:53]
	v_mfma_f32_16x16x32_bf16 v[34:37], v[190:193], v[206:209], v[34:37]
	v_mfma_f32_16x16x32_bf16 v[18:21], v[190:193], v[214:217], v[18:21]
	v_mfma_f32_16x16x32_bf16 v[2:5], v[190:193], v[222:225], v[2:5]
	s_barrier
; #define PG8_STAGE(bufoff, gbase, voff) do { _Pragma("unroll") for (int _i = 0; _i < 2; ++_i) \
;         __builtin_amdgcn_global_load_lds((const unsigned*)((const char*)(gbase) + (voff)[_i]), (LAS unsigned*)(lds + (bufoff) + ldsw + _i * 8192), 16, 0, 0); } while (0)
; #define PG8_LDA(dst, b, h) do { _Pragma("unroll") for (int m = 0; m < 4; ++m) _Pragma("unroll") for (int k = 0; k < 2; ++k) dst[m][k] = *(const LAS bf16x8*)(lds + PG8_SA(b, h) + aoff + m * 2048 + k * 1024); } while (0)
; #define PG8_LDB(dst, b, h) do { _Pragma("unroll") for (int n = 0; n < 2; ++n) _Pragma("unroll") for (int k = 0; k < 2; ++k) dst[n][k] = *(const LAS bf16x8*)(lds + PG8_SB(b, h) + boff + n * 2048 + k * 1024); } while (0)
; #define PG8_MMA(ai, bj, At, Bt) do { __builtin_amdgcn_s_setprio(1); _Pragma("unroll") for (int m = 0; m < 4; ++m) _Pragma("unroll") for (int n = 0; n < 2; ++n) _Pragma("unroll") for (int k = 0; k < 2; ++k) \
;         acc[ai][bj][m][n] = __builtin_amdgcn_mfma_f32_16x16x32_bf16(Bt[n][k], At[m][k], acc[ai][bj][m][n], 0, 0, 0); __builtin_amdgcn_s_setprio(0); } while (0)
; #define PG8_WAIT_V(n) asm volatile("s_waitcnt vmcnt(" #n ")" ::: "memory")
; #define PG8_WAIT_L(n) asm volatile("s_waitcnt lgkmcnt(" #n ")" ::: "memory")
; #define PG8_BAR __builtin_amdgcn_s_barrier()
; #define PG8_SCHED __builtin_amdgcn_sched_barrier(0)
; template <class Epi>
; __device__ __forceinline__ void gemm_phase(LAS unsigned char* lds, const Gemm g, const StaticOrder& S, const Epi& E) {
;     ...
;             PG8_LDB(B0, 1, 0); PG8_LDB(B1, 1, 1); PG8_SCHED; PG8_LDA(At, 1, 0); PG8_STAGE(PG8_SA(0, 1), a2 + hstep, voffA);
;             PG8_WAIT_V(8); PG8_WAIT_L(0); PG8_BAR; PG8_MMA(0, 0, At, B0); PG8_MMA(0, 1, At, B1); PG8_BAR; PG8_SCHED;
;             PG8_LDA(At, 1, 1); PG8_STAGE(PG8_SB(1, 0), b3, voffB); PG8_STAGE(PG8_SB(1, 1), b3 + hstep, voffB); PG8_STAGE(PG8_SA(1, 0), a3, voffA);
;             PG8_WAIT_V(8); PG8_WAIT_L(0); PG8_BAR; PG8_MMA(1, 0, At, B0); PG8_MMA(1, 1, At, B1); PG8_BAR; PG8_SCHED;
;         }
;         if (wr == 0) PG8_BAR;
	s_setprio 0
	s_add_i32 s68, 0, 0x18000
	s_add_i32 s69, 0, 0x1c000
	v_add_u32_e32 v174, s68, v148
	v_add_u32_e32 v190, s69, v148
	ds_read_b128 v[158:161], v174
	ds_read_b128 v[162:165], v174 offset:1024
	ds_read_b128 v[166:169], v174 offset:2048
	ds_read_b128 v[174:177], v174 offset:3072
	ds_read_b128 v[178:181], v190
	ds_read_b128 v[182:185], v190 offset:1024
	ds_read_b128 v[186:189], v190 offset:2048
	ds_read_b128 v[190:193], v190 offset:3072
	s_add_u32 s48, s48, 0x40000
	s_addc_u32 s49, s49, 0
	s_mov_b32 m0, s51
	ds_read_b128 v[194:197], v152 offset:32768
	ds_read_b128 v[198:201], v152 offset:33792
	ds_read_b128 v[202:205], v152 offset:34816
	ds_read_b128 v[206:209], v152 offset:35840
	ds_read_b128 v[210:213], v152 offset:36864
	ds_read_b128 v[214:217], v152 offset:37888
	ds_read_b128 v[218:221], v152 offset:38912
	ds_read_b128 v[222:225], v152 offset:39936
	global_load_lds_dwordx4 v130, s[48:49]
	s_mov_b32 m0, s52
	s_nop 0
	global_load_lds_dwordx4 v134, s[48:49]
	s_waitcnt vmcnt(8)
	s_waitcnt lgkmcnt(0)
	s_setprio 1
	s_barrier
	v_mfma_f32_16x16x32_bf16 v[126:129], v[158:161], v[194:197], v[126:129]
	v_mfma_f32_16x16x32_bf16 v[110:113], v[158:161], v[202:205], v[110:113]
	v_mfma_f32_16x16x32_bf16 v[94:97], v[158:161], v[210:213], v[94:97]
	v_mfma_f32_16x16x32_bf16 v[78:81], v[158:161], v[218:221], v[78:81]
	v_mfma_f32_16x16x32_bf16 v[118:121], v[166:169], v[194:197], v[118:121]
	v_mfma_f32_16x16x32_bf16 v[102:105], v[166:169], v[202:205], v[102:105]
	v_mfma_f32_16x16x32_bf16 v[86:89], v[166:169], v[210:213], v[86:89]
	v_mfma_f32_16x16x32_bf16 v[70:73], v[166:169], v[218:221], v[70:73]
	v_mfma_f32_16x16x32_bf16 v[126:129], v[162:165], v[198:201], v[126:129]
	v_mfma_f32_16x16x32_bf16 v[110:113], v[162:165], v[206:209], v[110:113]
	v_mfma_f32_16x16x32_bf16 v[94:97], v[162:165], v[214:217], v[94:97]
	v_mfma_f32_16x16x32_bf16 v[78:81], v[162:165], v[222:225], v[78:81]
	v_mfma_f32_16x16x32_bf16 v[118:121], v[174:177], v[198:201], v[118:121]
	v_mfma_f32_16x16x32_bf16 v[102:105], v[174:177], v[206:209], v[102:105]
	v_mfma_f32_16x16x32_bf16 v[86:89], v[174:177], v[214:217], v[86:89]
	v_mfma_f32_16x16x32_bf16 v[70:73], v[174:177], v[222:225], v[70:73]
	v_mfma_f32_16x16x32_bf16 v[122:125], v[178:181], v[194:197], v[122:125]
	v_mfma_f32_16x16x32_bf16 v[106:109], v[178:181], v[202:205], v[106:109]
	v_mfma_f32_16x16x32_bf16 v[90:93], v[178:181], v[210:213], v[90:93]
	v_mfma_f32_16x16x32_bf16 v[74:77], v[178:181], v[218:221], v[74:77]
	v_mfma_f32_16x16x32_bf16 v[114:117], v[186:189], v[194:197], v[114:117]
	v_mfma_f32_16x16x32_bf16 v[98:101], v[186:189], v[202:205], v[98:101]
	v_mfma_f32_16x16x32_bf16 v[82:85], v[186:189], v[210:213], v[82:85]
	v_mfma_f32_16x16x32_bf16 v[66:69], v[186:189], v[218:221], v[66:69]
	v_mfma_f32_16x16x32_bf16 v[122:125], v[182:185], v[198:201], v[122:125]
	v_mfma_f32_16x16x32_bf16 v[106:109], v[182:185], v[206:209], v[106:109]
	v_mfma_f32_16x16x32_bf16 v[90:93], v[182:185], v[214:217], v[90:93]
	v_mfma_f32_16x16x32_bf16 v[74:77], v[182:185], v[222:225], v[74:77]
	v_mfma_f32_16x16x32_bf16 v[114:117], v[190:193], v[198:201], v[114:117]
	v_mfma_f32_16x16x32_bf16 v[98:101], v[190:193], v[206:209], v[98:101]
	v_mfma_f32_16x16x32_bf16 v[82:85], v[190:193], v[214:217], v[82:85]
	v_mfma_f32_16x16x32_bf16 v[66:69], v[190:193], v[222:225], v[66:69]
	s_barrier
	s_setprio 0
	s_add_i32 s48, s68, s6
	s_mov_b32 m0, s48
	ds_read_b128 v[194:197], v152 offset:49152
	ds_read_b128 v[198:201], v152 offset:50176
	ds_read_b128 v[202:205], v152 offset:51200
	ds_read_b128 v[206:209], v152 offset:52224
	ds_read_b128 v[210:213], v152 offset:53248
	ds_read_b128 v[214:217], v152 offset:54272
	ds_read_b128 v[218:221], v152 offset:55296
	ds_read_b128 v[222:225], v152 offset:56320
	global_load_lds_dwordx4 v132, s[98:99]
	s_add_i32 m0, s48, 0x2000
	s_add_u32 s46, s46, 0x40080
	s_addc_u32 s47, s47, 0
	s_add_i32 s48, s69, s6
	global_load_lds_dwordx4 v136, s[98:99]
	s_mov_b32 m0, s48
	s_nop 0
	global_load_lds_dwordx4 v132, s[46:47]
	s_add_i32 m0, s48, 0x2000
	s_nop 0
	global_load_lds_dwordx4 v136, s[46:47]
	s_mov_b32 m0, s53
	s_nop 0
	global_load_lds_dwordx4 v130, s[100:101]
	s_mov_b32 m0, s54
	s_nop 0
	global_load_lds_dwordx4 v134, s[100:101]
	s_waitcnt vmcnt(8)
	s_waitcnt lgkmcnt(0)
	s_setprio 1
	s_barrier
	v_mfma_f32_16x16x32_bf16 v[62:65], v[158:161], v[194:197], v[62:65]
	v_mfma_f32_16x16x32_bf16 v[46:49], v[158:161], v[202:205], v[46:49]
	v_mfma_f32_16x16x32_bf16 v[30:33], v[158:161], v[210:213], v[30:33]
	v_mfma_f32_16x16x32_bf16 v[14:17], v[158:161], v[218:221], v[14:17]
	v_mfma_f32_16x16x32_bf16 v[54:57], v[166:169], v[194:197], v[54:57]
	v_mfma_f32_16x16x32_bf16 v[38:41], v[166:169], v[202:205], v[38:41]
	v_mfma_f32_16x16x32_bf16 v[22:25], v[166:169], v[210:213], v[22:25]
	v_mfma_f32_16x16x32_bf16 v[6:9], v[166:169], v[218:221], v[6:9]
	v_mfma_f32_16x16x32_bf16 v[62:65], v[162:165], v[198:201], v[62:65]
	v_mfma_f32_16x16x32_bf16 v[46:49], v[162:165], v[206:209], v[46:49]
	v_mfma_f32_16x16x32_bf16 v[30:33], v[162:165], v[214:217], v[30:33]
	v_mfma_f32_16x16x32_bf16 v[14:17], v[162:165], v[222:225], v[14:17]
	v_mfma_f32_16x16x32_bf16 v[54:57], v[174:177], v[198:201], v[54:57]
	v_mfma_f32_16x16x32_bf16 v[38:41], v[174:177], v[206:209], v[38:41]
	v_mfma_f32_16x16x32_bf16 v[22:25], v[174:177], v[214:217], v[22:25]
	v_mfma_f32_16x16x32_bf16 v[6:9], v[174:177], v[222:225], v[6:9]
	v_mfma_f32_16x16x32_bf16 v[58:61], v[178:181], v[194:197], v[58:61]
	v_mfma_f32_16x16x32_bf16 v[42:45], v[178:181], v[202:205], v[42:45]
	v_mfma_f32_16x16x32_bf16 v[26:29], v[178:181], v[210:213], v[26:29]
	v_mfma_f32_16x16x32_bf16 v[10:13], v[178:181], v[218:221], v[10:13]
	v_mfma_f32_16x16x32_bf16 v[50:53], v[186:189], v[194:197], v[50:53]
	v_mfma_f32_16x16x32_bf16 v[34:37], v[186:189], v[202:205], v[34:37]
	v_mfma_f32_16x16x32_bf16 v[18:21], v[186:189], v[210:213], v[18:21]
	v_mfma_f32_16x16x32_bf16 v[2:5], v[186:189], v[218:221], v[2:5]
	v_mfma_f32_16x16x32_bf16 v[58:61], v[182:185], v[198:201], v[58:61]
	v_mfma_f32_16x16x32_bf16 v[42:45], v[182:185], v[206:209], v[42:45]
	v_mfma_f32_16x16x32_bf16 v[26:29], v[182:185], v[214:217], v[26:29]
	v_mfma_f32_16x16x32_bf16 v[10:13], v[182:185], v[222:225], v[10:13]
	v_mfma_f32_16x16x32_bf16 v[50:53], v[190:193], v[198:201], v[50:53]
	v_mfma_f32_16x16x32_bf16 v[34:37], v[190:193], v[206:209], v[34:37]
	v_mfma_f32_16x16x32_bf16 v[18:21], v[190:193], v[214:217], v[18:21]
	v_mfma_f32_16x16x32_bf16 v[2:5], v[190:193], v[222:225], v[2:5]
	s_barrier
	s_setprio 0
	s_add_i32 s67, s67, 2
	s_add_u32 s44, s44, 0x100
	s_addc_u32 s45, s45, 0
	s_add_u32 s65, s65, 0x100
	s_addc_u32 s66, s66, 0
	s_cmp_gt_u32 s67, 13
	s_cbranch_scc0 .LBB0_884
	s_and_b64 vcc, exec, s[14:15]
	s_cbranch_vccz .LBB0_887
	s_barrier

; #define PG8_STAGE(bufoff, gbase, voff) do { _Pragma("unroll") for (int _i = 0; _i < 2; ++_i) \
;         __builtin_amdgcn_global_load_lds((const unsigned*)((const char*)(gbase) + (voff)[_i]), (LAS unsigned*)(lds + (bufoff) + ldsw + _i * 8192), 16, 0, 0); } while (0)
; #define PG8_LDA(dst, b, h) do { _Pragma("unroll") for (int m = 0; m < 4; ++m) _Pragma("unroll") for (int k = 0; k < 2; ++k) dst[m][k] = *(const LAS bf16x8*)(lds + PG8_SA(b, h) + aoff + m * 2048 + k * 1024); } while (0)
; #define PG8_LDB(dst, b, h) do { _Pragma("unroll") for (int n = 0; n < 2; ++n) _Pragma("unroll") for (int k = 0; k < 2; ++k) dst[n][k] = *(const LAS bf16x8*)(lds + PG8_SB(b, h) + boff + n * 2048 + k * 1024); } while (0)
; #define PG8_MMA(ai, bj, At, Bt) do { __builtin_amdgcn_s_setprio(1); _Pragma("unroll") for (int m = 0; m < 4; ++m) _Pragma("unroll") for (int n = 0; n < 2; ++n) _Pragma("unroll") for (int k = 0; k < 2; ++k) \
;         acc[ai][bj][m][n] = __builtin_amdgcn_mfma_f32_16x16x32_bf16(Bt[n][k], At[m][k], acc[ai][bj][m][n], 0, 0, 0); __builtin_amdgcn_s_setprio(0); } while (0)
; #define PG8_WAIT_V(n) asm volatile("s_waitcnt vmcnt(" #n ")" ::: "memory")
; #define PG8_WAIT_L(n) asm volatile("s_waitcnt lgkmcnt(" #n ")" ::: "memory")
; #define PG8_BAR __builtin_amdgcn_s_barrier()
; template <class Epi>
; __device__ __forceinline__ void gemm_phase(LAS unsigned char* lds, const Gemm g, const StaticOrder& S, const Epi& E) {
;     ...
;             const bool last = (t == nt - 2);
;             const char* a1 = cA + (size_t)(t + 1) * kstep;
;             const char* a2 = last ? nA : cA + (size_t)(t + 2) * kstep; const char* b2 = last ? nB : cB + (size_t)(t + 2) * kstep;
;             const char* a3 = a2 + kstep; const char* b3 = b2 + kstep;
;             if constexpr (Epi::MIDK > 0) { if (t == Epi::MIDK) E.mid(acc, cur, wr, wc, fr, fq); }
;             PG8_LDB(B0, 0, 0); PG8_LDB(B1, 0, 1); PG8_SCHED; PG8_LDA(At, 0, 0); PG8_STAGE(PG8_SA(1, 1), a1 + hstep, voffA);
;             PG8_WAIT_V(8); PG8_WAIT_L(0); PG8_BAR; PG8_MMA(0, 0, At, B0); PG8_MMA(0, 1, At, B1); PG8_BAR; PG8_SCHED;
;             PG8_LDA(At, 0, 1); PG8_STAGE(PG8_SB(0, 0), b2, voffB); PG8_STAGE(PG8_SB(0, 1), b2 + hstep, voffB); PG8_STAGE(PG8_SA(0, 0), a2, voffA);
;             PG8_WAIT_V(8); PG8_WAIT_L(0); PG8_BAR; PG8_MMA(1, 0, At, B0); PG8_MMA(1, 1, At, B1); PG8_BAR; PG8_SCHED;
.LBB0_971:
	ds_read_b128 v[130:133], v162
	ds_read_b128 v[134:137], v162 offset:1024
	ds_read_b128 v[154:157], v162 offset:2048
	ds_read_b128 v[166:169], v162 offset:3072
	ds_read_b128 v[174:177], v163
	ds_read_b128 v[178:181], v163 offset:1024
	ds_read_b128 v[182:185], v163 offset:2048
	ds_read_b128 v[186:189], v163 offset:3072
	s_add_u32 s24, s22, 0xfff50080
	s_addc_u32 s25, s23, -1
	s_cmp_eq_u32 s59, 40
	s_cselect_b32 s27, s5, s25
	s_cselect_b32 s26, s4, s24
	s_cselect_b32 s25, s21, s58
	s_cselect_b32 s24, s20, s57
	s_add_i32 m0, s39, 0xc000
	ds_read_b128 v[190:193], v164
	ds_read_b128 v[194:197], v164 offset:1024
	ds_read_b128 v[198:201], v164 offset:2048
	ds_read_b128 v[202:205], v164 offset:3072
	ds_read_b128 v[206:209], v164 offset:4096
	ds_read_b128 v[210:213], v164 offset:5120
	ds_read_b128 v[214:217], v164 offset:6144
	ds_read_b128 v[218:221], v164 offset:7168
	global_load_lds_dwordx4 v146, s[22:23]
	s_add_i32 m0, s39, 0xe000
	s_nop 0
	global_load_lds_dwordx4 v148, s[22:23]
	s_waitcnt vmcnt(8)
	s_waitcnt lgkmcnt(0)
	s_setprio 1
	s_barrier
	v_mfma_f32_16x16x32_bf16 v[126:129], v[130:133], v[190:193], v[126:129]
	v_mfma_f32_16x16x32_bf16 v[110:113], v[130:133], v[198:201], v[110:113]
	v_mfma_f32_16x16x32_bf16 v[94:97], v[130:133], v[206:209], v[94:97]
	v_mfma_f32_16x16x32_bf16 v[78:81], v[130:133], v[214:217], v[78:81]
	v_mfma_f32_16x16x32_bf16 v[122:125], v[154:157], v[190:193], v[122:125]
	v_mfma_f32_16x16x32_bf16 v[106:109], v[154:157], v[198:201], v[106:109]
	v_mfma_f32_16x16x32_bf16 v[90:93], v[154:157], v[206:209], v[90:93]
	v_mfma_f32_16x16x32_bf16 v[74:77], v[154:157], v[214:217], v[74:77]
	v_mfma_f32_16x16x32_bf16 v[126:129], v[134:137], v[194:197], v[126:129]
	v_mfma_f32_16x16x32_bf16 v[110:113], v[134:137], v[202:205], v[110:113]
	v_mfma_f32_16x16x32_bf16 v[94:97], v[134:137], v[210:213], v[94:97]
	v_mfma_f32_16x16x32_bf16 v[78:81], v[134:137], v[218:221], v[78:81]
	v_mfma_f32_16x16x32_bf16 v[122:125], v[166:169], v[194:197], v[122:125]
	v_mfma_f32_16x16x32_bf16 v[106:109], v[166:169], v[202:205], v[106:109]
	v_mfma_f32_16x16x32_bf16 v[90:93], v[166:169], v[210:213], v[90:93]
	v_mfma_f32_16x16x32_bf16 v[74:77], v[166:169], v[218:221], v[74:77]
	v_mfma_f32_16x16x32_bf16 v[118:121], v[174:177], v[190:193], v[118:121]
	v_mfma_f32_16x16x32_bf16 v[102:105], v[174:177], v[198:201], v[102:105]
	v_mfma_f32_16x16x32_bf16 v[86:89], v[174:177], v[206:209], v[86:89]
	v_mfma_f32_16x16x32_bf16 v[70:73], v[174:177], v[214:217], v[70:73]
	v_mfma_f32_16x16x32_bf16 v[114:117], v[182:185], v[190:193], v[114:117]
	v_mfma_f32_16x16x32_bf16 v[98:101], v[182:185], v[198:201], v[98:101]
	v_mfma_f32_16x16x32_bf16 v[82:85], v[182:185], v[206:209], v[82:85]
	v_mfma_f32_16x16x32_bf16 v[66:69], v[182:185], v[214:217], v[66:69]
	v_mfma_f32_16x16x32_bf16 v[118:121], v[178:181], v[194:197], v[118:121]
	v_mfma_f32_16x16x32_bf16 v[102:105], v[178:181], v[202:205], v[102:105]
	v_mfma_f32_16x16x32_bf16 v[86:89], v[178:181], v[210:213], v[86:89]
	v_mfma_f32_16x16x32_bf16 v[70:73], v[178:181], v[218:221], v[70:73]
	v_mfma_f32_16x16x32_bf16 v[114:117], v[186:189], v[194:197], v[114:117]
	v_mfma_f32_16x16x32_bf16 v[98:101], v[186:189], v[202:205], v[98:101]
	v_mfma_f32_16x16x32_bf16 v[82:85], v[186:189], v[210:213], v[82:85]
	v_mfma_f32_16x16x32_bf16 v[66:69], v[186:189], v[218:221], v[66:69]
	s_barrier
	s_setprio 0
	s_add_u32 s98, s24, s14
	s_addc_u32 s99, s25, s15
	s_add_u32 s100, s26, s14
	s_addc_u32 s101, s27, s15
	s_add_i32 s60, s51, s38
	s_mov_b32 m0, s60
	ds_read_b128 v[190:193], v164 offset:16384
	ds_read_b128 v[194:197], v164 offset:17408
	ds_read_b128 v[198:201], v164 offset:18432
	ds_read_b128 v[202:205], v164 offset:19456
	ds_read_b128 v[206:209], v164 offset:20480
	ds_read_b128 v[210:213], v164 offset:21504
	ds_read_b128 v[214:217], v164 offset:22528
	ds_read_b128 v[218:221], v164 offset:23552
	global_load_lds_dwordx4 v140, s[24:25]
	s_add_i32 m0, s60, 0x2000
	s_add_u32 s60, s24, 0xb0000
	s_addc_u32 s61, s25, 0
	s_add_i32 s62, s52, s38
	global_load_lds_dwordx4 v144, s[24:25]
	s_mov_b32 m0, s62
	s_nop 0
	global_load_lds_dwordx4 v140, s[60:61]
	s_add_i32 m0, s62, 0x2000
	s_nop 0
	global_load_lds_dwordx4 v144, s[60:61]
	s_mov_b32 m0, s39
	s_nop 0
	global_load_lds_dwordx4 v138, s[26:27]
	s_mov_b32 m0, s40
	s_nop 0
	global_load_lds_dwordx4 v142, s[26:27]
	s_waitcnt vmcnt(8)
	s_waitcnt lgkmcnt(0)
	s_setprio 1
	s_barrier
	v_mfma_f32_16x16x32_bf16 v[62:65], v[130:133], v[190:193], v[62:65]
	v_mfma_f32_16x16x32_bf16 v[46:49], v[130:133], v[198:201], v[46:49]
	v_mfma_f32_16x16x32_bf16 v[30:33], v[130:133], v[206:209], v[30:33]
	v_mfma_f32_16x16x32_bf16 v[14:17], v[130:133], v[214:217], v[14:17]
	v_mfma_f32_16x16x32_bf16 v[58:61], v[154:157], v[190:193], v[58:61]
	v_mfma_f32_16x16x32_bf16 v[42:45], v[154:157], v[198:201], v[42:45]
	v_mfma_f32_16x16x32_bf16 v[26:29], v[154:157], v[206:209], v[26:29]
	v_mfma_f32_16x16x32_bf16 v[10:13], v[154:157], v[214:217], v[10:13]
	v_mfma_f32_16x16x32_bf16 v[62:65], v[134:137], v[194:197], v[62:65]
	v_mfma_f32_16x16x32_bf16 v[46:49], v[134:137], v[202:205], v[46:49]
	v_mfma_f32_16x16x32_bf16 v[30:33], v[134:137], v[210:213], v[30:33]
	v_mfma_f32_16x16x32_bf16 v[14:17], v[134:137], v[218:221], v[14:17]
	v_mfma_f32_16x16x32_bf16 v[58:61], v[166:169], v[194:197], v[58:61]
	v_mfma_f32_16x16x32_bf16 v[42:45], v[166:169], v[202:205], v[42:45]
	v_mfma_f32_16x16x32_bf16 v[26:29], v[166:169], v[210:213], v[26:29]
	v_mfma_f32_16x16x32_bf16 v[10:13], v[166:169], v[218:221], v[10:13]
	v_mfma_f32_16x16x32_bf16 v[54:57], v[174:177], v[190:193], v[54:57]
	v_mfma_f32_16x16x32_bf16 v[38:41], v[174:177], v[198:201], v[38:41]
	v_mfma_f32_16x16x32_bf16 v[22:25], v[174:177], v[206:209], v[22:25]
	v_mfma_f32_16x16x32_bf16 v[6:9], v[174:177], v[214:217], v[6:9]
	v_mfma_f32_16x16x32_bf16 v[50:53], v[182:185], v[190:193], v[50:53]
	v_mfma_f32_16x16x32_bf16 v[34:37], v[182:185], v[198:201], v[34:37]
	v_mfma_f32_16x16x32_bf16 v[18:21], v[182:185], v[206:209], v[18:21]
	v_mfma_f32_16x16x32_bf16 v[2:5], v[182:185], v[214:217], v[2:5]
	v_mfma_f32_16x16x32_bf16 v[54:57], v[178:181], v[194:197], v[54:57]
	v_mfma_f32_16x16x32_bf16 v[38:41], v[178:181], v[202:205], v[38:41]
	v_mfma_f32_16x16x32_bf16 v[22:25], v[178:181], v[210:213], v[22:25]
	v_mfma_f32_16x16x32_bf16 v[6:9], v[178:181], v[218:221], v[6:9]
	v_mfma_f32_16x16x32_bf16 v[50:53], v[186:189], v[194:197], v[50:53]
	v_mfma_f32_16x16x32_bf16 v[34:37], v[186:189], v[202:205], v[34:37]
	v_mfma_f32_16x16x32_bf16 v[18:21], v[186:189], v[210:213], v[18:21]
	v_mfma_f32_16x16x32_bf16 v[2:5], v[186:189], v[218:221], v[2:5]
	s_barrier
; #define PG8_STAGE(bufoff, gbase, voff) do { _Pragma("unroll") for (int _i = 0; _i < 2; ++_i) \
;         __builtin_amdgcn_global_load_lds((const unsigned*)((const char*)(gbase) + (voff)[_i]), (LAS unsigned*)(lds + (bufoff) + ldsw + _i * 8192), 16, 0, 0); } while (0)
; #define PG8_LDA(dst, b, h) do { _Pragma("unroll") for (int m = 0; m < 4; ++m) _Pragma("unroll") for (int k = 0; k < 2; ++k) dst[m][k] = *(const LAS bf16x8*)(lds + PG8_SA(b, h) + aoff + m * 2048 + k * 1024); } while (0)
; #define PG8_LDB(dst, b, h) do { _Pragma("unroll") for (int n = 0; n < 2; ++n) _Pragma("unroll") for (int k = 0; k < 2; ++k) dst[n][k] = *(const LAS bf16x8*)(lds + PG8_SB(b, h) + boff + n * 2048 + k * 1024); } while (0)
; #define PG8_MMA(ai, bj, At, Bt) do { __builtin_amdgcn_s_setprio(1); _Pragma("unroll") for (int m = 0; m < 4; ++m) _Pragma("unroll") for (int n = 0; n < 2; ++n) _Pragma("unroll") for (int k = 0; k < 2; ++k) \
;         acc[ai][bj][m][n] = __builtin_amdgcn_mfma_f32_16x16x32_bf16(Bt[n][k], At[m][k], acc[ai][bj][m][n], 0, 0, 0); __builtin_amdgcn_s_setprio(0); } while (0)
; #define PG8_WAIT_V(n) asm volatile("s_waitcnt vmcnt(" #n ")" ::: "memory")
; #define PG8_WAIT_L(n) asm volatile("s_waitcnt lgkmcnt(" #n ")" ::: "memory")
; #define PG8_BAR __builtin_amdgcn_s_barrier()
; #define PG8_SCHED __builtin_amdgcn_sched_barrier(0)
; template <class Epi>
; __device__ __forceinline__ void gemm_phase(LAS unsigned char* lds, const Gemm g, const StaticOrder& S, const Epi& E) {
;     ...
;             PG8_LDB(B0, 1, 0); PG8_LDB(B1, 1, 1); PG8_SCHED; PG8_LDA(At, 1, 0); PG8_STAGE(PG8_SA(0, 1), a2 + hstep, voffA);
;             PG8_WAIT_V(8); PG8_WAIT_L(0); PG8_BAR; PG8_MMA(0, 0, At, B0); PG8_MMA(0, 1, At, B1); PG8_BAR; PG8_SCHED;
;             PG8_LDA(At, 1, 1); PG8_STAGE(PG8_SB(1, 0), b3, voffB); PG8_STAGE(PG8_SB(1, 1), b3 + hstep, voffB); PG8_STAGE(PG8_SA(1, 0), a3, voffA);
;             PG8_WAIT_V(8); PG8_WAIT_L(0); PG8_BAR; PG8_MMA(1, 0, At, B0); PG8_MMA(1, 1, At, B1); PG8_BAR; PG8_SCHED;
;         }
;         if (wr == 0) PG8_BAR;
	s_setprio 0
	s_add_i32 s60, 0, 0x18000
	s_add_i32 s61, 0, 0x1c000
	v_add_u32_e32 v166, s60, v160
	v_add_u32_e32 v186, s61, v160
	ds_read_b128 v[130:133], v166
	ds_read_b128 v[134:137], v166 offset:1024
	ds_read_b128 v[154:157], v166 offset:2048
	ds_read_b128 v[166:169], v166 offset:3072
	ds_read_b128 v[174:177], v186
	ds_read_b128 v[178:181], v186 offset:1024
	ds_read_b128 v[182:185], v186 offset:2048
	ds_read_b128 v[186:189], v186 offset:3072
	s_add_u32 s26, s26, 0xb0000
	s_addc_u32 s27, s27, 0
	s_mov_b32 m0, s41
	ds_read_b128 v[190:193], v164 offset:32768
	ds_read_b128 v[194:197], v164 offset:33792
	ds_read_b128 v[198:201], v164 offset:34816
	ds_read_b128 v[202:205], v164 offset:35840
	ds_read_b128 v[206:209], v164 offset:36864
	ds_read_b128 v[210:213], v164 offset:37888
	ds_read_b128 v[214:217], v164 offset:38912
	ds_read_b128 v[218:221], v164 offset:39936
	global_load_lds_dwordx4 v138, s[26:27]
	s_mov_b32 m0, s42
	s_nop 0
	global_load_lds_dwordx4 v142, s[26:27]
	s_waitcnt vmcnt(8)
	s_waitcnt lgkmcnt(0)
	s_setprio 1
	s_barrier
	v_mfma_f32_16x16x32_bf16 v[126:129], v[130:133], v[190:193], v[126:129]
	v_mfma_f32_16x16x32_bf16 v[110:113], v[130:133], v[198:201], v[110:113]
	v_mfma_f32_16x16x32_bf16 v[94:97], v[130:133], v[206:209], v[94:97]
	v_mfma_f32_16x16x32_bf16 v[78:81], v[130:133], v[214:217], v[78:81]
	v_mfma_f32_16x16x32_bf16 v[122:125], v[154:157], v[190:193], v[122:125]
	v_mfma_f32_16x16x32_bf16 v[106:109], v[154:157], v[198:201], v[106:109]
	v_mfma_f32_16x16x32_bf16 v[90:93], v[154:157], v[206:209], v[90:93]
	v_mfma_f32_16x16x32_bf16 v[74:77], v[154:157], v[214:217], v[74:77]
	v_mfma_f32_16x16x32_bf16 v[126:129], v[134:137], v[194:197], v[126:129]
	v_mfma_f32_16x16x32_bf16 v[110:113], v[134:137], v[202:205], v[110:113]
	v_mfma_f32_16x16x32_bf16 v[94:97], v[134:137], v[210:213], v[94:97]
	v_mfma_f32_16x16x32_bf16 v[78:81], v[134:137], v[218:221], v[78:81]
	v_mfma_f32_16x16x32_bf16 v[122:125], v[166:169], v[194:197], v[122:125]
	v_mfma_f32_16x16x32_bf16 v[106:109], v[166:169], v[202:205], v[106:109]
	v_mfma_f32_16x16x32_bf16 v[90:93], v[166:169], v[210:213], v[90:93]
	v_mfma_f32_16x16x32_bf16 v[74:77], v[166:169], v[218:221], v[74:77]
	v_mfma_f32_16x16x32_bf16 v[118:121], v[174:177], v[190:193], v[118:121]
	v_mfma_f32_16x16x32_bf16 v[102:105], v[174:177], v[198:201], v[102:105]
	v_mfma_f32_16x16x32_bf16 v[86:89], v[174:177], v[206:209], v[86:89]
	v_mfma_f32_16x16x32_bf16 v[70:73], v[174:177], v[214:217], v[70:73]
	v_mfma_f32_16x16x32_bf16 v[114:117], v[182:185], v[190:193], v[114:117]
	v_mfma_f32_16x16x32_bf16 v[98:101], v[182:185], v[198:201], v[98:101]
	v_mfma_f32_16x16x32_bf16 v[82:85], v[182:185], v[206:209], v[82:85]
	v_mfma_f32_16x16x32_bf16 v[66:69], v[182:185], v[214:217], v[66:69]
	v_mfma_f32_16x16x32_bf16 v[118:121], v[178:181], v[194:197], v[118:121]
	v_mfma_f32_16x16x32_bf16 v[102:105], v[178:181], v[202:205], v[102:105]
	v_mfma_f32_16x16x32_bf16 v[86:89], v[178:181], v[210:213], v[86:89]
	v_mfma_f32_16x16x32_bf16 v[70:73], v[178:181], v[218:221], v[70:73]
	v_mfma_f32_16x16x32_bf16 v[114:117], v[186:189], v[194:197], v[114:117]
	v_mfma_f32_16x16x32_bf16 v[98:101], v[186:189], v[202:205], v[98:101]
	v_mfma_f32_16x16x32_bf16 v[82:85], v[186:189], v[210:213], v[82:85]
	v_mfma_f32_16x16x32_bf16 v[66:69], v[186:189], v[218:221], v[66:69]
	s_barrier
	s_setprio 0
	s_add_i32 s26, s60, s38
	s_mov_b32 m0, s26
	ds_read_b128 v[190:193], v164 offset:49152
	ds_read_b128 v[194:197], v164 offset:50176
	ds_read_b128 v[198:201], v164 offset:51200
	ds_read_b128 v[202:205], v164 offset:52224
	ds_read_b128 v[206:209], v164 offset:53248
	ds_read_b128 v[210:213], v164 offset:54272
	ds_read_b128 v[214:217], v164 offset:55296
	ds_read_b128 v[218:221], v164 offset:56320
	global_load_lds_dwordx4 v140, s[98:99]
	s_add_i32 m0, s26, 0x2000
	s_add_u32 s24, s24, 0xb0080
	s_addc_u32 s25, s25, 0
	s_add_i32 s26, s61, s38
	global_load_lds_dwordx4 v144, s[98:99]
	s_mov_b32 m0, s26
	s_nop 0
	global_load_lds_dwordx4 v140, s[24:25]
	s_add_i32 m0, s26, 0x2000
	s_nop 0
	global_load_lds_dwordx4 v144, s[24:25]
	s_mov_b32 m0, s44
	s_nop 0
	global_load_lds_dwordx4 v138, s[100:101]
	s_mov_b32 m0, s45
	s_nop 0
	global_load_lds_dwordx4 v142, s[100:101]
	s_waitcnt vmcnt(8)
	s_waitcnt lgkmcnt(0)
	s_setprio 1
	s_barrier
	v_mfma_f32_16x16x32_bf16 v[62:65], v[130:133], v[190:193], v[62:65]
	v_mfma_f32_16x16x32_bf16 v[46:49], v[130:133], v[198:201], v[46:49]
	v_mfma_f32_16x16x32_bf16 v[30:33], v[130:133], v[206:209], v[30:33]
	v_mfma_f32_16x16x32_bf16 v[14:17], v[130:133], v[214:217], v[14:17]
	v_mfma_f32_16x16x32_bf16 v[58:61], v[154:157], v[190:193], v[58:61]
	v_mfma_f32_16x16x32_bf16 v[42:45], v[154:157], v[198:201], v[42:45]
	v_mfma_f32_16x16x32_bf16 v[26:29], v[154:157], v[206:209], v[26:29]
	v_mfma_f32_16x16x32_bf16 v[10:13], v[154:157], v[214:217], v[10:13]
	v_mfma_f32_16x16x32_bf16 v[62:65], v[134:137], v[194:197], v[62:65]
	v_mfma_f32_16x16x32_bf16 v[46:49], v[134:137], v[202:205], v[46:49]
	v_mfma_f32_16x16x32_bf16 v[30:33], v[134:137], v[210:213], v[30:33]
	v_mfma_f32_16x16x32_bf16 v[14:17], v[134:137], v[218:221], v[14:17]
	v_mfma_f32_16x16x32_bf16 v[58:61], v[166:169], v[194:197], v[58:61]
	v_mfma_f32_16x16x32_bf16 v[42:45], v[166:169], v[202:205], v[42:45]
	v_mfma_f32_16x16x32_bf16 v[26:29], v[166:169], v[210:213], v[26:29]
	v_mfma_f32_16x16x32_bf16 v[10:13], v[166:169], v[218:221], v[10:13]
	v_mfma_f32_16x16x32_bf16 v[54:57], v[174:177], v[190:193], v[54:57]
	v_mfma_f32_16x16x32_bf16 v[38:41], v[174:177], v[198:201], v[38:41]
	v_mfma_f32_16x16x32_bf16 v[22:25], v[174:177], v[206:209], v[22:25]
	v_mfma_f32_16x16x32_bf16 v[6:9], v[174:177], v[214:217], v[6:9]
	v_mfma_f32_16x16x32_bf16 v[50:53], v[182:185], v[190:193], v[50:53]
	v_mfma_f32_16x16x32_bf16 v[34:37], v[182:185], v[198:201], v[34:37]
	v_mfma_f32_16x16x32_bf16 v[18:21], v[182:185], v[206:209], v[18:21]
	v_mfma_f32_16x16x32_bf16 v[2:5], v[182:185], v[214:217], v[2:5]
	v_mfma_f32_16x16x32_bf16 v[54:57], v[178:181], v[194:197], v[54:57]
	v_mfma_f32_16x16x32_bf16 v[38:41], v[178:181], v[202:205], v[38:41]
	v_mfma_f32_16x16x32_bf16 v[22:25], v[178:181], v[210:213], v[22:25]
	v_mfma_f32_16x16x32_bf16 v[6:9], v[178:181], v[218:221], v[6:9]
	v_mfma_f32_16x16x32_bf16 v[50:53], v[186:189], v[194:197], v[50:53]
	v_mfma_f32_16x16x32_bf16 v[34:37], v[186:189], v[202:205], v[34:37]
	v_mfma_f32_16x16x32_bf16 v[18:21], v[186:189], v[210:213], v[18:21]
	v_mfma_f32_16x16x32_bf16 v[2:5], v[186:189], v[218:221], v[2:5]
	s_barrier
	s_setprio 0
	s_add_i32 s59, s59, 2
	s_add_u32 s22, s22, 0x100
	s_addc_u32 s23, s23, 0
	s_add_u32 s57, s57, 0x100
	s_addc_u32 s58, s58, 0
	s_cmp_gt_u32 s59, 41
	s_cbranch_scc0 .LBB0_971
	s_and_b64 vcc, exec, s[18:19]
	s_cbranch_vccz .LBB0_974
	s_barrier
